# U loop trimmed: dedicated mask SGPRs, LDS address bases in VGPRs, one-pair-ahead bpermute with merged waitcnt, x base folded
# speedup vs baseline: 1.0362x; 1.0063x over previous
; DEV void sort_lists(int lane, int& myi0, int& myi1, float& myg0, float& myg1) {
; #pragma unroll
;     for (int k = 2; k <= 128; k <<= 1) {
; #pragma unroll
;       for (int j = k >> 1; j >= 1; j >>= 1) {
;         if (j == 64) {
;           const bool sw_ = myi1 < myi0;
;           const int ti = sw_ ? myi1 : myi0, tj = sw_ ? myi0 : myi1; const float tg = sw_ ? myg1 : myg0, th = sw_ ? myg0 : myg1;
;           myi0 = ti; myi1 = tj; myg0 = tg; myg1 = th;
;         } else {
;           const bool lower = (lane & j) == 0;
;           {
;             const bool up = (k == 128) ? true : ((k == 64) ? true : ((lane & k) == 0));
;             const int oi = __shfl_xor(myi0, j); const float og = __shfl_xor(myg0, j);
;             const bool take = (lower == up) ? (oi < myi0) : (oi > myi0);
;             myi0 = take ? oi : myi0; myg0 = take ? og : myg0;
;           }
;           {
;             const bool up = (k == 128) ? true : ((k == 64) ? false : ((lane & k) == 0));
;             const int oi = __shfl_xor(myi1, j); const float og = __shfl_xor(myg1, j);
;             const bool take = (lower == up) ? (oi < myi1) : (oi > myi1);
;             myi1 = take ? oi : myi1; myg1 = take ? og : myg1;
;           }
;         }
;       }
;     }
; }
; DEV void peer_gather(const Params& P, int l, int m0, const int* idxs, const float* gs) {
;     ...
;   int ni0 = idxs[(wid * 16) * 128 + lane], ni1 = idxs[(wid * 16) * 128 + 64 + lane];
;   float ng0 = gs[(wid * 16) * 128 + lane], ng1 = gs[(wid * 16) * 128 + 64 + lane];
;   sort_lists(lane, ni0, ni1, ng0, ng1);
.Lpg0_p0:
	v_readlane_b32 s82, v231, 26
	v_readlane_b32 s83, v231, 27
	s_nop 4
	s_lshl_b32 s98, s2, 2
	s_add_u32 s98, s98, s33
	s_add_u32 s98, s98, 0
	s_lshl_b32 s98, s98, 9
	v_add_u32_e32 v116, s98, v234
	global_load_dword v241, v116, s[82:83]
	global_load_dword v242, v116, s[82:83] offset:256
	s_lshl_b32 s98, s2, 2
	s_add_u32 s98, s98, s33
	s_add_u32 s98, s98, 1
	s_lshl_b32 s98, s98, 9
	v_add_u32_e32 v117, s98, v234
	global_load_dword v243, v117, s[82:83]
	global_load_dword v244, v117, s[82:83] offset:256
	s_lshl_b32 s98, s2, 2
	s_add_u32 s98, s98, s33
	s_add_u32 s98, s98, 2
	s_lshl_b32 s98, s98, 9
	v_add_u32_e32 v118, s98, v234
	global_load_dword v245, v118, s[82:83]
	global_load_dword v246, v118, s[82:83] offset:256
	s_lshl_b32 s98, s2, 2
	s_add_u32 s98, s98, s33
	s_add_u32 s98, s98, 3
	s_lshl_b32 s98, s98, 9
	v_add_u32_e32 v119, s98, v234
	global_load_dword v247, v119, s[82:83]
	global_load_dword v248, v119, s[82:83] offset:256
	s_waitcnt vmcnt(0)
	v_or_b32_e32 v116, 64, v233
	v_lshl_or_b32 v241, v241, 7, v233
	v_lshl_or_b32 v242, v242, 7, v116
	v_lshl_or_b32 v243, v243, 7, v233
	v_lshl_or_b32 v244, v244, 7, v116
	v_lshl_or_b32 v245, v245, 7, v233
	v_lshl_or_b32 v246, v246, 7, v116
	v_lshl_or_b32 v247, v247, 7, v233
	v_lshl_or_b32 v248, v248, 7, v116
	v_xor_b32_e32 v116, 4, v234
	ds_bpermute_b32 v0, v116, v241
	ds_bpermute_b32 v1, v116, v243
	ds_bpermute_b32 v2, v116, v245
	ds_bpermute_b32 v3, v116, v247
	ds_bpermute_b32 v4, v116, v242
	ds_bpermute_b32 v5, v116, v244
	ds_bpermute_b32 v6, v116, v246
	ds_bpermute_b32 v7, v116, v248
	s_waitcnt lgkmcnt(0)
	s_mov_b32 s88, 0x99999999
	s_mov_b32 s89, 0x99999999
	v_min_u32_e32 v104, v241, v0
	v_max_u32_e32 v105, v241, v0
	v_cndmask_b32_e64 v241, v105, v104, s[88:89]
	v_min_u32_e32 v106, v243, v1
	v_max_u32_e32 v107, v243, v1
	v_cndmask_b32_e64 v243, v107, v106, s[88:89]
	v_min_u32_e32 v104, v245, v2
	v_max_u32_e32 v105, v245, v2
	v_cndmask_b32_e64 v245, v105, v104, s[88:89]
	v_min_u32_e32 v106, v247, v3
	v_max_u32_e32 v107, v247, v3
	v_cndmask_b32_e64 v247, v107, v106, s[88:89]
	v_min_u32_e32 v104, v242, v4
	v_max_u32_e32 v105, v242, v4
	v_cndmask_b32_e64 v242, v105, v104, s[88:89]
	v_min_u32_e32 v106, v244, v5
	v_max_u32_e32 v107, v244, v5
	v_cndmask_b32_e64 v244, v107, v106, s[88:89]
	v_min_u32_e32 v104, v246, v6
	v_max_u32_e32 v105, v246, v6
	v_cndmask_b32_e64 v246, v105, v104, s[88:89]
	v_min_u32_e32 v106, v248, v7
	v_max_u32_e32 v107, v248, v7
	v_cndmask_b32_e64 v248, v107, v106, s[88:89]
	v_xor_b32_e32 v116, 8, v234
	ds_bpermute_b32 v0, v116, v241
	ds_bpermute_b32 v1, v116, v243
	ds_bpermute_b32 v2, v116, v245
	ds_bpermute_b32 v3, v116, v247
	ds_bpermute_b32 v4, v116, v242
	ds_bpermute_b32 v5, v116, v244
	ds_bpermute_b32 v6, v116, v246
	ds_bpermute_b32 v7, v116, v248
	s_waitcnt lgkmcnt(0)
	s_mov_b32 s88, 0xc3c3c3c3
	s_mov_b32 s89, 0xc3c3c3c3
	v_min_u32_e32 v104, v241, v0
	v_max_u32_e32 v105, v241, v0
	v_cndmask_b32_e64 v241, v105, v104, s[88:89]
	v_min_u32_e32 v106, v243, v1
	v_max_u32_e32 v107, v243, v1
	v_cndmask_b32_e64 v243, v107, v106, s[88:89]
	v_min_u32_e32 v104, v245, v2
	v_max_u32_e32 v105, v245, v2
	v_cndmask_b32_e64 v245, v105, v104, s[88:89]
	v_min_u32_e32 v106, v247, v3
	v_max_u32_e32 v107, v247, v3
	v_cndmask_b32_e64 v247, v107, v106, s[88:89]
	v_min_u32_e32 v104, v242, v4
	v_max_u32_e32 v105, v242, v4
	v_cndmask_b32_e64 v242, v105, v104, s[88:89]
	v_min_u32_e32 v106, v244, v5
	v_max_u32_e32 v107, v244, v5
	v_cndmask_b32_e64 v244, v107, v106, s[88:89]
	v_min_u32_e32 v104, v246, v6
	v_max_u32_e32 v105, v246, v6
	v_cndmask_b32_e64 v246, v105, v104, s[88:89]
	v_min_u32_e32 v106, v248, v7
	v_max_u32_e32 v107, v248, v7
	v_cndmask_b32_e64 v248, v107, v106, s[88:89]
	v_xor_b32_e32 v116, 4, v234
	ds_bpermute_b32 v0, v116, v241
	ds_bpermute_b32 v1, v116, v243
	ds_bpermute_b32 v2, v116, v245
	ds_bpermute_b32 v3, v116, v247
	ds_bpermute_b32 v4, v116, v242
	ds_bpermute_b32 v5, v116, v244
	ds_bpermute_b32 v6, v116, v246
	ds_bpermute_b32 v7, v116, v248
	s_waitcnt lgkmcnt(0)
	s_mov_b32 s88, 0xa5a5a5a5
	s_mov_b32 s89, 0xa5a5a5a5
	v_min_u32_e32 v104, v241, v0
	v_max_u32_e32 v105, v241, v0
	v_cndmask_b32_e64 v241, v105, v104, s[88:89]
	v_min_u32_e32 v106, v243, v1
	v_max_u32_e32 v107, v243, v1
	v_cndmask_b32_e64 v243, v107, v106, s[88:89]
	v_min_u32_e32 v104, v245, v2
	v_max_u32_e32 v105, v245, v2
	v_cndmask_b32_e64 v245, v105, v104, s[88:89]
	v_min_u32_e32 v106, v247, v3
	v_max_u32_e32 v107, v247, v3
	v_cndmask_b32_e64 v247, v107, v106, s[88:89]
	v_min_u32_e32 v104, v242, v4
	v_max_u32_e32 v105, v242, v4
	v_cndmask_b32_e64 v242, v105, v104, s[88:89]
	v_min_u32_e32 v106, v244, v5
	v_max_u32_e32 v107, v244, v5
	v_cndmask_b32_e64 v244, v107, v106, s[88:89]
	v_min_u32_e32 v104, v246, v6
	v_max_u32_e32 v105, v246, v6
	v_cndmask_b32_e64 v246, v105, v104, s[88:89]
	v_min_u32_e32 v106, v248, v7
	v_max_u32_e32 v107, v248, v7
	v_cndmask_b32_e64 v248, v107, v106, s[88:89]
	v_xor_b32_e32 v116, 16, v234
	ds_bpermute_b32 v0, v116, v241
	ds_bpermute_b32 v1, v116, v243
	ds_bpermute_b32 v2, v116, v245
	ds_bpermute_b32 v3, v116, v247
	ds_bpermute_b32 v4, v116, v242
	ds_bpermute_b32 v5, v116, v244
	ds_bpermute_b32 v6, v116, v246
	ds_bpermute_b32 v7, v116, v248
	s_waitcnt lgkmcnt(0)
; DEV void sort_lists(int lane, int& myi0, int& myi1, float& myg0, float& myg1) {
; #pragma unroll
;     for (int k = 2; k <= 128; k <<= 1) {
; #pragma unroll
;       for (int j = k >> 1; j >= 1; j >>= 1) {
;         if (j == 64) {
;           const bool sw_ = myi1 < myi0;
;           const int ti = sw_ ? myi1 : myi0, tj = sw_ ? myi0 : myi1; const float tg = sw_ ? myg1 : myg0, th = sw_ ? myg0 : myg1;
;           myi0 = ti; myi1 = tj; myg0 = tg; myg1 = th;
;         } else {
;           const bool lower = (lane & j) == 0;
;           {
;             const bool up = (k == 128) ? true : ((k == 64) ? true : ((lane & k) == 0));
;             const int oi = __shfl_xor(myi0, j); const float og = __shfl_xor(myg0, j);
;             const bool take = (lower == up) ? (oi < myi0) : (oi > myi0);
;             myi0 = take ? oi : myi0; myg0 = take ? og : myg0;
;           }
;           {
;             const bool up = (k == 128) ? true : ((k == 64) ? false : ((lane & k) == 0));
;             const int oi = __shfl_xor(myi1, j); const float og = __shfl_xor(myg1, j);
;             const bool take = (lower == up) ? (oi < myi1) : (oi > myi1);
;             myi1 = take ? oi : myi1; myg1 = take ? og : myg1;
;           }
;         }
;       }
;     }
; }
	s_mov_b32 s88, 0xf00ff00f
	s_mov_b32 s89, 0xf00ff00f
	v_min_u32_e32 v104, v241, v0
	v_max_u32_e32 v105, v241, v0
	v_cndmask_b32_e64 v241, v105, v104, s[88:89]
	v_min_u32_e32 v106, v243, v1
	v_max_u32_e32 v107, v243, v1
	v_cndmask_b32_e64 v243, v107, v106, s[88:89]
	v_min_u32_e32 v104, v245, v2
	v_max_u32_e32 v105, v245, v2
	v_cndmask_b32_e64 v245, v105, v104, s[88:89]
	v_min_u32_e32 v106, v247, v3
	v_max_u32_e32 v107, v247, v3
	v_cndmask_b32_e64 v247, v107, v106, s[88:89]
	v_min_u32_e32 v104, v242, v4
	v_max_u32_e32 v105, v242, v4
	v_cndmask_b32_e64 v242, v105, v104, s[88:89]
	v_min_u32_e32 v106, v244, v5
	v_max_u32_e32 v107, v244, v5
	v_cndmask_b32_e64 v244, v107, v106, s[88:89]
	v_min_u32_e32 v104, v246, v6
	v_max_u32_e32 v105, v246, v6
	v_cndmask_b32_e64 v246, v105, v104, s[88:89]
	v_min_u32_e32 v106, v248, v7
	v_max_u32_e32 v107, v248, v7
	v_cndmask_b32_e64 v248, v107, v106, s[88:89]
	v_xor_b32_e32 v116, 8, v234
	ds_bpermute_b32 v0, v116, v241
	ds_bpermute_b32 v1, v116, v243
	ds_bpermute_b32 v2, v116, v245
	ds_bpermute_b32 v3, v116, v247
	ds_bpermute_b32 v4, v116, v242
	ds_bpermute_b32 v5, v116, v244
	ds_bpermute_b32 v6, v116, v246
	ds_bpermute_b32 v7, v116, v248
	s_waitcnt lgkmcnt(0)
	s_mov_b32 s88, 0xcc33cc33
	s_mov_b32 s89, 0xcc33cc33
	v_min_u32_e32 v104, v241, v0
	v_max_u32_e32 v105, v241, v0
	v_cndmask_b32_e64 v241, v105, v104, s[88:89]
	v_min_u32_e32 v106, v243, v1
	v_max_u32_e32 v107, v243, v1
	v_cndmask_b32_e64 v243, v107, v106, s[88:89]
	v_min_u32_e32 v104, v245, v2
	v_max_u32_e32 v105, v245, v2
	v_cndmask_b32_e64 v245, v105, v104, s[88:89]
	v_min_u32_e32 v106, v247, v3
	v_max_u32_e32 v107, v247, v3
	v_cndmask_b32_e64 v247, v107, v106, s[88:89]
	v_min_u32_e32 v104, v242, v4
	v_max_u32_e32 v105, v242, v4
	v_cndmask_b32_e64 v242, v105, v104, s[88:89]
	v_min_u32_e32 v106, v244, v5
	v_max_u32_e32 v107, v244, v5
	v_cndmask_b32_e64 v244, v107, v106, s[88:89]
	v_min_u32_e32 v104, v246, v6
	v_max_u32_e32 v105, v246, v6
	v_cndmask_b32_e64 v246, v105, v104, s[88:89]
	v_min_u32_e32 v106, v248, v7
	v_max_u32_e32 v107, v248, v7
	v_cndmask_b32_e64 v248, v107, v106, s[88:89]
	v_xor_b32_e32 v116, 4, v234
	ds_bpermute_b32 v0, v116, v241
	ds_bpermute_b32 v1, v116, v243
	ds_bpermute_b32 v2, v116, v245
	ds_bpermute_b32 v3, v116, v247
	ds_bpermute_b32 v4, v116, v242
	ds_bpermute_b32 v5, v116, v244
	ds_bpermute_b32 v6, v116, v246
	ds_bpermute_b32 v7, v116, v248
	s_waitcnt lgkmcnt(0)
	s_mov_b32 s88, 0xaa55aa55
	s_mov_b32 s89, 0xaa55aa55
	v_min_u32_e32 v104, v241, v0
	v_max_u32_e32 v105, v241, v0
	v_cndmask_b32_e64 v241, v105, v104, s[88:89]
	v_min_u32_e32 v106, v243, v1
	v_max_u32_e32 v107, v243, v1
	v_cndmask_b32_e64 v243, v107, v106, s[88:89]
	v_min_u32_e32 v104, v245, v2
	v_max_u32_e32 v105, v245, v2
	v_cndmask_b32_e64 v245, v105, v104, s[88:89]
	v_min_u32_e32 v106, v247, v3
	v_max_u32_e32 v107, v247, v3
	v_cndmask_b32_e64 v247, v107, v106, s[88:89]
	v_min_u32_e32 v104, v242, v4
	v_max_u32_e32 v105, v242, v4
	v_cndmask_b32_e64 v242, v105, v104, s[88:89]
	v_min_u32_e32 v106, v244, v5
	v_max_u32_e32 v107, v244, v5
	v_cndmask_b32_e64 v244, v107, v106, s[88:89]
	v_min_u32_e32 v104, v246, v6
	v_max_u32_e32 v105, v246, v6
	v_cndmask_b32_e64 v246, v105, v104, s[88:89]
	v_min_u32_e32 v106, v248, v7
	v_max_u32_e32 v107, v248, v7
	v_cndmask_b32_e64 v248, v107, v106, s[88:89]
	v_xor_b32_e32 v116, 32, v234
	ds_bpermute_b32 v0, v116, v241
	ds_bpermute_b32 v1, v116, v243
	ds_bpermute_b32 v2, v116, v245
	ds_bpermute_b32 v3, v116, v247
	ds_bpermute_b32 v4, v116, v242
	ds_bpermute_b32 v5, v116, v244
	ds_bpermute_b32 v6, v116, v246
	ds_bpermute_b32 v7, v116, v248
	s_waitcnt lgkmcnt(0)
	s_mov_b32 s88, 0xff0000ff
	s_mov_b32 s89, 0xff0000ff
	v_min_u32_e32 v104, v241, v0
	v_max_u32_e32 v105, v241, v0
	v_cndmask_b32_e64 v241, v105, v104, s[88:89]
	v_min_u32_e32 v106, v243, v1
	v_max_u32_e32 v107, v243, v1
	v_cndmask_b32_e64 v243, v107, v106, s[88:89]
	v_min_u32_e32 v104, v245, v2
	v_max_u32_e32 v105, v245, v2
	v_cndmask_b32_e64 v245, v105, v104, s[88:89]
	v_min_u32_e32 v106, v247, v3
	v_max_u32_e32 v107, v247, v3
	v_cndmask_b32_e64 v247, v107, v106, s[88:89]
	v_min_u32_e32 v104, v242, v4
	v_max_u32_e32 v105, v242, v4
	v_cndmask_b32_e64 v242, v105, v104, s[88:89]
	v_min_u32_e32 v106, v244, v5
	v_max_u32_e32 v107, v244, v5
	v_cndmask_b32_e64 v244, v107, v106, s[88:89]
	v_min_u32_e32 v104, v246, v6
	v_max_u32_e32 v105, v246, v6
	v_cndmask_b32_e64 v246, v105, v104, s[88:89]
	v_min_u32_e32 v106, v248, v7
	v_max_u32_e32 v107, v248, v7
	v_cndmask_b32_e64 v248, v107, v106, s[88:89]
	v_xor_b32_e32 v116, 16, v234
	ds_bpermute_b32 v0, v116, v241
	ds_bpermute_b32 v1, v116, v243
	ds_bpermute_b32 v2, v116, v245
	ds_bpermute_b32 v3, v116, v247
	ds_bpermute_b32 v4, v116, v242
	ds_bpermute_b32 v5, v116, v244
	ds_bpermute_b32 v6, v116, v246
	ds_bpermute_b32 v7, v116, v248
	s_waitcnt lgkmcnt(0)
	s_mov_b32 s88, 0xf0f00f0f
	s_mov_b32 s89, 0xf0f00f0f
	v_min_u32_e32 v104, v241, v0
	v_max_u32_e32 v105, v241, v0
	v_cndmask_b32_e64 v241, v105, v104, s[88:89]
	v_min_u32_e32 v106, v243, v1
	v_max_u32_e32 v107, v243, v1
	v_cndmask_b32_e64 v243, v107, v106, s[88:89]
	v_min_u32_e32 v104, v245, v2
	v_max_u32_e32 v105, v245, v2
	v_cndmask_b32_e64 v245, v105, v104, s[88:89]
	v_min_u32_e32 v106, v247, v3
	v_max_u32_e32 v107, v247, v3
	v_cndmask_b32_e64 v247, v107, v106, s[88:89]
	v_min_u32_e32 v104, v242, v4
	v_max_u32_e32 v105, v242, v4
	v_cndmask_b32_e64 v242, v105, v104, s[88:89]
	v_min_u32_e32 v106, v244, v5
	v_max_u32_e32 v107, v244, v5
	v_cndmask_b32_e64 v244, v107, v106, s[88:89]
	v_min_u32_e32 v104, v246, v6
	v_max_u32_e32 v105, v246, v6
	v_cndmask_b32_e64 v246, v105, v104, s[88:89]
	v_min_u32_e32 v106, v248, v7
	v_max_u32_e32 v107, v248, v7
	v_cndmask_b32_e64 v248, v107, v106, s[88:89]
	v_xor_b32_e32 v116, 8, v234
	ds_bpermute_b32 v0, v116, v241
	ds_bpermute_b32 v1, v116, v243
	ds_bpermute_b32 v2, v116, v245
	ds_bpermute_b32 v3, v116, v247
	ds_bpermute_b32 v4, v116, v242
	ds_bpermute_b32 v5, v116, v244
	ds_bpermute_b32 v6, v116, v246
	ds_bpermute_b32 v7, v116, v248
	s_waitcnt lgkmcnt(0)
; DEV void sort_lists(int lane, int& myi0, int& myi1, float& myg0, float& myg1) {
; #pragma unroll
;     for (int k = 2; k <= 128; k <<= 1) {
; #pragma unroll
;       for (int j = k >> 1; j >= 1; j >>= 1) {
;         if (j == 64) {
;           const bool sw_ = myi1 < myi0;
;           const int ti = sw_ ? myi1 : myi0, tj = sw_ ? myi0 : myi1; const float tg = sw_ ? myg1 : myg0, th = sw_ ? myg0 : myg1;
;           myi0 = ti; myi1 = tj; myg0 = tg; myg1 = th;
;         } else {
;           const bool lower = (lane & j) == 0;
;           {
;             const bool up = (k == 128) ? true : ((k == 64) ? true : ((lane & k) == 0));
;             const int oi = __shfl_xor(myi0, j); const float og = __shfl_xor(myg0, j);
;             const bool take = (lower == up) ? (oi < myi0) : (oi > myi0);
;             myi0 = take ? oi : myi0; myg0 = take ? og : myg0;
;           }
;           {
;             const bool up = (k == 128) ? true : ((k == 64) ? false : ((lane & k) == 0));
;             const int oi = __shfl_xor(myi1, j); const float og = __shfl_xor(myg1, j);
;             const bool take = (lower == up) ? (oi < myi1) : (oi > myi1);
;             myi1 = take ? oi : myi1; myg1 = take ? og : myg1;
;           }
;         }
;       }
;     }
; }
	s_mov_b32 s88, 0xcccc3333
	s_mov_b32 s89, 0xcccc3333
	v_min_u32_e32 v104, v241, v0
	v_max_u32_e32 v105, v241, v0
	v_cndmask_b32_e64 v241, v105, v104, s[88:89]
	v_min_u32_e32 v106, v243, v1
	v_max_u32_e32 v107, v243, v1
	v_cndmask_b32_e64 v243, v107, v106, s[88:89]
	v_min_u32_e32 v104, v245, v2
	v_max_u32_e32 v105, v245, v2
	v_cndmask_b32_e64 v245, v105, v104, s[88:89]
	v_min_u32_e32 v106, v247, v3
	v_max_u32_e32 v107, v247, v3
	v_cndmask_b32_e64 v247, v107, v106, s[88:89]
	v_min_u32_e32 v104, v242, v4
	v_max_u32_e32 v105, v242, v4
	v_cndmask_b32_e64 v242, v105, v104, s[88:89]
	v_min_u32_e32 v106, v244, v5
	v_max_u32_e32 v107, v244, v5
	v_cndmask_b32_e64 v244, v107, v106, s[88:89]
	v_min_u32_e32 v104, v246, v6
	v_max_u32_e32 v105, v246, v6
	v_cndmask_b32_e64 v246, v105, v104, s[88:89]
	v_min_u32_e32 v106, v248, v7
	v_max_u32_e32 v107, v248, v7
	v_cndmask_b32_e64 v248, v107, v106, s[88:89]
	v_xor_b32_e32 v116, 4, v234
	ds_bpermute_b32 v0, v116, v241
	ds_bpermute_b32 v1, v116, v243
	ds_bpermute_b32 v2, v116, v245
	ds_bpermute_b32 v3, v116, v247
	ds_bpermute_b32 v4, v116, v242
	ds_bpermute_b32 v5, v116, v244
	ds_bpermute_b32 v6, v116, v246
	ds_bpermute_b32 v7, v116, v248
	s_waitcnt lgkmcnt(0)
	s_mov_b32 s88, 0xaaaa5555
	s_mov_b32 s89, 0xaaaa5555
	v_min_u32_e32 v104, v241, v0
	v_max_u32_e32 v105, v241, v0
	v_cndmask_b32_e64 v241, v105, v104, s[88:89]
	v_min_u32_e32 v106, v243, v1
	v_max_u32_e32 v107, v243, v1
	v_cndmask_b32_e64 v243, v107, v106, s[88:89]
	v_min_u32_e32 v104, v245, v2
	v_max_u32_e32 v105, v245, v2
	v_cndmask_b32_e64 v245, v105, v104, s[88:89]
	v_min_u32_e32 v106, v247, v3
	v_max_u32_e32 v107, v247, v3
	v_cndmask_b32_e64 v247, v107, v106, s[88:89]
	v_min_u32_e32 v104, v242, v4
	v_max_u32_e32 v105, v242, v4
	v_cndmask_b32_e64 v242, v105, v104, s[88:89]
	v_min_u32_e32 v106, v244, v5
	v_max_u32_e32 v107, v244, v5
	v_cndmask_b32_e64 v244, v107, v106, s[88:89]
	v_min_u32_e32 v104, v246, v6
	v_max_u32_e32 v105, v246, v6
	v_cndmask_b32_e64 v246, v105, v104, s[88:89]
	v_min_u32_e32 v106, v248, v7
	v_max_u32_e32 v107, v248, v7
	v_cndmask_b32_e64 v248, v107, v106, s[88:89]
	v_xor_b32_e32 v116, 64, v234
	ds_bpermute_b32 v0, v116, v241
	ds_bpermute_b32 v1, v116, v243
	ds_bpermute_b32 v2, v116, v245
	ds_bpermute_b32 v3, v116, v247
	ds_bpermute_b32 v4, v116, v242
	ds_bpermute_b32 v5, v116, v244
	ds_bpermute_b32 v6, v116, v246
	ds_bpermute_b32 v7, v116, v248
	s_waitcnt lgkmcnt(0)
	s_mov_b32 s88, 0xffff
	s_mov_b32 s89, 0xffff0000
	v_min_u32_e32 v104, v241, v0
	v_max_u32_e32 v105, v241, v0
	v_cndmask_b32_e64 v241, v105, v104, s[88:89]
	v_min_u32_e32 v106, v243, v1
	v_max_u32_e32 v107, v243, v1
	v_cndmask_b32_e64 v243, v107, v106, s[88:89]
	v_min_u32_e32 v104, v245, v2
	v_max_u32_e32 v105, v245, v2
	v_cndmask_b32_e64 v245, v105, v104, s[88:89]
	v_min_u32_e32 v106, v247, v3
	v_max_u32_e32 v107, v247, v3
	v_cndmask_b32_e64 v247, v107, v106, s[88:89]
	v_min_u32_e32 v104, v242, v4
	v_max_u32_e32 v105, v242, v4
	v_cndmask_b32_e64 v242, v105, v104, s[88:89]
	v_min_u32_e32 v106, v244, v5
	v_max_u32_e32 v107, v244, v5
	v_cndmask_b32_e64 v244, v107, v106, s[88:89]
	v_min_u32_e32 v104, v246, v6
	v_max_u32_e32 v105, v246, v6
	v_cndmask_b32_e64 v246, v105, v104, s[88:89]
	v_min_u32_e32 v106, v248, v7
	v_max_u32_e32 v107, v248, v7
	v_cndmask_b32_e64 v248, v107, v106, s[88:89]
	v_xor_b32_e32 v116, 32, v234
	ds_bpermute_b32 v0, v116, v241
	ds_bpermute_b32 v1, v116, v243
	ds_bpermute_b32 v2, v116, v245
	ds_bpermute_b32 v3, v116, v247
	ds_bpermute_b32 v4, v116, v242
	ds_bpermute_b32 v5, v116, v244
	ds_bpermute_b32 v6, v116, v246
	ds_bpermute_b32 v7, v116, v248
	s_waitcnt lgkmcnt(0)
	s_mov_b32 s88, 0xff00ff
	s_mov_b32 s89, 0xff00ff00
	v_min_u32_e32 v104, v241, v0
	v_max_u32_e32 v105, v241, v0
	v_cndmask_b32_e64 v241, v105, v104, s[88:89]
	v_min_u32_e32 v106, v243, v1
	v_max_u32_e32 v107, v243, v1
	v_cndmask_b32_e64 v243, v107, v106, s[88:89]
	v_min_u32_e32 v104, v245, v2
	v_max_u32_e32 v105, v245, v2
	v_cndmask_b32_e64 v245, v105, v104, s[88:89]
	v_min_u32_e32 v106, v247, v3
	v_max_u32_e32 v107, v247, v3
	v_cndmask_b32_e64 v247, v107, v106, s[88:89]
	v_min_u32_e32 v104, v242, v4
	v_max_u32_e32 v105, v242, v4
	v_cndmask_b32_e64 v242, v105, v104, s[88:89]
	v_min_u32_e32 v106, v244, v5
	v_max_u32_e32 v107, v244, v5
	v_cndmask_b32_e64 v244, v107, v106, s[88:89]
	v_min_u32_e32 v104, v246, v6
	v_max_u32_e32 v105, v246, v6
	v_cndmask_b32_e64 v246, v105, v104, s[88:89]
	v_min_u32_e32 v106, v248, v7
	v_max_u32_e32 v107, v248, v7
	v_cndmask_b32_e64 v248, v107, v106, s[88:89]
	v_xor_b32_e32 v116, 16, v234
	ds_bpermute_b32 v0, v116, v241
	ds_bpermute_b32 v1, v116, v243
	ds_bpermute_b32 v2, v116, v245
	ds_bpermute_b32 v3, v116, v247
	ds_bpermute_b32 v4, v116, v242
	ds_bpermute_b32 v5, v116, v244
	ds_bpermute_b32 v6, v116, v246
	ds_bpermute_b32 v7, v116, v248
	s_waitcnt lgkmcnt(0)
	s_mov_b32 s88, 0xf0f0f0f
	s_mov_b32 s89, 0xf0f0f0f0
	v_min_u32_e32 v104, v241, v0
	v_max_u32_e32 v105, v241, v0
	v_cndmask_b32_e64 v241, v105, v104, s[88:89]
	v_min_u32_e32 v106, v243, v1
	v_max_u32_e32 v107, v243, v1
	v_cndmask_b32_e64 v243, v107, v106, s[88:89]
	v_min_u32_e32 v104, v245, v2
	v_max_u32_e32 v105, v245, v2
	v_cndmask_b32_e64 v245, v105, v104, s[88:89]
	v_min_u32_e32 v106, v247, v3
	v_max_u32_e32 v107, v247, v3
	v_cndmask_b32_e64 v247, v107, v106, s[88:89]
	v_min_u32_e32 v104, v242, v4
	v_max_u32_e32 v105, v242, v4
	v_cndmask_b32_e64 v242, v105, v104, s[88:89]
	v_min_u32_e32 v106, v244, v5
	v_max_u32_e32 v107, v244, v5
	v_cndmask_b32_e64 v244, v107, v106, s[88:89]
	v_min_u32_e32 v104, v246, v6
	v_max_u32_e32 v105, v246, v6
	v_cndmask_b32_e64 v246, v105, v104, s[88:89]
	v_min_u32_e32 v106, v248, v7
	v_max_u32_e32 v107, v248, v7
	v_cndmask_b32_e64 v248, v107, v106, s[88:89]
	v_xor_b32_e32 v116, 8, v234
	ds_bpermute_b32 v0, v116, v241
	ds_bpermute_b32 v1, v116, v243
	ds_bpermute_b32 v2, v116, v245
	ds_bpermute_b32 v3, v116, v247
	ds_bpermute_b32 v4, v116, v242
	ds_bpermute_b32 v5, v116, v244
	ds_bpermute_b32 v6, v116, v246
	ds_bpermute_b32 v7, v116, v248
	s_waitcnt lgkmcnt(0)
; DEV void sort_lists(int lane, int& myi0, int& myi1, float& myg0, float& myg1) {
; #pragma unroll
;     for (int k = 2; k <= 128; k <<= 1) {
; #pragma unroll
;       for (int j = k >> 1; j >= 1; j >>= 1) {
;         if (j == 64) {
;           const bool sw_ = myi1 < myi0;
;           const int ti = sw_ ? myi1 : myi0, tj = sw_ ? myi0 : myi1; const float tg = sw_ ? myg1 : myg0, th = sw_ ? myg0 : myg1;
;           myi0 = ti; myi1 = tj; myg0 = tg; myg1 = th;
;         } else {
;           const bool lower = (lane & j) == 0;
;           {
;             const bool up = (k == 128) ? true : ((k == 64) ? true : ((lane & k) == 0));
;             const int oi = __shfl_xor(myi0, j); const float og = __shfl_xor(myg0, j);
;             const bool take = (lower == up) ? (oi < myi0) : (oi > myi0);
;             myi0 = take ? oi : myi0; myg0 = take ? og : myg0;
;           }
;           {
;             const bool up = (k == 128) ? true : ((k == 64) ? false : ((lane & k) == 0));
;             const int oi = __shfl_xor(myi1, j); const float og = __shfl_xor(myg1, j);
;             const bool take = (lower == up) ? (oi < myi1) : (oi > myi1);
;             myi1 = take ? oi : myi1; myg1 = take ? og : myg1;
;           }
;         }
;       }
;     }
; }
	s_mov_b32 s88, 0x33333333
	s_mov_b32 s89, 0xcccccccc
	v_min_u32_e32 v104, v241, v0
	v_max_u32_e32 v105, v241, v0
	v_cndmask_b32_e64 v241, v105, v104, s[88:89]
	v_min_u32_e32 v106, v243, v1
	v_max_u32_e32 v107, v243, v1
	v_cndmask_b32_e64 v243, v107, v106, s[88:89]
	v_min_u32_e32 v104, v245, v2
	v_max_u32_e32 v105, v245, v2
	v_cndmask_b32_e64 v245, v105, v104, s[88:89]
	v_min_u32_e32 v106, v247, v3
	v_max_u32_e32 v107, v247, v3
	v_cndmask_b32_e64 v247, v107, v106, s[88:89]
	v_min_u32_e32 v104, v242, v4
	v_max_u32_e32 v105, v242, v4
	v_cndmask_b32_e64 v242, v105, v104, s[88:89]
	v_min_u32_e32 v106, v244, v5
	v_max_u32_e32 v107, v244, v5
	v_cndmask_b32_e64 v244, v107, v106, s[88:89]
	v_min_u32_e32 v104, v246, v6
	v_max_u32_e32 v105, v246, v6
	v_cndmask_b32_e64 v246, v105, v104, s[88:89]
	v_min_u32_e32 v106, v248, v7
	v_max_u32_e32 v107, v248, v7
	v_cndmask_b32_e64 v248, v107, v106, s[88:89]
	v_xor_b32_e32 v116, 4, v234
	ds_bpermute_b32 v0, v116, v241
	ds_bpermute_b32 v1, v116, v243
	ds_bpermute_b32 v2, v116, v245
	ds_bpermute_b32 v3, v116, v247
	ds_bpermute_b32 v4, v116, v242
	ds_bpermute_b32 v5, v116, v244
	ds_bpermute_b32 v6, v116, v246
	ds_bpermute_b32 v7, v116, v248
	s_waitcnt lgkmcnt(0)
	s_mov_b32 s88, 0x55555555
	s_mov_b32 s89, 0xaaaaaaaa
	v_min_u32_e32 v104, v241, v0
	v_max_u32_e32 v105, v241, v0
	v_cndmask_b32_e64 v241, v105, v104, s[88:89]
	v_min_u32_e32 v106, v243, v1
	v_max_u32_e32 v107, v243, v1
	v_cndmask_b32_e64 v243, v107, v106, s[88:89]
	v_min_u32_e32 v104, v245, v2
	v_max_u32_e32 v105, v245, v2
	v_cndmask_b32_e64 v245, v105, v104, s[88:89]
	v_min_u32_e32 v106, v247, v3
	v_max_u32_e32 v107, v247, v3
	v_cndmask_b32_e64 v247, v107, v106, s[88:89]
	v_min_u32_e32 v104, v242, v4
	v_max_u32_e32 v105, v242, v4
	v_cndmask_b32_e64 v242, v105, v104, s[88:89]
	v_min_u32_e32 v106, v244, v5
	v_max_u32_e32 v107, v244, v5
	v_cndmask_b32_e64 v244, v107, v106, s[88:89]
	v_min_u32_e32 v104, v246, v6
	v_max_u32_e32 v105, v246, v6
	v_cndmask_b32_e64 v246, v105, v104, s[88:89]
	v_min_u32_e32 v106, v248, v7
	v_max_u32_e32 v107, v248, v7
	v_cndmask_b32_e64 v248, v107, v106, s[88:89]
	v_xor_b32_e32 v116, 128, v234
	ds_bpermute_b32 v0, v116, v241
	ds_bpermute_b32 v1, v116, v243
	ds_bpermute_b32 v2, v116, v245
	ds_bpermute_b32 v3, v116, v247
	ds_bpermute_b32 v4, v116, v242
	ds_bpermute_b32 v5, v116, v244
	ds_bpermute_b32 v6, v116, v246
	ds_bpermute_b32 v7, v116, v248
	s_waitcnt lgkmcnt(0)
	s_mov_b32 s88, 0xffffffff
	s_mov_b32 s89, 0x0
	v_min_u32_e32 v104, v241, v0
	v_max_u32_e32 v105, v241, v0
	v_cndmask_b32_e64 v241, v105, v104, s[88:89]
	v_min_u32_e32 v106, v243, v1
	v_max_u32_e32 v107, v243, v1
	v_cndmask_b32_e64 v243, v107, v106, s[88:89]
	v_min_u32_e32 v104, v245, v2
	v_max_u32_e32 v105, v245, v2
	v_cndmask_b32_e64 v245, v105, v104, s[88:89]
	v_min_u32_e32 v106, v247, v3
	v_max_u32_e32 v107, v247, v3
	v_cndmask_b32_e64 v247, v107, v106, s[88:89]
	s_mov_b32 s88, 0x0
	s_mov_b32 s89, 0xffffffff
	v_min_u32_e32 v104, v242, v4
	v_max_u32_e32 v105, v242, v4
	v_cndmask_b32_e64 v242, v105, v104, s[88:89]
	v_min_u32_e32 v106, v244, v5
	v_max_u32_e32 v107, v244, v5
	v_cndmask_b32_e64 v244, v107, v106, s[88:89]
	v_min_u32_e32 v104, v246, v6
	v_max_u32_e32 v105, v246, v6
	v_cndmask_b32_e64 v246, v105, v104, s[88:89]
	v_min_u32_e32 v106, v248, v7
	v_max_u32_e32 v107, v248, v7
	v_cndmask_b32_e64 v248, v107, v106, s[88:89]
	v_xor_b32_e32 v116, 64, v234
	ds_bpermute_b32 v0, v116, v241
	ds_bpermute_b32 v1, v116, v243
	ds_bpermute_b32 v2, v116, v245
	ds_bpermute_b32 v3, v116, v247
	ds_bpermute_b32 v4, v116, v242
	ds_bpermute_b32 v5, v116, v244
	ds_bpermute_b32 v6, v116, v246
	ds_bpermute_b32 v7, v116, v248
	s_waitcnt lgkmcnt(0)
	s_mov_b32 s88, 0xffff
	s_mov_b32 s89, 0xffff
	v_min_u32_e32 v104, v241, v0
	v_max_u32_e32 v105, v241, v0
	v_cndmask_b32_e64 v241, v105, v104, s[88:89]
	v_min_u32_e32 v106, v243, v1
	v_max_u32_e32 v107, v243, v1
	v_cndmask_b32_e64 v243, v107, v106, s[88:89]
	v_min_u32_e32 v104, v245, v2
	v_max_u32_e32 v105, v245, v2
	v_cndmask_b32_e64 v245, v105, v104, s[88:89]
	v_min_u32_e32 v106, v247, v3
	v_max_u32_e32 v107, v247, v3
	v_cndmask_b32_e64 v247, v107, v106, s[88:89]
	s_mov_b32 s88, 0xffff0000
	s_mov_b32 s89, 0xffff0000
	v_min_u32_e32 v104, v242, v4
	v_max_u32_e32 v105, v242, v4
	v_cndmask_b32_e64 v242, v105, v104, s[88:89]
	v_min_u32_e32 v106, v244, v5
	v_max_u32_e32 v107, v244, v5
	v_cndmask_b32_e64 v244, v107, v106, s[88:89]
	v_min_u32_e32 v104, v246, v6
	v_max_u32_e32 v105, v246, v6
	v_cndmask_b32_e64 v246, v105, v104, s[88:89]
	v_min_u32_e32 v106, v248, v7
	v_max_u32_e32 v107, v248, v7
	v_cndmask_b32_e64 v248, v107, v106, s[88:89]
	v_xor_b32_e32 v116, 32, v234
	ds_bpermute_b32 v0, v116, v241
	ds_bpermute_b32 v1, v116, v243
	ds_bpermute_b32 v2, v116, v245
	ds_bpermute_b32 v3, v116, v247
	ds_bpermute_b32 v4, v116, v242
	ds_bpermute_b32 v5, v116, v244
	ds_bpermute_b32 v6, v116, v246
	ds_bpermute_b32 v7, v116, v248
	s_waitcnt lgkmcnt(0)
	s_mov_b32 s88, 0xff00ff
	s_mov_b32 s89, 0xff00ff
	v_min_u32_e32 v104, v241, v0
	v_max_u32_e32 v105, v241, v0
	v_cndmask_b32_e64 v241, v105, v104, s[88:89]
	v_min_u32_e32 v106, v243, v1
	v_max_u32_e32 v107, v243, v1
	v_cndmask_b32_e64 v243, v107, v106, s[88:89]
	v_min_u32_e32 v104, v245, v2
	v_max_u32_e32 v105, v245, v2
	v_cndmask_b32_e64 v245, v105, v104, s[88:89]
	v_min_u32_e32 v106, v247, v3
	v_max_u32_e32 v107, v247, v3
	v_cndmask_b32_e64 v247, v107, v106, s[88:89]
	s_mov_b32 s88, 0xff00ff00
	s_mov_b32 s89, 0xff00ff00
	v_min_u32_e32 v104, v242, v4
	v_max_u32_e32 v105, v242, v4
	v_cndmask_b32_e64 v242, v105, v104, s[88:89]
	v_min_u32_e32 v106, v244, v5
	v_max_u32_e32 v107, v244, v5
	v_cndmask_b32_e64 v244, v107, v106, s[88:89]
	v_min_u32_e32 v104, v246, v6
	v_max_u32_e32 v105, v246, v6
	v_cndmask_b32_e64 v246, v105, v104, s[88:89]
	v_min_u32_e32 v106, v248, v7
	v_max_u32_e32 v107, v248, v7
	v_cndmask_b32_e64 v248, v107, v106, s[88:89]
	v_xor_b32_e32 v116, 16, v234
	ds_bpermute_b32 v0, v116, v241
	ds_bpermute_b32 v1, v116, v243
	ds_bpermute_b32 v2, v116, v245
	ds_bpermute_b32 v3, v116, v247
	ds_bpermute_b32 v4, v116, v242
	ds_bpermute_b32 v5, v116, v244
	ds_bpermute_b32 v6, v116, v246
	ds_bpermute_b32 v7, v116, v248
	s_waitcnt lgkmcnt(0)
; DEV void sort_lists(int lane, int& myi0, int& myi1, float& myg0, float& myg1) {
; #pragma unroll
;     for (int k = 2; k <= 128; k <<= 1) {
; #pragma unroll
;       for (int j = k >> 1; j >= 1; j >>= 1) {
;         if (j == 64) {
;           const bool sw_ = myi1 < myi0;
;           const int ti = sw_ ? myi1 : myi0, tj = sw_ ? myi0 : myi1; const float tg = sw_ ? myg1 : myg0, th = sw_ ? myg0 : myg1;
;           myi0 = ti; myi1 = tj; myg0 = tg; myg1 = th;
;         } else {
;           const bool lower = (lane & j) == 0;
;           {
;             const bool up = (k == 128) ? true : ((k == 64) ? true : ((lane & k) == 0));
;             const int oi = __shfl_xor(myi0, j); const float og = __shfl_xor(myg0, j);
;             const bool take = (lower == up) ? (oi < myi0) : (oi > myi0);
;             myi0 = take ? oi : myi0; myg0 = take ? og : myg0;
;           }
;           {
;             const bool up = (k == 128) ? true : ((k == 64) ? false : ((lane & k) == 0));
;             const int oi = __shfl_xor(myi1, j); const float og = __shfl_xor(myg1, j);
;             const bool take = (lower == up) ? (oi < myi1) : (oi > myi1);
;             myi1 = take ? oi : myi1; myg1 = take ? og : myg1;
;           }
;         }
;       }
;     }
; }
	s_mov_b32 s88, 0xf0f0f0f
	s_mov_b32 s89, 0xf0f0f0f
	v_min_u32_e32 v104, v241, v0
	v_max_u32_e32 v105, v241, v0
	v_cndmask_b32_e64 v241, v105, v104, s[88:89]
	v_min_u32_e32 v106, v243, v1
	v_max_u32_e32 v107, v243, v1
	v_cndmask_b32_e64 v243, v107, v106, s[88:89]
	v_min_u32_e32 v104, v245, v2
	v_max_u32_e32 v105, v245, v2
	v_cndmask_b32_e64 v245, v105, v104, s[88:89]
	v_min_u32_e32 v106, v247, v3
	v_max_u32_e32 v107, v247, v3
	v_cndmask_b32_e64 v247, v107, v106, s[88:89]
	s_mov_b32 s88, 0xf0f0f0f0
	s_mov_b32 s89, 0xf0f0f0f0
	v_min_u32_e32 v104, v242, v4
	v_max_u32_e32 v105, v242, v4
	v_cndmask_b32_e64 v242, v105, v104, s[88:89]
	v_min_u32_e32 v106, v244, v5
	v_max_u32_e32 v107, v244, v5
	v_cndmask_b32_e64 v244, v107, v106, s[88:89]
	v_min_u32_e32 v104, v246, v6
	v_max_u32_e32 v105, v246, v6
	v_cndmask_b32_e64 v246, v105, v104, s[88:89]
	v_min_u32_e32 v106, v248, v7
	v_max_u32_e32 v107, v248, v7
	v_cndmask_b32_e64 v248, v107, v106, s[88:89]
	v_xor_b32_e32 v116, 8, v234
	ds_bpermute_b32 v0, v116, v241
	ds_bpermute_b32 v1, v116, v243
	ds_bpermute_b32 v2, v116, v245
	ds_bpermute_b32 v3, v116, v247
	ds_bpermute_b32 v4, v116, v242
	ds_bpermute_b32 v5, v116, v244
	ds_bpermute_b32 v6, v116, v246
	ds_bpermute_b32 v7, v116, v248
	s_waitcnt lgkmcnt(0)
	s_mov_b32 s88, 0x33333333
	s_mov_b32 s89, 0x33333333
	v_min_u32_e32 v104, v241, v0
	v_max_u32_e32 v105, v241, v0
	v_cndmask_b32_e64 v241, v105, v104, s[88:89]
	v_min_u32_e32 v106, v243, v1
	v_max_u32_e32 v107, v243, v1
	v_cndmask_b32_e64 v243, v107, v106, s[88:89]
	v_min_u32_e32 v104, v245, v2
	v_max_u32_e32 v105, v245, v2
	v_cndmask_b32_e64 v245, v105, v104, s[88:89]
	v_min_u32_e32 v106, v247, v3
	v_max_u32_e32 v107, v247, v3
	v_cndmask_b32_e64 v247, v107, v106, s[88:89]
	s_mov_b32 s88, 0xcccccccc
	s_mov_b32 s89, 0xcccccccc
	v_min_u32_e32 v104, v242, v4
	v_max_u32_e32 v105, v242, v4
	v_cndmask_b32_e64 v242, v105, v104, s[88:89]
	v_min_u32_e32 v106, v244, v5
	v_max_u32_e32 v107, v244, v5
	v_cndmask_b32_e64 v244, v107, v106, s[88:89]
	v_min_u32_e32 v104, v246, v6
	v_max_u32_e32 v105, v246, v6
	v_cndmask_b32_e64 v246, v105, v104, s[88:89]
	v_min_u32_e32 v106, v248, v7
	v_max_u32_e32 v107, v248, v7
	v_cndmask_b32_e64 v248, v107, v106, s[88:89]
	v_xor_b32_e32 v116, 4, v234
	ds_bpermute_b32 v0, v116, v241
	ds_bpermute_b32 v1, v116, v243
	ds_bpermute_b32 v2, v116, v245
	ds_bpermute_b32 v3, v116, v247
	ds_bpermute_b32 v4, v116, v242
	ds_bpermute_b32 v5, v116, v244
	ds_bpermute_b32 v6, v116, v246
	ds_bpermute_b32 v7, v116, v248
	s_waitcnt lgkmcnt(0)
	s_mov_b32 s88, 0x55555555
	s_mov_b32 s89, 0x55555555
	v_min_u32_e32 v104, v241, v0
	v_max_u32_e32 v105, v241, v0
	v_cndmask_b32_e64 v241, v105, v104, s[88:89]
	v_min_u32_e32 v106, v243, v1
	v_max_u32_e32 v107, v243, v1
	v_cndmask_b32_e64 v243, v107, v106, s[88:89]
	v_min_u32_e32 v104, v245, v2
	v_max_u32_e32 v105, v245, v2
	v_cndmask_b32_e64 v245, v105, v104, s[88:89]
	v_min_u32_e32 v106, v247, v3
	v_max_u32_e32 v107, v247, v3
	v_cndmask_b32_e64 v247, v107, v106, s[88:89]
	s_mov_b32 s88, 0xaaaaaaaa
	s_mov_b32 s89, 0xaaaaaaaa
	v_min_u32_e32 v104, v242, v4
	v_max_u32_e32 v105, v242, v4
	v_cndmask_b32_e64 v242, v105, v104, s[88:89]
	v_min_u32_e32 v106, v244, v5
	v_max_u32_e32 v107, v244, v5
	v_cndmask_b32_e64 v244, v107, v106, s[88:89]
	v_min_u32_e32 v104, v246, v6
	v_max_u32_e32 v105, v246, v6
	v_cndmask_b32_e64 v246, v105, v104, s[88:89]
	v_min_u32_e32 v106, v248, v7
	v_max_u32_e32 v107, v248, v7
	v_cndmask_b32_e64 v248, v107, v106, s[88:89]
	v_min_u32_e32 v104, v241, v242
	v_max_u32_e32 v242, v241, v242
	v_mov_b32_e32 v241, v104
	v_min_u32_e32 v106, v243, v244
	v_max_u32_e32 v244, v243, v244
	v_mov_b32_e32 v243, v106
	v_min_u32_e32 v104, v245, v246
	v_max_u32_e32 v246, v245, v246
	v_mov_b32_e32 v245, v104
	v_min_u32_e32 v106, v247, v248
	v_max_u32_e32 v248, v247, v248
	v_mov_b32_e32 v247, v106
	v_xor_b32_e32 v116, 128, v234
	ds_bpermute_b32 v0, v116, v241
	ds_bpermute_b32 v1, v116, v243
	ds_bpermute_b32 v2, v116, v245
	ds_bpermute_b32 v3, v116, v247
	ds_bpermute_b32 v4, v116, v242
	ds_bpermute_b32 v5, v116, v244
	ds_bpermute_b32 v6, v116, v246
	ds_bpermute_b32 v7, v116, v248
	s_waitcnt lgkmcnt(0)
	s_mov_b32 s88, 0xffffffff
	s_mov_b32 s89, 0x0
	v_min_u32_e32 v104, v241, v0
	v_max_u32_e32 v105, v241, v0
	v_cndmask_b32_e64 v241, v105, v104, s[88:89]
	v_min_u32_e32 v106, v243, v1
	v_max_u32_e32 v107, v243, v1
	v_cndmask_b32_e64 v243, v107, v106, s[88:89]
	v_min_u32_e32 v104, v245, v2
	v_max_u32_e32 v105, v245, v2
	v_cndmask_b32_e64 v245, v105, v104, s[88:89]
	v_min_u32_e32 v106, v247, v3
	v_max_u32_e32 v107, v247, v3
	v_cndmask_b32_e64 v247, v107, v106, s[88:89]
	v_min_u32_e32 v104, v242, v4
	v_max_u32_e32 v105, v242, v4
	v_cndmask_b32_e64 v242, v105, v104, s[88:89]
	v_min_u32_e32 v106, v244, v5
	v_max_u32_e32 v107, v244, v5
	v_cndmask_b32_e64 v244, v107, v106, s[88:89]
	v_min_u32_e32 v104, v246, v6
	v_max_u32_e32 v105, v246, v6
	v_cndmask_b32_e64 v246, v105, v104, s[88:89]
	v_min_u32_e32 v106, v248, v7
	v_max_u32_e32 v107, v248, v7
	v_cndmask_b32_e64 v248, v107, v106, s[88:89]
	v_xor_b32_e32 v116, 64, v234
	ds_bpermute_b32 v0, v116, v241
	ds_bpermute_b32 v1, v116, v243
	ds_bpermute_b32 v2, v116, v245
	ds_bpermute_b32 v3, v116, v247
	ds_bpermute_b32 v4, v116, v242
	ds_bpermute_b32 v5, v116, v244
	ds_bpermute_b32 v6, v116, v246
	ds_bpermute_b32 v7, v116, v248
	s_waitcnt lgkmcnt(0)
; DEV void sort_lists(int lane, int& myi0, int& myi1, float& myg0, float& myg1) {
; #pragma unroll
;     for (int k = 2; k <= 128; k <<= 1) {
; #pragma unroll
;       for (int j = k >> 1; j >= 1; j >>= 1) {
;         if (j == 64) {
;           const bool sw_ = myi1 < myi0;
;           const int ti = sw_ ? myi1 : myi0, tj = sw_ ? myi0 : myi1; const float tg = sw_ ? myg1 : myg0, th = sw_ ? myg0 : myg1;
;           myi0 = ti; myi1 = tj; myg0 = tg; myg1 = th;
;         } else {
;           const bool lower = (lane & j) == 0;
;           {
;             const bool up = (k == 128) ? true : ((k == 64) ? true : ((lane & k) == 0));
;             const int oi = __shfl_xor(myi0, j); const float og = __shfl_xor(myg0, j);
;             const bool take = (lower == up) ? (oi < myi0) : (oi > myi0);
;             myi0 = take ? oi : myi0; myg0 = take ? og : myg0;
;           }
;           {
;             const bool up = (k == 128) ? true : ((k == 64) ? false : ((lane & k) == 0));
;             const int oi = __shfl_xor(myi1, j); const float og = __shfl_xor(myg1, j);
;             const bool take = (lower == up) ? (oi < myi1) : (oi > myi1);
;             myi1 = take ? oi : myi1; myg1 = take ? og : myg1;
;           }
;         }
;       }
;     }
; }
	s_mov_b32 s88, 0xffff
	s_mov_b32 s89, 0xffff
	v_min_u32_e32 v104, v241, v0
	v_max_u32_e32 v105, v241, v0
	v_cndmask_b32_e64 v241, v105, v104, s[88:89]
	v_min_u32_e32 v106, v243, v1
	v_max_u32_e32 v107, v243, v1
	v_cndmask_b32_e64 v243, v107, v106, s[88:89]
	v_min_u32_e32 v104, v245, v2
	v_max_u32_e32 v105, v245, v2
	v_cndmask_b32_e64 v245, v105, v104, s[88:89]
	v_min_u32_e32 v106, v247, v3
	v_max_u32_e32 v107, v247, v3
	v_cndmask_b32_e64 v247, v107, v106, s[88:89]
	v_min_u32_e32 v104, v242, v4
	v_max_u32_e32 v105, v242, v4
	v_cndmask_b32_e64 v242, v105, v104, s[88:89]
	v_min_u32_e32 v106, v244, v5
	v_max_u32_e32 v107, v244, v5
	v_cndmask_b32_e64 v244, v107, v106, s[88:89]
	v_min_u32_e32 v104, v246, v6
	v_max_u32_e32 v105, v246, v6
	v_cndmask_b32_e64 v246, v105, v104, s[88:89]
	v_min_u32_e32 v106, v248, v7
	v_max_u32_e32 v107, v248, v7
	v_cndmask_b32_e64 v248, v107, v106, s[88:89]
	v_xor_b32_e32 v116, 32, v234
	ds_bpermute_b32 v0, v116, v241
	ds_bpermute_b32 v1, v116, v243
	ds_bpermute_b32 v2, v116, v245
	ds_bpermute_b32 v3, v116, v247
	ds_bpermute_b32 v4, v116, v242
	ds_bpermute_b32 v5, v116, v244
	ds_bpermute_b32 v6, v116, v246
	ds_bpermute_b32 v7, v116, v248
	s_waitcnt lgkmcnt(0)
	s_mov_b32 s88, 0xff00ff
	s_mov_b32 s89, 0xff00ff
	v_min_u32_e32 v104, v241, v0
	v_max_u32_e32 v105, v241, v0
	v_cndmask_b32_e64 v241, v105, v104, s[88:89]
	v_min_u32_e32 v106, v243, v1
	v_max_u32_e32 v107, v243, v1
	v_cndmask_b32_e64 v243, v107, v106, s[88:89]
	v_min_u32_e32 v104, v245, v2
	v_max_u32_e32 v105, v245, v2
	v_cndmask_b32_e64 v245, v105, v104, s[88:89]
	v_min_u32_e32 v106, v247, v3
	v_max_u32_e32 v107, v247, v3
	v_cndmask_b32_e64 v247, v107, v106, s[88:89]
	v_min_u32_e32 v104, v242, v4
	v_max_u32_e32 v105, v242, v4
	v_cndmask_b32_e64 v242, v105, v104, s[88:89]
	v_min_u32_e32 v106, v244, v5
	v_max_u32_e32 v107, v244, v5
	v_cndmask_b32_e64 v244, v107, v106, s[88:89]
	v_min_u32_e32 v104, v246, v6
	v_max_u32_e32 v105, v246, v6
	v_cndmask_b32_e64 v246, v105, v104, s[88:89]
	v_min_u32_e32 v106, v248, v7
	v_max_u32_e32 v107, v248, v7
	v_cndmask_b32_e64 v248, v107, v106, s[88:89]
	v_xor_b32_e32 v116, 16, v234
	ds_bpermute_b32 v0, v116, v241
	ds_bpermute_b32 v1, v116, v243
	ds_bpermute_b32 v2, v116, v245
	ds_bpermute_b32 v3, v116, v247
	ds_bpermute_b32 v4, v116, v242
	ds_bpermute_b32 v5, v116, v244
	ds_bpermute_b32 v6, v116, v246
	ds_bpermute_b32 v7, v116, v248
	s_waitcnt lgkmcnt(0)
	s_mov_b32 s88, 0xf0f0f0f
	s_mov_b32 s89, 0xf0f0f0f
	v_min_u32_e32 v104, v241, v0
	v_max_u32_e32 v105, v241, v0
	v_cndmask_b32_e64 v241, v105, v104, s[88:89]
	v_min_u32_e32 v106, v243, v1
	v_max_u32_e32 v107, v243, v1
	v_cndmask_b32_e64 v243, v107, v106, s[88:89]
	v_min_u32_e32 v104, v245, v2
	v_max_u32_e32 v105, v245, v2
	v_cndmask_b32_e64 v245, v105, v104, s[88:89]
	v_min_u32_e32 v106, v247, v3
	v_max_u32_e32 v107, v247, v3
	v_cndmask_b32_e64 v247, v107, v106, s[88:89]
	v_min_u32_e32 v104, v242, v4
	v_max_u32_e32 v105, v242, v4
	v_cndmask_b32_e64 v242, v105, v104, s[88:89]
	v_min_u32_e32 v106, v244, v5
	v_max_u32_e32 v107, v244, v5
	v_cndmask_b32_e64 v244, v107, v106, s[88:89]
	v_min_u32_e32 v104, v246, v6
	v_max_u32_e32 v105, v246, v6
	v_cndmask_b32_e64 v246, v105, v104, s[88:89]
	v_min_u32_e32 v106, v248, v7
	v_max_u32_e32 v107, v248, v7
	v_cndmask_b32_e64 v248, v107, v106, s[88:89]
	v_xor_b32_e32 v116, 8, v234
	ds_bpermute_b32 v0, v116, v241
	ds_bpermute_b32 v1, v116, v243
	ds_bpermute_b32 v2, v116, v245
	ds_bpermute_b32 v3, v116, v247
	ds_bpermute_b32 v4, v116, v242
	ds_bpermute_b32 v5, v116, v244
	ds_bpermute_b32 v6, v116, v246
	ds_bpermute_b32 v7, v116, v248
	s_waitcnt lgkmcnt(0)
	s_mov_b32 s88, 0x33333333
	s_mov_b32 s89, 0x33333333
	v_min_u32_e32 v104, v241, v0
	v_max_u32_e32 v105, v241, v0
	v_cndmask_b32_e64 v241, v105, v104, s[88:89]
	v_min_u32_e32 v106, v243, v1
	v_max_u32_e32 v107, v243, v1
	v_cndmask_b32_e64 v243, v107, v106, s[88:89]
	v_min_u32_e32 v104, v245, v2
	v_max_u32_e32 v105, v245, v2
	v_cndmask_b32_e64 v245, v105, v104, s[88:89]
	v_min_u32_e32 v106, v247, v3
	v_max_u32_e32 v107, v247, v3
	v_cndmask_b32_e64 v247, v107, v106, s[88:89]
	v_min_u32_e32 v104, v242, v4
	v_max_u32_e32 v105, v242, v4
	v_cndmask_b32_e64 v242, v105, v104, s[88:89]
	v_min_u32_e32 v106, v244, v5
	v_max_u32_e32 v107, v244, v5
	v_cndmask_b32_e64 v244, v107, v106, s[88:89]
	v_min_u32_e32 v104, v246, v6
	v_max_u32_e32 v105, v246, v6
	v_cndmask_b32_e64 v246, v105, v104, s[88:89]
	v_min_u32_e32 v106, v248, v7
	v_max_u32_e32 v107, v248, v7
	v_cndmask_b32_e64 v248, v107, v106, s[88:89]
	v_xor_b32_e32 v116, 4, v234
	ds_bpermute_b32 v0, v116, v241
	ds_bpermute_b32 v1, v116, v243
	ds_bpermute_b32 v2, v116, v245
	ds_bpermute_b32 v3, v116, v247
	ds_bpermute_b32 v4, v116, v242
	ds_bpermute_b32 v5, v116, v244
	ds_bpermute_b32 v6, v116, v246
	ds_bpermute_b32 v7, v116, v248
	s_waitcnt lgkmcnt(0)
	s_mov_b32 s88, 0x55555555
	s_mov_b32 s89, 0x55555555
	v_min_u32_e32 v104, v241, v0
	v_max_u32_e32 v105, v241, v0
	v_cndmask_b32_e64 v241, v105, v104, s[88:89]
	v_min_u32_e32 v106, v243, v1
	v_max_u32_e32 v107, v243, v1
	v_cndmask_b32_e64 v243, v107, v106, s[88:89]
	v_min_u32_e32 v104, v245, v2
	v_max_u32_e32 v105, v245, v2
	v_cndmask_b32_e64 v245, v105, v104, s[88:89]
	v_min_u32_e32 v106, v247, v3
	v_max_u32_e32 v107, v247, v3
	v_cndmask_b32_e64 v247, v107, v106, s[88:89]
	v_min_u32_e32 v104, v242, v4
	v_max_u32_e32 v105, v242, v4
	v_cndmask_b32_e64 v242, v105, v104, s[88:89]
	v_min_u32_e32 v106, v244, v5
	v_max_u32_e32 v107, v244, v5
	v_cndmask_b32_e64 v244, v107, v106, s[88:89]
	v_min_u32_e32 v104, v246, v6
	v_max_u32_e32 v105, v246, v6
	v_cndmask_b32_e64 v246, v105, v104, s[88:89]
	v_min_u32_e32 v106, v248, v7
	v_max_u32_e32 v107, v248, v7
	v_cndmask_b32_e64 v248, v107, v106, s[88:89]
	v_mov_b32_e32 v117, 0
	s_lshl_b32 s98, s2, 11
	s_add_u32 s98, s98, s101
	v_add_u32_e32 v116, s98, v234
	ds_write_b32 v116, v241 offset:0
	ds_write_b32 v116, v242 offset:256
	ds_write_b32 v116, v243 offset:512
	ds_write_b32 v116, v244 offset:768
	ds_write_b32 v116, v245 offset:1024
	ds_write_b32 v116, v246 offset:1280
	ds_write_b32 v116, v247 offset:1536
	ds_write_b32 v116, v248 offset:1792
	v_add_u32_e32 v118, 0x10000, v116
	ds_write_b32 v118, v117 offset:0
	ds_write_b32 v118, v117 offset:256
	ds_write_b32 v118, v117 offset:512
	ds_write_b32 v118, v117 offset:768
	ds_write_b32 v118, v117 offset:1024
	ds_write_b32 v118, v117 offset:1280
	ds_write_b32 v118, v117 offset:1536
	ds_write_b32 v118, v117 offset:1792
	s_add_u32 s2, s2, 1
	s_cmp_lt_u32 s2, 4
	s_cbranch_scc1 .Lpg0_p0
; #define PG_ISSUE(BUF, TAB, e0_) do { const int isrc_ = ((e0_) < 64) ? myi0 : myi1; \
;       _Pragma("unroll") for (int e = 0; e < 8; ++e) { const int idx_ = __builtin_amdgcn_readlane(isrc_, ((e0_) + e) & 63); \
;         BUF[e] = *(const u32x4*)((TAB) + (size_t)idx_ * 1024 + lane * 16); } } while (0)
; DEV void peer_gather(const Params& P, int l, int m0, const int* idxs, const float* gs) {
;     ...
;     PG_ISSUE(b0, U, 0);
; #pragma nounroll
;     for (int e0 = 0; e0 < 128; e0 += 16) {
;       PG_ISSUE(b1, U, e0 + 8);
;       PG_U8(b0, 0, e0);
;       if (e0 + 16 < 128) PG_ISSUE(b0, U, e0 + 16); else PG_ISSUE(b0, V, 0);
;       PG_U8(b1, 0, e0 + 8);
;     }
	s_waitcnt lgkmcnt(0)
	v_lshrrev_b32_e32 v248, 3, v233
	v_readfirstlane_b32 s82, v128
	v_readfirstlane_b32 s83, v129
	s_nop 4
	v_readfirstlane_b32 s80, v124
	v_readfirstlane_b32 s81, v125
	s_nop 4
	s_mov_b32 s2, 0xffffff80
	s_mov_b32 s86, 0xcccccccc
	s_mov_b32 s87, 0xcccccccc
	s_mov_b32 s88, 0xaaaaaaaa
	s_mov_b32 s89, 0xaaaaaaaa
	s_mov_b32 s90, 0xf0f0f0f0
	s_mov_b32 s91, 0xf0f0f0f0
	s_lshl_b32 vcc_lo, s3, 11
	s_add_u32 s82, s82, vcc_lo
	s_addc_u32 s83, s83, 0
	v_add_u32_e32 v246, s101, v234
	v_add_u32_e32 v247, 0x10000, v246
	s_mov_b32 s100, 0
	s_mov_b32 s98, 0
	s_mov_b32 s99, 0
	s_lshl3_add_u32 vcc_lo, s98, s99
	v_lshl_add_u32 v119, vcc_lo, 8, v236
	global_load_dwordx4 v[80:83], v119, s[82:83]
	global_load_dwordx4 v[84:87], v119, s[82:83] offset:16
	v_lshl_add_u32 v116, s98, 9, v246
	ds_read_b32 v134, v116
	ds_read_b32 v135, v116 offset:256
	s_lshl_b32 vcc_lo, s99, 21
	s_add_u32 s84, s80, vcc_lo
	s_addc_u32 s85, s81, 0
	s_waitcnt lgkmcnt(0)
	ds_bpermute_b32 v142, v249, v134
	ds_bpermute_b32 v143, v250, v134
	s_waitcnt lgkmcnt(0)
	v_and_or_b32 v142, v142, s2, v235
	v_and_or_b32 v143, v143, s2, v235
	global_load_dwordx4 v[0:3], v142, s[84:85]
	global_load_dwordx4 v[4:7], v143, s[84:85]
	ds_bpermute_b32 v142, v251, v134
	ds_bpermute_b32 v143, v252, v134
	s_waitcnt lgkmcnt(0)
	v_and_or_b32 v142, v142, s2, v235
	v_and_or_b32 v143, v143, s2, v235
	global_load_dwordx4 v[8:11], v142, s[84:85]
	global_load_dwordx4 v[12:15], v143, s[84:85]
	ds_bpermute_b32 v142, v253, v134
	ds_bpermute_b32 v143, v254, v134
	s_waitcnt lgkmcnt(0)
	v_and_or_b32 v142, v142, s2, v235
	v_and_or_b32 v143, v143, s2, v235
	global_load_dwordx4 v[16:19], v142, s[84:85]
	global_load_dwordx4 v[20:23], v143, s[84:85]
	ds_bpermute_b32 v142, v255, v134
	ds_bpermute_b32 v143, v153, v134
	s_waitcnt lgkmcnt(0)
	v_and_or_b32 v142, v142, s2, v235
	v_and_or_b32 v143, v143, s2, v235
	global_load_dwordx4 v[24:27], v142, s[84:85]
	global_load_dwordx4 v[28:31], v143, s[84:85]
	ds_bpermute_b32 v142, v249, v135
	ds_bpermute_b32 v143, v250, v135
	s_waitcnt lgkmcnt(0)
	v_and_or_b32 v142, v142, s2, v235
	v_and_or_b32 v143, v143, s2, v235
	global_load_dwordx4 v[32:35], v142, s[84:85]
	global_load_dwordx4 v[36:39], v143, s[84:85]
	ds_bpermute_b32 v142, v251, v135
	ds_bpermute_b32 v143, v252, v135
	s_waitcnt lgkmcnt(0)
	v_and_or_b32 v142, v142, s2, v235
	v_and_or_b32 v143, v143, s2, v235
	global_load_dwordx4 v[40:43], v142, s[84:85]
	global_load_dwordx4 v[44:47], v143, s[84:85]
	ds_bpermute_b32 v142, v253, v135
	ds_bpermute_b32 v143, v254, v135
	s_waitcnt lgkmcnt(0)
	v_and_or_b32 v142, v142, s2, v235
	v_and_or_b32 v143, v143, s2, v235
	global_load_dwordx4 v[48:51], v142, s[84:85]
	global_load_dwordx4 v[52:55], v143, s[84:85]
	ds_bpermute_b32 v142, v255, v135
	ds_bpermute_b32 v143, v153, v135
	s_waitcnt lgkmcnt(0)
	v_and_or_b32 v142, v142, s2, v235
	v_and_or_b32 v143, v143, s2, v235
	global_load_dwordx4 v[56:59], v142, s[84:85]
	global_load_dwordx4 v[60:63], v143, s[84:85]
	s_mov_b32 s92, 1
	v_lshl_add_u32 v116, s92, 9, v246
	ds_read_b32 v134, v116
	ds_read_b32 v135, v116 offset:256
.Lpg0_uloop:
	s_and_b32 s98, s100, 15
	s_add_u32 s92, s100, 1
	s_min_u32 s92, s92, 127
	s_lshr_b32 s93, s92, 4
	s_and_b32 s92, s92, 15
	s_waitcnt lgkmcnt(0)
	ds_bpermute_b32 v142, v249, v134
	ds_bpermute_b32 v143, v250, v134
	s_waitcnt vmcnt(16)
	v_mov_b32_e32 v64, v80
	v_mov_b32_e32 v65, v81
	v_mov_b32_e32 v66, v82
	v_mov_b32_e32 v67, v83
	v_mov_b32_e32 v68, v84
	v_mov_b32_e32 v69, v85
	v_mov_b32_e32 v70, v86
	v_mov_b32_e32 v71, v87
	s_lshl3_add_u32 vcc_lo, s92, s93
	v_lshl_add_u32 v119, vcc_lo, 8, v236
	global_load_dwordx4 v[80:83], v119, s[82:83]
	global_load_dwordx4 v[84:87], v119, s[82:83] offset:16
	s_lshl_b32 vcc_lo, s93, 21
	s_add_u32 s84, s80, vcc_lo
	s_addc_u32 s85, s81, 0
	s_waitcnt vmcnt(16) lgkmcnt(0)
	ds_bpermute_b32 v244, v251, v134
	ds_bpermute_b32 v245, v252, v134
	v_cvt_scalef32_pk_bf16_fp8 v104, v0, 1.0
	v_cvt_scalef32_pk_bf16_fp8 v106, v4, 1.0
	v_cvt_scalef32_pk_bf16_fp8 v105, v0, 1.0 op_sel:[1,0,0]
	v_cvt_scalef32_pk_bf16_fp8 v107, v4, 1.0 op_sel:[1,0,0]
	v_cvt_scalef32_pk_bf16_fp8 v108, v1, 1.0
	v_cvt_scalef32_pk_bf16_fp8 v109, v1, 1.0 op_sel:[1,0,0]
	v_mfma_f32_4x4x4_16b_bf16 v[72:75], v[104:105], v[64:65], 0
	v_cvt_scalef32_pk_bf16_fp8 v110, v5, 1.0
	v_cvt_scalef32_pk_bf16_fp8 v111, v5, 1.0 op_sel:[1,0,0]
	v_mfma_f32_4x4x4_16b_bf16 v[76:79], v[106:107], v[64:65], 0
	v_cvt_scalef32_pk_bf16_fp8 v104, v2, 1.0
	v_cvt_scalef32_pk_bf16_fp8 v105, v2, 1.0 op_sel:[1,0,0]
	v_mfma_f32_4x4x4_16b_bf16 v[72:75], v[108:109], v[66:67], v[72:75]
	v_cvt_scalef32_pk_bf16_fp8 v106, v6, 1.0
	v_cvt_scalef32_pk_bf16_fp8 v107, v6, 1.0 op_sel:[1,0,0]
	v_mfma_f32_4x4x4_16b_bf16 v[76:79], v[110:111], v[66:67], v[76:79]
	v_cvt_scalef32_pk_bf16_fp8 v108, v3, 1.0
	v_cvt_scalef32_pk_bf16_fp8 v109, v3, 1.0 op_sel:[1,0,0]
	v_mfma_f32_4x4x4_16b_bf16 v[72:75], v[104:105], v[68:69], v[72:75]
	v_cvt_scalef32_pk_bf16_fp8 v110, v7, 1.0
	v_cvt_scalef32_pk_bf16_fp8 v111, v7, 1.0 op_sel:[1,0,0]
	v_mfma_f32_4x4x4_16b_bf16 v[76:79], v[106:107], v[68:69], v[76:79]
	v_and_or_b32 v142, v142, s2, v235
	v_and_or_b32 v143, v143, s2, v235
	global_load_dwordx4 v[0:3], v142, s[84:85]
	global_load_dwordx4 v[4:7], v143, s[84:85]
	s_waitcnt vmcnt(16) lgkmcnt(0)
	ds_bpermute_b32 v142, v253, v134
	ds_bpermute_b32 v143, v254, v134
	v_cvt_scalef32_pk_bf16_fp8 v104, v8, 1.0
	v_cvt_scalef32_pk_bf16_fp8 v105, v8, 1.0 op_sel:[1,0,0]
	v_mfma_f32_4x4x4_16b_bf16 v[72:75], v[108:109], v[70:71], v[72:75]
	v_cvt_scalef32_pk_bf16_fp8 v106, v12, 1.0
	v_cvt_scalef32_pk_bf16_fp8 v107, v12, 1.0 op_sel:[1,0,0]
	v_mfma_f32_4x4x4_16b_bf16 v[76:79], v[110:111], v[70:71], v[76:79]
	v_cvt_scalef32_pk_bf16_fp8 v108, v9, 1.0
	v_cvt_scalef32_pk_bf16_fp8 v110, v13, 1.0
	v_cvt_scalef32_pk_bf16_fp8 v109, v9, 1.0 op_sel:[1,0,0]
	v_cvt_scalef32_pk_bf16_fp8 v111, v13, 1.0 op_sel:[1,0,0]
	v_cndmask_b32_e64 v148, v72, v73, s[88:89]
	v_cndmask_b32_e64 v149, v74, v75, s[88:89]
	v_cndmask_b32_e64 v88, v148, v149, s[86:87]
	v_mfma_f32_4x4x4_16b_bf16 v[72:75], v[104:105], v[64:65], 0
	v_cndmask_b32_e64 v150, v76, v77, s[88:89]
	v_cndmask_b32_e64 v151, v78, v79, s[88:89]
	v_cndmask_b32_e64 v89, v150, v151, s[86:87]
	v_mfma_f32_4x4x4_16b_bf16 v[76:79], v[106:107], v[64:65], 0
	v_cvt_scalef32_pk_bf16_fp8 v104, v10, 1.0
	v_cvt_scalef32_pk_bf16_fp8 v105, v10, 1.0 op_sel:[1,0,0]
	v_mfma_f32_4x4x4_16b_bf16 v[72:75], v[108:109], v[66:67], v[72:75]
	v_cvt_scalef32_pk_bf16_fp8 v106, v14, 1.0
	v_cvt_scalef32_pk_bf16_fp8 v107, v14, 1.0 op_sel:[1,0,0]
	v_mfma_f32_4x4x4_16b_bf16 v[76:79], v[110:111], v[66:67], v[76:79]
	v_cvt_scalef32_pk_bf16_fp8 v108, v11, 1.0
	v_cvt_scalef32_pk_bf16_fp8 v109, v11, 1.0 op_sel:[1,0,0]
	v_mfma_f32_4x4x4_16b_bf16 v[72:75], v[104:105], v[68:69], v[72:75]
	v_cvt_scalef32_pk_bf16_fp8 v110, v15, 1.0
	v_cvt_scalef32_pk_bf16_fp8 v111, v15, 1.0 op_sel:[1,0,0]
	v_mfma_f32_4x4x4_16b_bf16 v[76:79], v[106:107], v[68:69], v[76:79]
	v_and_or_b32 v244, v244, s2, v235
	v_and_or_b32 v245, v245, s2, v235
	global_load_dwordx4 v[8:11], v244, s[84:85]
	global_load_dwordx4 v[12:15], v245, s[84:85]
	s_waitcnt vmcnt(16) lgkmcnt(0)
	ds_bpermute_b32 v244, v255, v134
	ds_bpermute_b32 v245, v153, v134
	v_cvt_scalef32_pk_bf16_fp8 v104, v16, 1.0
	v_cvt_scalef32_pk_bf16_fp8 v105, v16, 1.0 op_sel:[1,0,0]
	v_mfma_f32_4x4x4_16b_bf16 v[72:75], v[108:109], v[70:71], v[72:75]
	v_cvt_scalef32_pk_bf16_fp8 v106, v20, 1.0
	v_cvt_scalef32_pk_bf16_fp8 v107, v20, 1.0 op_sel:[1,0,0]
	v_mfma_f32_4x4x4_16b_bf16 v[76:79], v[110:111], v[70:71], v[76:79]
	v_cvt_scalef32_pk_bf16_fp8 v108, v17, 1.0
	v_cvt_scalef32_pk_bf16_fp8 v110, v21, 1.0
	v_cvt_scalef32_pk_bf16_fp8 v109, v17, 1.0 op_sel:[1,0,0]
	v_cvt_scalef32_pk_bf16_fp8 v111, v21, 1.0 op_sel:[1,0,0]
	v_cndmask_b32_e64 v148, v72, v73, s[88:89]
	v_cndmask_b32_e64 v149, v74, v75, s[88:89]
	v_cndmask_b32_e64 v90, v148, v149, s[86:87]
	v_mfma_f32_4x4x4_16b_bf16 v[72:75], v[104:105], v[64:65], 0
	v_cndmask_b32_e64 v150, v76, v77, s[88:89]
	v_cndmask_b32_e64 v151, v78, v79, s[88:89]
	v_cndmask_b32_e64 v91, v150, v151, s[86:87]
	v_mfma_f32_4x4x4_16b_bf16 v[76:79], v[106:107], v[64:65], 0
	v_cvt_scalef32_pk_bf16_fp8 v104, v18, 1.0
	v_cvt_scalef32_pk_bf16_fp8 v105, v18, 1.0 op_sel:[1,0,0]
	v_mfma_f32_4x4x4_16b_bf16 v[72:75], v[108:109], v[66:67], v[72:75]
	v_cvt_scalef32_pk_bf16_fp8 v106, v22, 1.0
	v_cvt_scalef32_pk_bf16_fp8 v107, v22, 1.0 op_sel:[1,0,0]
	v_mfma_f32_4x4x4_16b_bf16 v[76:79], v[110:111], v[66:67], v[76:79]
	v_cvt_scalef32_pk_bf16_fp8 v108, v19, 1.0
	v_cvt_scalef32_pk_bf16_fp8 v109, v19, 1.0 op_sel:[1,0,0]
	v_mfma_f32_4x4x4_16b_bf16 v[72:75], v[104:105], v[68:69], v[72:75]
	v_cvt_scalef32_pk_bf16_fp8 v110, v23, 1.0
	v_cvt_scalef32_pk_bf16_fp8 v111, v23, 1.0 op_sel:[1,0,0]
	v_mfma_f32_4x4x4_16b_bf16 v[76:79], v[106:107], v[68:69], v[76:79]
	v_and_or_b32 v142, v142, s2, v235
	v_and_or_b32 v143, v143, s2, v235
	global_load_dwordx4 v[16:19], v142, s[84:85]
	global_load_dwordx4 v[20:23], v143, s[84:85]
	s_waitcnt vmcnt(16) lgkmcnt(0)
	ds_bpermute_b32 v142, v249, v135
	ds_bpermute_b32 v143, v250, v135
	v_cvt_scalef32_pk_bf16_fp8 v104, v24, 1.0
	v_cvt_scalef32_pk_bf16_fp8 v105, v24, 1.0 op_sel:[1,0,0]
	v_mfma_f32_4x4x4_16b_bf16 v[72:75], v[108:109], v[70:71], v[72:75]
	v_cvt_scalef32_pk_bf16_fp8 v106, v28, 1.0
	v_cvt_scalef32_pk_bf16_fp8 v107, v28, 1.0 op_sel:[1,0,0]
	v_mfma_f32_4x4x4_16b_bf16 v[76:79], v[110:111], v[70:71], v[76:79]
	v_cvt_scalef32_pk_bf16_fp8 v108, v25, 1.0
	v_cvt_scalef32_pk_bf16_fp8 v110, v29, 1.0
	v_cvt_scalef32_pk_bf16_fp8 v109, v25, 1.0 op_sel:[1,0,0]
	v_cvt_scalef32_pk_bf16_fp8 v111, v29, 1.0 op_sel:[1,0,0]
	v_cndmask_b32_e64 v148, v72, v73, s[88:89]
	v_cndmask_b32_e64 v149, v74, v75, s[88:89]
	v_cndmask_b32_e64 v92, v148, v149, s[86:87]
	v_mfma_f32_4x4x4_16b_bf16 v[72:75], v[104:105], v[64:65], 0
	v_cndmask_b32_e64 v150, v76, v77, s[88:89]
	v_cndmask_b32_e64 v151, v78, v79, s[88:89]
	v_cndmask_b32_e64 v93, v150, v151, s[86:87]
	v_mfma_f32_4x4x4_16b_bf16 v[76:79], v[106:107], v[64:65], 0
	v_cvt_scalef32_pk_bf16_fp8 v104, v26, 1.0
	v_cvt_scalef32_pk_bf16_fp8 v105, v26, 1.0 op_sel:[1,0,0]
	v_mfma_f32_4x4x4_16b_bf16 v[72:75], v[108:109], v[66:67], v[72:75]
	v_cvt_scalef32_pk_bf16_fp8 v106, v30, 1.0
	v_cvt_scalef32_pk_bf16_fp8 v107, v30, 1.0 op_sel:[1,0,0]
	v_mfma_f32_4x4x4_16b_bf16 v[76:79], v[110:111], v[66:67], v[76:79]
	v_cvt_scalef32_pk_bf16_fp8 v108, v27, 1.0
	v_cvt_scalef32_pk_bf16_fp8 v109, v27, 1.0 op_sel:[1,0,0]
	v_mfma_f32_4x4x4_16b_bf16 v[72:75], v[104:105], v[68:69], v[72:75]
	v_cvt_scalef32_pk_bf16_fp8 v110, v31, 1.0
	v_cvt_scalef32_pk_bf16_fp8 v111, v31, 1.0 op_sel:[1,0,0]
	v_mfma_f32_4x4x4_16b_bf16 v[76:79], v[106:107], v[68:69], v[76:79]
	v_and_or_b32 v244, v244, s2, v235
	v_and_or_b32 v245, v245, s2, v235
	global_load_dwordx4 v[24:27], v244, s[84:85]
	global_load_dwordx4 v[28:31], v245, s[84:85]
	s_waitcnt vmcnt(16) lgkmcnt(0)
	ds_bpermute_b32 v244, v251, v135
	ds_bpermute_b32 v245, v252, v135
	v_cvt_scalef32_pk_bf16_fp8 v104, v32, 1.0
	v_cvt_scalef32_pk_bf16_fp8 v105, v32, 1.0 op_sel:[1,0,0]
	v_mfma_f32_4x4x4_16b_bf16 v[72:75], v[108:109], v[70:71], v[72:75]
	v_cvt_scalef32_pk_bf16_fp8 v106, v36, 1.0
	v_cvt_scalef32_pk_bf16_fp8 v107, v36, 1.0 op_sel:[1,0,0]
	v_mfma_f32_4x4x4_16b_bf16 v[76:79], v[110:111], v[70:71], v[76:79]
	v_cvt_scalef32_pk_bf16_fp8 v108, v33, 1.0
	v_cvt_scalef32_pk_bf16_fp8 v110, v37, 1.0
	v_cvt_scalef32_pk_bf16_fp8 v109, v33, 1.0 op_sel:[1,0,0]
	v_cvt_scalef32_pk_bf16_fp8 v111, v37, 1.0 op_sel:[1,0,0]
	v_cndmask_b32_e64 v148, v72, v73, s[88:89]
	v_cndmask_b32_e64 v149, v74, v75, s[88:89]
	v_cndmask_b32_e64 v94, v148, v149, s[86:87]
	v_mfma_f32_4x4x4_16b_bf16 v[72:75], v[104:105], v[64:65], 0
	v_cndmask_b32_e64 v150, v76, v77, s[88:89]
	v_cndmask_b32_e64 v151, v78, v79, s[88:89]
	v_cndmask_b32_e64 v95, v150, v151, s[86:87]
	v_mfma_f32_4x4x4_16b_bf16 v[76:79], v[106:107], v[64:65], 0
	v_cvt_scalef32_pk_bf16_fp8 v104, v34, 1.0
	v_cvt_scalef32_pk_bf16_fp8 v105, v34, 1.0 op_sel:[1,0,0]
	v_mfma_f32_4x4x4_16b_bf16 v[72:75], v[108:109], v[66:67], v[72:75]
	v_cvt_scalef32_pk_bf16_fp8 v106, v38, 1.0
	v_cvt_scalef32_pk_bf16_fp8 v107, v38, 1.0 op_sel:[1,0,0]
	v_mfma_f32_4x4x4_16b_bf16 v[76:79], v[110:111], v[66:67], v[76:79]
	v_cvt_scalef32_pk_bf16_fp8 v108, v35, 1.0
	v_cvt_scalef32_pk_bf16_fp8 v109, v35, 1.0 op_sel:[1,0,0]
	v_mfma_f32_4x4x4_16b_bf16 v[72:75], v[104:105], v[68:69], v[72:75]
	v_cvt_scalef32_pk_bf16_fp8 v110, v39, 1.0
	v_cvt_scalef32_pk_bf16_fp8 v111, v39, 1.0 op_sel:[1,0,0]
	v_mfma_f32_4x4x4_16b_bf16 v[76:79], v[106:107], v[68:69], v[76:79]
	v_and_or_b32 v142, v142, s2, v235
	v_and_or_b32 v143, v143, s2, v235
	global_load_dwordx4 v[32:35], v142, s[84:85]
	global_load_dwordx4 v[36:39], v143, s[84:85]
	s_waitcnt vmcnt(16) lgkmcnt(0)
	ds_bpermute_b32 v142, v253, v135
	ds_bpermute_b32 v143, v254, v135
	v_cvt_scalef32_pk_bf16_fp8 v104, v40, 1.0
	v_cvt_scalef32_pk_bf16_fp8 v105, v40, 1.0 op_sel:[1,0,0]
	v_mfma_f32_4x4x4_16b_bf16 v[72:75], v[108:109], v[70:71], v[72:75]
	v_cvt_scalef32_pk_bf16_fp8 v106, v44, 1.0
	v_cvt_scalef32_pk_bf16_fp8 v107, v44, 1.0 op_sel:[1,0,0]
	v_mfma_f32_4x4x4_16b_bf16 v[76:79], v[110:111], v[70:71], v[76:79]
	v_cvt_scalef32_pk_bf16_fp8 v108, v41, 1.0
	v_cvt_scalef32_pk_bf16_fp8 v110, v45, 1.0
	v_cvt_scalef32_pk_bf16_fp8 v109, v41, 1.0 op_sel:[1,0,0]
	v_cvt_scalef32_pk_bf16_fp8 v111, v45, 1.0 op_sel:[1,0,0]
	v_cndmask_b32_e64 v148, v72, v73, s[88:89]
	v_cndmask_b32_e64 v149, v74, v75, s[88:89]
	v_cndmask_b32_e64 v96, v148, v149, s[86:87]
	v_mfma_f32_4x4x4_16b_bf16 v[72:75], v[104:105], v[64:65], 0
	v_cndmask_b32_e64 v150, v76, v77, s[88:89]
	v_cndmask_b32_e64 v151, v78, v79, s[88:89]
	v_cndmask_b32_e64 v97, v150, v151, s[86:87]
	v_mfma_f32_4x4x4_16b_bf16 v[76:79], v[106:107], v[64:65], 0
	v_cvt_scalef32_pk_bf16_fp8 v104, v42, 1.0
	v_cvt_scalef32_pk_bf16_fp8 v105, v42, 1.0 op_sel:[1,0,0]
	v_mfma_f32_4x4x4_16b_bf16 v[72:75], v[108:109], v[66:67], v[72:75]
	v_cvt_scalef32_pk_bf16_fp8 v106, v46, 1.0
	v_cvt_scalef32_pk_bf16_fp8 v107, v46, 1.0 op_sel:[1,0,0]
	v_mfma_f32_4x4x4_16b_bf16 v[76:79], v[110:111], v[66:67], v[76:79]
	v_cvt_scalef32_pk_bf16_fp8 v108, v43, 1.0
	v_cvt_scalef32_pk_bf16_fp8 v109, v43, 1.0 op_sel:[1,0,0]
	v_mfma_f32_4x4x4_16b_bf16 v[72:75], v[104:105], v[68:69], v[72:75]
	v_cvt_scalef32_pk_bf16_fp8 v110, v47, 1.0
	v_cvt_scalef32_pk_bf16_fp8 v111, v47, 1.0 op_sel:[1,0,0]
	v_mfma_f32_4x4x4_16b_bf16 v[76:79], v[106:107], v[68:69], v[76:79]
	v_and_or_b32 v244, v244, s2, v235
	v_and_or_b32 v245, v245, s2, v235
	global_load_dwordx4 v[40:43], v244, s[84:85]
	global_load_dwordx4 v[44:47], v245, s[84:85]
	s_waitcnt vmcnt(16) lgkmcnt(0)
	ds_bpermute_b32 v244, v255, v135
	ds_bpermute_b32 v245, v153, v135
	v_cvt_scalef32_pk_bf16_fp8 v104, v48, 1.0
	v_cvt_scalef32_pk_bf16_fp8 v105, v48, 1.0 op_sel:[1,0,0]
	v_mfma_f32_4x4x4_16b_bf16 v[72:75], v[108:109], v[70:71], v[72:75]
	v_cvt_scalef32_pk_bf16_fp8 v106, v52, 1.0
	v_cvt_scalef32_pk_bf16_fp8 v107, v52, 1.0 op_sel:[1,0,0]
	v_mfma_f32_4x4x4_16b_bf16 v[76:79], v[110:111], v[70:71], v[76:79]
	v_cvt_scalef32_pk_bf16_fp8 v108, v49, 1.0
	v_cvt_scalef32_pk_bf16_fp8 v110, v53, 1.0
	v_cvt_scalef32_pk_bf16_fp8 v109, v49, 1.0 op_sel:[1,0,0]
	v_cvt_scalef32_pk_bf16_fp8 v111, v53, 1.0 op_sel:[1,0,0]
	v_cndmask_b32_e64 v148, v72, v73, s[88:89]
	v_cndmask_b32_e64 v149, v74, v75, s[88:89]
	v_cndmask_b32_e64 v98, v148, v149, s[86:87]
	v_mfma_f32_4x4x4_16b_bf16 v[72:75], v[104:105], v[64:65], 0
	v_cndmask_b32_e64 v150, v76, v77, s[88:89]
	v_cndmask_b32_e64 v151, v78, v79, s[88:89]
	v_cndmask_b32_e64 v99, v150, v151, s[86:87]
	v_mfma_f32_4x4x4_16b_bf16 v[76:79], v[106:107], v[64:65], 0
	v_cvt_scalef32_pk_bf16_fp8 v104, v50, 1.0
	v_cvt_scalef32_pk_bf16_fp8 v105, v50, 1.0 op_sel:[1,0,0]
	v_mfma_f32_4x4x4_16b_bf16 v[72:75], v[108:109], v[66:67], v[72:75]
	v_cvt_scalef32_pk_bf16_fp8 v106, v54, 1.0
	v_cvt_scalef32_pk_bf16_fp8 v107, v54, 1.0 op_sel:[1,0,0]
	v_mfma_f32_4x4x4_16b_bf16 v[76:79], v[110:111], v[66:67], v[76:79]
	v_cvt_scalef32_pk_bf16_fp8 v108, v51, 1.0
	v_cvt_scalef32_pk_bf16_fp8 v109, v51, 1.0 op_sel:[1,0,0]
	v_mfma_f32_4x4x4_16b_bf16 v[72:75], v[104:105], v[68:69], v[72:75]
	v_cvt_scalef32_pk_bf16_fp8 v110, v55, 1.0
	v_cvt_scalef32_pk_bf16_fp8 v111, v55, 1.0 op_sel:[1,0,0]
	v_mfma_f32_4x4x4_16b_bf16 v[76:79], v[106:107], v[68:69], v[76:79]
	v_and_or_b32 v142, v142, s2, v235
	v_and_or_b32 v143, v143, s2, v235
	global_load_dwordx4 v[48:51], v142, s[84:85]
	global_load_dwordx4 v[52:55], v143, s[84:85]
	s_waitcnt vmcnt(16) lgkmcnt(0)
; #define PG_ISSUE(BUF, TAB, e0_) do { const int isrc_ = ((e0_) < 64) ? myi0 : myi1; \
;       _Pragma("unroll") for (int e = 0; e < 8; ++e) { const int idx_ = __builtin_amdgcn_readlane(isrc_, ((e0_) + e) & 63); \
;         BUF[e] = *(const u32x4*)((TAB) + (size_t)idx_ * 1024 + lane * 16); } } while (0)
; DEV void peer_gather(const Params& P, int l, int m0, const int* idxs, const float* gs) {
;     ...
;     PG_ISSUE(b0, U, 0);
; #pragma nounroll
;     for (int e0 = 0; e0 < 128; e0 += 16) {
;       PG_ISSUE(b1, U, e0 + 8);
;       PG_U8(b0, 0, e0);
;       if (e0 + 16 < 128) PG_ISSUE(b0, U, e0 + 16); else PG_ISSUE(b0, V, 0);
;       PG_U8(b1, 0, e0 + 8);
;     }
	v_cvt_scalef32_pk_bf16_fp8 v104, v56, 1.0
	v_cvt_scalef32_pk_bf16_fp8 v105, v56, 1.0 op_sel:[1,0,0]
	v_mfma_f32_4x4x4_16b_bf16 v[72:75], v[108:109], v[70:71], v[72:75]
	v_cvt_scalef32_pk_bf16_fp8 v106, v60, 1.0
	v_cvt_scalef32_pk_bf16_fp8 v107, v60, 1.0 op_sel:[1,0,0]
	v_mfma_f32_4x4x4_16b_bf16 v[76:79], v[110:111], v[70:71], v[76:79]
	v_cvt_scalef32_pk_bf16_fp8 v108, v57, 1.0
	v_cvt_scalef32_pk_bf16_fp8 v110, v61, 1.0
	v_cvt_scalef32_pk_bf16_fp8 v109, v57, 1.0 op_sel:[1,0,0]
	v_cvt_scalef32_pk_bf16_fp8 v111, v61, 1.0 op_sel:[1,0,0]
	v_cndmask_b32_e64 v148, v72, v73, s[88:89]
	v_cndmask_b32_e64 v149, v74, v75, s[88:89]
	v_cndmask_b32_e64 v100, v148, v149, s[86:87]
	v_mfma_f32_4x4x4_16b_bf16 v[72:75], v[104:105], v[64:65], 0
	v_cndmask_b32_e64 v150, v76, v77, s[88:89]
	v_cndmask_b32_e64 v151, v78, v79, s[88:89]
	v_cndmask_b32_e64 v101, v150, v151, s[86:87]
	v_mfma_f32_4x4x4_16b_bf16 v[76:79], v[106:107], v[64:65], 0
	v_cvt_scalef32_pk_bf16_fp8 v104, v58, 1.0
	v_cvt_scalef32_pk_bf16_fp8 v105, v58, 1.0 op_sel:[1,0,0]
	v_mfma_f32_4x4x4_16b_bf16 v[72:75], v[108:109], v[66:67], v[72:75]
	v_cvt_scalef32_pk_bf16_fp8 v106, v62, 1.0
	v_cvt_scalef32_pk_bf16_fp8 v107, v62, 1.0 op_sel:[1,0,0]
	v_mfma_f32_4x4x4_16b_bf16 v[76:79], v[110:111], v[66:67], v[76:79]
	v_cvt_scalef32_pk_bf16_fp8 v108, v59, 1.0
	v_cvt_scalef32_pk_bf16_fp8 v109, v59, 1.0 op_sel:[1,0,0]
	v_mfma_f32_4x4x4_16b_bf16 v[72:75], v[104:105], v[68:69], v[72:75]
	v_cvt_scalef32_pk_bf16_fp8 v110, v63, 1.0
	v_cvt_scalef32_pk_bf16_fp8 v111, v63, 1.0 op_sel:[1,0,0]
	v_mfma_f32_4x4x4_16b_bf16 v[76:79], v[106:107], v[68:69], v[76:79]
	v_and_or_b32 v244, v244, s2, v235
	v_and_or_b32 v245, v245, s2, v235
	global_load_dwordx4 v[56:59], v244, s[84:85]
	global_load_dwordx4 v[60:63], v245, s[84:85]
	v_mfma_f32_4x4x4_16b_bf16 v[72:75], v[108:109], v[70:71], v[72:75]
	v_mfma_f32_4x4x4_16b_bf16 v[76:79], v[110:111], v[70:71], v[76:79]
	s_add_u32 s92, s100, 2
	s_and_b32 s92, s92, 15
	v_lshl_add_u32 v116, s92, 9, v246
	ds_read_b32 v134, v116
	ds_read_b32 v135, v116 offset:256
	v_lshl_add_u32 v117, s98, 9, v247
	ds_read_b32 v136, v117
	ds_read_b32 v137, v117 offset:256
	v_cndmask_b32_e64 v148, v72, v73, s[88:89]
	v_cndmask_b32_e64 v149, v74, v75, s[88:89]
	v_cndmask_b32_e64 v102, v148, v149, s[86:87]
	v_cndmask_b32_e64 v150, v76, v77, s[88:89]
	v_cndmask_b32_e64 v151, v78, v79, s[88:89]
	v_cndmask_b32_e64 v103, v150, v151, s[86:87]
	v_cndmask_b32_e64 v144, v88, v92, s[90:91]
	v_cndmask_b32_e64 v92, v92, v88, s[90:91]
	v_cndmask_b32_e64 v145, v89, v93, s[90:91]
	v_cndmask_b32_e64 v93, v93, v89, s[90:91]
	v_cndmask_b32_e64 v146, v90, v94, s[90:91]
	v_cndmask_b32_e64 v94, v94, v90, s[90:91]
	v_cndmask_b32_e64 v147, v91, v95, s[90:91]
	v_cndmask_b32_e64 v95, v95, v91, s[90:91]
	v_add_f32_dpp v88, v92, v144 row_half_mirror row_mask:0xf bank_mask:0xf
	v_add_f32_dpp v89, v93, v145 row_half_mirror row_mask:0xf bank_mask:0xf
	v_add_f32_dpp v90, v94, v146 row_half_mirror row_mask:0xf bank_mask:0xf
	v_add_f32_dpp v91, v95, v147 row_half_mirror row_mask:0xf bank_mask:0xf
	v_cndmask_b32_e64 v144, v96, v100, s[90:91]
	v_cndmask_b32_e64 v100, v100, v96, s[90:91]
	v_cndmask_b32_e64 v145, v97, v101, s[90:91]
	v_cndmask_b32_e64 v101, v101, v97, s[90:91]
	v_cndmask_b32_e64 v146, v98, v102, s[90:91]
	v_cndmask_b32_e64 v102, v102, v98, s[90:91]
	v_cndmask_b32_e64 v147, v99, v103, s[90:91]
	v_cndmask_b32_e64 v103, v103, v99, s[90:91]
	v_add_f32_dpp v96, v100, v144 row_half_mirror row_mask:0xf bank_mask:0xf
	v_add_f32_dpp v97, v101, v145 row_half_mirror row_mask:0xf bank_mask:0xf
	v_add_f32_dpp v98, v102, v146 row_half_mirror row_mask:0xf bank_mask:0xf
	v_add_f32_dpp v99, v103, v147 row_half_mirror row_mask:0xf bank_mask:0xf
	v_cndmask_b32_e64 v144, v88, v90, s[86:87]
	v_cndmask_b32_e64 v90, v90, v88, s[86:87]
	v_cndmask_b32_e64 v145, v89, v91, s[86:87]
	v_cndmask_b32_e64 v91, v91, v89, s[86:87]
	v_cndmask_b32_e64 v146, v96, v98, s[86:87]
	v_cndmask_b32_e64 v98, v98, v96, s[86:87]
	v_cndmask_b32_e64 v147, v97, v99, s[86:87]
	v_cndmask_b32_e64 v99, v99, v97, s[86:87]
	v_add_f32_dpp v88, v90, v144 quad_perm:[2,3,0,1] row_mask:0xf bank_mask:0xf
	v_add_f32_dpp v89, v91, v145 quad_perm:[2,3,0,1] row_mask:0xf bank_mask:0xf
	v_add_f32_dpp v96, v98, v146 quad_perm:[2,3,0,1] row_mask:0xf bank_mask:0xf
	v_add_f32_dpp v97, v99, v147 quad_perm:[2,3,0,1] row_mask:0xf bank_mask:0xf
	v_cndmask_b32_e64 v144, v88, v89, s[88:89]
	v_cndmask_b32_e64 v89, v89, v88, s[88:89]
	v_cndmask_b32_e64 v145, v96, v97, s[88:89]
	v_cndmask_b32_e64 v97, v97, v96, s[88:89]
	s_nop 1
	v_add_f32_dpp v88, v89, v144 quad_perm:[1,0,3,2] row_mask:0xf bank_mask:0xf
	v_add_f32_dpp v96, v97, v145 quad_perm:[1,0,3,2] row_mask:0xf bank_mask:0xf
	s_nop 0
	ds_bpermute_b32 v144, v239, v88
	ds_bpermute_b32 v145, v239, v96
	s_waitcnt lgkmcnt(0)
	v_add_f32_e32 v136, v136, v144
	v_add_f32_e32 v137, v137, v145
	ds_write_b32 v117, v136
	ds_write_b32 v117, v137 offset:256
	s_add_u32 s100, s100, 1
	s_cmp_lt_u32 s100, 128
	s_cbranch_scc1 .Lpg0_uloop
	s_waitcnt vmcnt(0) lgkmcnt(0)
	s_mov_b32 s2, 0
.Lpg0_act:
	v_readlane_b32 s82, v231, 28
	v_readlane_b32 s83, v231, 29
	s_nop 4
	s_lshl_b32 s98, s2, 11
	s_add_u32 s98, s98, s101
	v_add_u32_e32 v116, s98, v234
	v_add_u32_e32 v117, 0x10000, v116
	ds_read_b32 v0, v116 offset:0
	ds_read_b32 v8, v117 offset:0
	ds_read_b32 v1, v116 offset:256
	ds_read_b32 v9, v117 offset:256
	ds_read_b32 v2, v116 offset:512
	ds_read_b32 v10, v117 offset:512
	ds_read_b32 v3, v116 offset:768
	ds_read_b32 v11, v117 offset:768
	ds_read_b32 v4, v116 offset:1024
	ds_read_b32 v12, v117 offset:1024
	ds_read_b32 v5, v116 offset:1280
	ds_read_b32 v13, v117 offset:1280
	ds_read_b32 v6, v116 offset:1536
	ds_read_b32 v14, v117 offset:1536
	ds_read_b32 v7, v116 offset:1792
	ds_read_b32 v15, v117 offset:1792
	s_waitcnt lgkmcnt(0)
	s_lshl_b32 s99, s2, 2
	s_add_u32 s99, s99, s33
	s_add_u32 s99, s99, 0
	s_lshl_b32 s99, s99, 9
	v_and_b32_e32 v0, 0x7f, v0
	v_lshl_add_u32 v0, v0, 2, s99
	global_load_dword v16, v0, s[82:83]
	v_and_b32_e32 v1, 0x7f, v1
	v_lshl_add_u32 v1, v1, 2, s99
	global_load_dword v17, v1, s[82:83]
	s_lshl_b32 s99, s2, 2
	s_add_u32 s99, s99, s33
	s_add_u32 s99, s99, 1
	s_lshl_b32 s99, s99, 9
	v_and_b32_e32 v2, 0x7f, v2
	v_lshl_add_u32 v2, v2, 2, s99
	global_load_dword v18, v2, s[82:83]
	v_and_b32_e32 v3, 0x7f, v3
	v_lshl_add_u32 v3, v3, 2, s99
	global_load_dword v19, v3, s[82:83]
	s_lshl_b32 s99, s2, 2
	s_add_u32 s99, s99, s33
	s_add_u32 s99, s99, 2
	s_lshl_b32 s99, s99, 9
	v_and_b32_e32 v4, 0x7f, v4
	v_lshl_add_u32 v4, v4, 2, s99
	global_load_dword v20, v4, s[82:83]
	v_and_b32_e32 v5, 0x7f, v5
	v_lshl_add_u32 v5, v5, 2, s99
	global_load_dword v21, v5, s[82:83]
	s_lshl_b32 s99, s2, 2
	s_add_u32 s99, s99, s33
	s_add_u32 s99, s99, 3
	s_lshl_b32 s99, s99, 9
	v_and_b32_e32 v6, 0x7f, v6
	v_lshl_add_u32 v6, v6, 2, s99
	global_load_dword v22, v6, s[82:83]
	v_and_b32_e32 v7, 0x7f, v7
	v_lshl_add_u32 v7, v7, 2, s99
	global_load_dword v23, v7, s[82:83]
	v_mul_f32_e32 v8, 0x3c800000, v8
	v_mul_f32_e32 v9, 0x3c800000, v9
	v_mul_f32_e32 v10, 0x3c800000, v10
	v_mul_f32_e32 v11, 0x3c800000, v11
	v_mul_f32_e32 v12, 0x3c800000, v12
	v_mul_f32_e32 v13, 0x3c800000, v13
	v_mul_f32_e32 v14, 0x3c800000, v14
	v_mul_f32_e32 v15, 0x3c800000, v15
	v_mul_f32_e32 v24, 0x3d372713, v8
	v_mul_f32_e32 v25, 0x3d372713, v9
	v_mul_f32_e32 v26, 0x3d372713, v10
	v_mul_f32_e32 v27, 0x3d372713, v11
	v_mul_f32_e32 v28, 0x3d372713, v12
	v_mul_f32_e32 v29, 0x3d372713, v13
	v_mul_f32_e32 v30, 0x3d372713, v14
	v_mul_f32_e32 v31, 0x3d372713, v15
	v_mul_f32_e32 v24, v8, v24
	v_mul_f32_e32 v25, v9, v25
	v_mul_f32_e32 v26, v10, v26
	v_mul_f32_e32 v27, v11, v27
	v_mul_f32_e32 v28, v12, v28
	v_mul_f32_e32 v29, v13, v29
	v_mul_f32_e32 v30, v14, v30
	v_mul_f32_e32 v31, v15, v31
	v_fma_f32 v24, v8, v24, v8
	v_fma_f32 v25, v9, v25, v9
	v_fma_f32 v26, v10, v26, v10
	v_fma_f32 v27, v11, v27, v11
	v_fma_f32 v28, v12, v28, v12
	v_fma_f32 v29, v13, v29, v13
	v_fma_f32 v30, v14, v30, v14
	v_fma_f32 v31, v15, v31, v15
	v_mul_f32_e32 v24, 0xbfcc422a, v24
	v_mul_f32_e32 v25, 0xbfcc422a, v25
	v_mul_f32_e32 v26, 0xbfcc422a, v26
	v_mul_f32_e32 v27, 0xbfcc422a, v27
	v_mul_f32_e32 v28, 0xbfcc422a, v28
	v_mul_f32_e32 v29, 0xbfcc422a, v29
	v_mul_f32_e32 v30, 0xbfcc422a, v30
	v_mul_f32_e32 v31, 0xbfcc422a, v31
	v_mul_f32_e32 v24, 0x3fb8aa3b, v24
	v_mul_f32_e32 v25, 0x3fb8aa3b, v25
	v_mul_f32_e32 v26, 0x3fb8aa3b, v26
	v_mul_f32_e32 v27, 0x3fb8aa3b, v27
	v_mul_f32_e32 v28, 0x3fb8aa3b, v28
	v_mul_f32_e32 v29, 0x3fb8aa3b, v29
	v_mul_f32_e32 v30, 0x3fb8aa3b, v30
	v_mul_f32_e32 v31, 0x3fb8aa3b, v31
	v_exp_f32_e32 v24, v24
	v_exp_f32_e32 v25, v25
	v_exp_f32_e32 v26, v26
	v_exp_f32_e32 v27, v27
	v_exp_f32_e32 v28, v28
	v_exp_f32_e32 v29, v29
	v_exp_f32_e32 v30, v30
	v_exp_f32_e32 v31, v31
	s_nop 0
	v_add_f32_e32 v24, 1.0, v24
	v_add_f32_e32 v25, 1.0, v25
	v_add_f32_e32 v26, 1.0, v26
	v_add_f32_e32 v27, 1.0, v27
	v_add_f32_e32 v28, 1.0, v28
	v_add_f32_e32 v29, 1.0, v29
	v_add_f32_e32 v30, 1.0, v30
	v_add_f32_e32 v31, 1.0, v31
	v_rcp_f32_e32 v24, v24
	v_rcp_f32_e32 v25, v25
	v_rcp_f32_e32 v26, v26
	v_rcp_f32_e32 v27, v27
	v_rcp_f32_e32 v28, v28
	v_rcp_f32_e32 v29, v29
	v_rcp_f32_e32 v30, v30
	v_rcp_f32_e32 v31, v31
	s_nop 0
	v_mul_f32_e32 v24, v8, v24
	v_mul_f32_e32 v25, v9, v25
	v_mul_f32_e32 v26, v10, v26
	v_mul_f32_e32 v27, v11, v27
	v_mul_f32_e32 v28, v12, v28
	v_mul_f32_e32 v29, v13, v29
	v_mul_f32_e32 v30, v14, v30
	v_mul_f32_e32 v31, v15, v31
	s_waitcnt vmcnt(0)
	v_mul_f32_e32 v24, v24, v16
	ds_write_b32 v117, v24 offset:0
	v_mul_f32_e32 v25, v25, v17
	ds_write_b32 v117, v25 offset:256
	v_mul_f32_e32 v26, v26, v18
	ds_write_b32 v117, v26 offset:512
	v_mul_f32_e32 v27, v27, v19
	ds_write_b32 v117, v27 offset:768
	v_mul_f32_e32 v28, v28, v20
	ds_write_b32 v117, v28 offset:1024
	v_mul_f32_e32 v29, v29, v21
	ds_write_b32 v117, v29 offset:1280
	v_mul_f32_e32 v30, v30, v22
	ds_write_b32 v117, v30 offset:1536
	v_mul_f32_e32 v31, v31, v23
	ds_write_b32 v117, v31 offset:1792
	s_add_u32 s2, s2, 1
	s_cmp_lt_u32 s2, 4
	s_cbranch_scc1 .Lpg0_act
; #define PG_ISSUE(BUF, TAB, e0_) do { const int isrc_ = ((e0_) < 64) ? myi0 : myi1; \
;       _Pragma("unroll") for (int e = 0; e < 8; ++e) { const int idx_ = __builtin_amdgcn_readlane(isrc_, ((e0_) + e) & 63); \
;         BUF[e] = *(const u32x4*)((TAB) + (size_t)idx_ * 1024 + lane * 16); } } while (0)
; DEV void peer_gather(const Params& P, int l, int m0, const int* idxs, const float* gs) {
;     ...
;     PG_ISSUE(b0, U, 0);
; #pragma nounroll
;     for (int e0 = 0; e0 < 128; e0 += 16) {
;       PG_ISSUE(b1, U, e0 + 8);
;       PG_U8(b0, 0, e0);
;       if (e0 + 16 < 128) PG_ISSUE(b0, U, e0 + 16); else PG_ISSUE(b0, V, 0);
;       PG_U8(b1, 0, e0 + 8);
;     }
;     float* hrow = P.out + tok * DM + lane * 16;
;     f32x4 hv[4];
; #pragma unroll
;     for (int q = 0; q < 4; ++q) hv[q] = *(const f32x4*)(hrow + 4 * q);
;     if (i + 1 < 16) {
;       const int tn = tt + 1;
;       nxa = *(const u32x4*)(hn + (size_t)(m0 + tn) * DM + lane * 16); nxb = *(const u32x4*)(hn + (size_t)(m0 + tn) * DM + lane * 16 + 8);
;       ni0 = idxs[tn * 128 + lane]; ni1 = idxs[tn * 128 + 64 + lane]; ng0 = gs[tn * 128 + lane]; ng1 = gs[tn * 128 + 64 + lane];
;     }
; #pragma nounroll
;     for (int e0 = 0; e0 < 128; e0 += 16) {
;       PG_ISSUE(b1, V, e0 + 8);
;       if (e0 == 64 && i + 1 < 16) sort_lists(lane, ni0, ni1, ng0, ng1);
;       PG_V16(b0, e0);
;       if (e0 + 16 < 128) PG_ISSUE(b0, V, e0 + 16);
;       PG_V16(b1, e0 + 8);
	s_waitcnt lgkmcnt(0)
	v_add_u32_e32 v249, 0, v237
	v_add_u32_e32 v250, 32, v237
	v_add_u32_e32 v251, 64, v237
	v_add_u32_e32 v252, 96, v237
	v_add_u32_e32 v253, 128, v237
	v_add_u32_e32 v254, 160, v237
	v_add_u32_e32 v255, 192, v237
	v_add_u32_e32 v153, 224, v237
	v_readfirstlane_b32 s80, v126
	v_readfirstlane_b32 s81, v127
	s_nop 4
	v_add_u32_e32 v246, s101, v234
	v_add_u32_e32 v247, 0x10000, v246
	v_readfirstlane_b32 s82, v132
	v_readfirstlane_b32 s83, v133
	s_nop 4
	s_mov_b32 s2, 0xffffff80
	s_mov_b32 s100, 0
	s_mov_b32 s98, 0
	s_mov_b32 s99, 0
	v_lshl_add_u32 v116, s98, 9, v246
	ds_read_b32 v134, v116
	ds_read_b32 v135, v116 offset:256
	s_lshl_b32 vcc_lo, s99, 21
	s_add_u32 s84, s80, vcc_lo
	s_addc_u32 s85, s81, 0
	s_waitcnt lgkmcnt(0)
	ds_bpermute_b32 v142, v249, v134
	ds_bpermute_b32 v143, v250, v134
	s_waitcnt lgkmcnt(0)
	v_and_or_b32 v142, v142, s2, v235
	v_and_or_b32 v143, v143, s2, v235
	global_load_dwordx4 v[0:3], v142, s[84:85]
	global_load_dwordx4 v[4:7], v143, s[84:85]
	ds_bpermute_b32 v142, v251, v134
	ds_bpermute_b32 v143, v252, v134
	s_waitcnt lgkmcnt(0)
	v_and_or_b32 v142, v142, s2, v235
	v_and_or_b32 v143, v143, s2, v235
	global_load_dwordx4 v[8:11], v142, s[84:85]
	global_load_dwordx4 v[12:15], v143, s[84:85]
	ds_bpermute_b32 v142, v253, v134
	ds_bpermute_b32 v143, v254, v134
	s_waitcnt lgkmcnt(0)
	v_and_or_b32 v142, v142, s2, v235
	v_and_or_b32 v143, v143, s2, v235
	global_load_dwordx4 v[16:19], v142, s[84:85]
	global_load_dwordx4 v[20:23], v143, s[84:85]
	ds_bpermute_b32 v142, v255, v134
	ds_bpermute_b32 v143, v153, v134
	s_waitcnt lgkmcnt(0)
	v_and_or_b32 v142, v142, s2, v235
	v_and_or_b32 v143, v143, s2, v235
	global_load_dwordx4 v[24:27], v142, s[84:85]
	global_load_dwordx4 v[28:31], v143, s[84:85]
	ds_bpermute_b32 v142, v249, v135
	ds_bpermute_b32 v143, v250, v135
	s_waitcnt lgkmcnt(0)
	v_and_or_b32 v142, v142, s2, v235
	v_and_or_b32 v143, v143, s2, v235
	global_load_dwordx4 v[32:35], v142, s[84:85]
	global_load_dwordx4 v[36:39], v143, s[84:85]
	ds_bpermute_b32 v142, v251, v135
	ds_bpermute_b32 v143, v252, v135
	s_waitcnt lgkmcnt(0)
	v_and_or_b32 v142, v142, s2, v235
	v_and_or_b32 v143, v143, s2, v235
	global_load_dwordx4 v[40:43], v142, s[84:85]
	global_load_dwordx4 v[44:47], v143, s[84:85]
	ds_bpermute_b32 v142, v253, v135
	ds_bpermute_b32 v143, v254, v135
	s_waitcnt lgkmcnt(0)
	v_and_or_b32 v142, v142, s2, v235
	v_and_or_b32 v143, v143, s2, v235
	global_load_dwordx4 v[48:51], v142, s[84:85]
	global_load_dwordx4 v[52:55], v143, s[84:85]
	ds_bpermute_b32 v142, v255, v135
	ds_bpermute_b32 v143, v153, v135
	s_waitcnt lgkmcnt(0)
	v_and_or_b32 v142, v142, s2, v235
	v_and_or_b32 v143, v143, s2, v235
	global_load_dwordx4 v[56:59], v142, s[84:85]
	global_load_dwordx4 v[60:63], v143, s[84:85]
	s_mov_b32 s92, 1
	v_lshl_add_u32 v116, s92, 9, v246
	ds_read_b32 v134, v116
	ds_read_b32 v135, v116 offset:256
	v_lshl_add_u32 v117, s98, 9, v247
	ds_read_b32 v136, v117
	ds_read_b32 v137, v117 offset:256
	s_waitcnt vmcnt(0)
.Lpg0_vloop:
	s_and_b32 s98, s100, 15
	s_lshr_b32 s99, s100, 4
	s_add_u32 s92, s100, 1
	s_min_u32 s92, s92, 127
	s_lshr_b32 s93, s92, 4
	s_and_b32 s92, s92, 15
	s_add_u32 vcc_lo, s3, s98
	s_lshl_b32 vcc_lo, vcc_lo, 12
	s_lshl_b32 vcc_hi, s99, 9
	s_add_u32 vcc_lo, vcc_lo, vcc_hi
	v_add_u32_e32 v119, vcc_lo, v238
	global_load_dword v80, v119, s[82:83]
	global_load_dword v81, v119, s[82:83] offset:32
	s_lshl_b32 vcc_lo, s93, 21
	s_add_u32 s84, s80, vcc_lo
	s_addc_u32 s85, s81, 0
	s_waitcnt lgkmcnt(0)
	ds_bpermute_b32 v138, v249, v136
	ds_bpermute_b32 v140, v250, v136
	ds_bpermute_b32 v142, v249, v134
	ds_bpermute_b32 v143, v250, v134
	ds_bpermute_b32 v144, v251, v136
	ds_bpermute_b32 v146, v252, v136
	s_waitcnt vmcnt(18) lgkmcnt(4)
	v_cvt_pk_f32_fp8_e32 v[104:105], v0
	v_cvt_pk_f32_fp8_e32 v[108:109], v4
	v_cvt_pk_f32_fp8_sdwa v[106:107], v0 src0_sel:WORD_1
	v_cvt_pk_f32_fp8_sdwa v[110:111], v4 src0_sel:WORD_1
	v_pk_mul_f32 v[64:65], v[104:105], v[138:139] op_sel_hi:[1,0]
	v_pk_mul_f32 v[66:67], v[106:107], v[138:139] op_sel_hi:[1,0]
	v_pk_fma_f32 v[64:65], v[108:109], v[140:141], v[64:65] op_sel_hi:[1,0,1]
	v_pk_fma_f32 v[66:67], v[110:111], v[140:141], v[66:67] op_sel_hi:[1,0,1]
	v_cvt_pk_f32_fp8_e32 v[104:105], v1
	v_cvt_pk_f32_fp8_e32 v[108:109], v5
	v_cvt_pk_f32_fp8_sdwa v[106:107], v1 src0_sel:WORD_1
	v_cvt_pk_f32_fp8_sdwa v[110:111], v5 src0_sel:WORD_1
	v_pk_mul_f32 v[68:69], v[104:105], v[138:139] op_sel_hi:[1,0]
	v_pk_mul_f32 v[70:71], v[106:107], v[138:139] op_sel_hi:[1,0]
	v_pk_fma_f32 v[68:69], v[108:109], v[140:141], v[68:69] op_sel_hi:[1,0,1]
	v_pk_fma_f32 v[70:71], v[110:111], v[140:141], v[70:71] op_sel_hi:[1,0,1]
	v_cvt_pk_f32_fp8_e32 v[104:105], v2
	v_cvt_pk_f32_fp8_e32 v[108:109], v6
	v_cvt_pk_f32_fp8_sdwa v[106:107], v2 src0_sel:WORD_1
	v_cvt_pk_f32_fp8_sdwa v[110:111], v6 src0_sel:WORD_1
	v_pk_mul_f32 v[72:73], v[104:105], v[138:139] op_sel_hi:[1,0]
	v_pk_mul_f32 v[74:75], v[106:107], v[138:139] op_sel_hi:[1,0]
	v_pk_fma_f32 v[72:73], v[108:109], v[140:141], v[72:73] op_sel_hi:[1,0,1]
	v_pk_fma_f32 v[74:75], v[110:111], v[140:141], v[74:75] op_sel_hi:[1,0,1]
	v_cvt_pk_f32_fp8_e32 v[104:105], v3
	v_cvt_pk_f32_fp8_e32 v[108:109], v7
	v_cvt_pk_f32_fp8_sdwa v[106:107], v3 src0_sel:WORD_1
	v_cvt_pk_f32_fp8_sdwa v[110:111], v7 src0_sel:WORD_1
	v_pk_mul_f32 v[76:77], v[104:105], v[138:139] op_sel_hi:[1,0]
	v_pk_mul_f32 v[78:79], v[106:107], v[138:139] op_sel_hi:[1,0]
	s_waitcnt lgkmcnt(0)
; #define PG_ISSUE(BUF, TAB, e0_) do { const int isrc_ = ((e0_) < 64) ? myi0 : myi1; \
;       _Pragma("unroll") for (int e = 0; e < 8; ++e) { const int idx_ = __builtin_amdgcn_readlane(isrc_, ((e0_) + e) & 63); \
;         BUF[e] = *(const u32x4*)((TAB) + (size_t)idx_ * 1024 + lane * 16); } } while (0)
; DEV void peer_gather(const Params& P, int l, int m0, const int* idxs, const float* gs) {
;     ...
;     for (int e0 = 0; e0 < 128; e0 += 16) {
;       PG_ISSUE(b1, V, e0 + 8);
;       if (e0 == 64 && i + 1 < 16) sort_lists(lane, ni0, ni1, ng0, ng1);
;       PG_V16(b0, e0);
;       if (e0 + 16 < 128) PG_ISSUE(b0, V, e0 + 16);
;       PG_V16(b1, e0 + 8);
	v_and_or_b32 v142, v142, s2, v235
	v_and_or_b32 v143, v143, s2, v235
	global_load_dwordx4 v[0:3], v142, s[84:85]
	global_load_dwordx4 v[4:7], v143, s[84:85]
	v_pk_fma_f32 v[76:77], v[108:109], v[140:141], v[76:77] op_sel_hi:[1,0,1]
	v_pk_fma_f32 v[78:79], v[110:111], v[140:141], v[78:79] op_sel_hi:[1,0,1]
	ds_bpermute_b32 v142, v251, v134
	ds_bpermute_b32 v143, v252, v134
	ds_bpermute_b32 v138, v253, v136
	ds_bpermute_b32 v140, v254, v136
	s_waitcnt vmcnt(18) lgkmcnt(4)
	v_cvt_pk_f32_fp8_e32 v[104:105], v8
	v_cvt_pk_f32_fp8_e32 v[108:109], v12
	v_cvt_pk_f32_fp8_sdwa v[106:107], v8 src0_sel:WORD_1
	v_cvt_pk_f32_fp8_sdwa v[110:111], v12 src0_sel:WORD_1
	v_pk_fma_f32 v[64:65], v[104:105], v[144:145], v[64:65] op_sel_hi:[1,0,1]
	v_pk_fma_f32 v[66:67], v[106:107], v[144:145], v[66:67] op_sel_hi:[1,0,1]
	v_pk_fma_f32 v[64:65], v[108:109], v[146:147], v[64:65] op_sel_hi:[1,0,1]
	v_pk_fma_f32 v[66:67], v[110:111], v[146:147], v[66:67] op_sel_hi:[1,0,1]
	v_cvt_pk_f32_fp8_e32 v[104:105], v9
	v_cvt_pk_f32_fp8_e32 v[108:109], v13
	v_cvt_pk_f32_fp8_sdwa v[106:107], v9 src0_sel:WORD_1
	v_cvt_pk_f32_fp8_sdwa v[110:111], v13 src0_sel:WORD_1
	v_pk_fma_f32 v[68:69], v[104:105], v[144:145], v[68:69] op_sel_hi:[1,0,1]
	v_pk_fma_f32 v[70:71], v[106:107], v[144:145], v[70:71] op_sel_hi:[1,0,1]
	v_pk_fma_f32 v[68:69], v[108:109], v[146:147], v[68:69] op_sel_hi:[1,0,1]
	v_pk_fma_f32 v[70:71], v[110:111], v[146:147], v[70:71] op_sel_hi:[1,0,1]
	v_cvt_pk_f32_fp8_e32 v[104:105], v10
	v_cvt_pk_f32_fp8_e32 v[108:109], v14
	v_cvt_pk_f32_fp8_sdwa v[106:107], v10 src0_sel:WORD_1
	v_cvt_pk_f32_fp8_sdwa v[110:111], v14 src0_sel:WORD_1
	v_pk_fma_f32 v[72:73], v[104:105], v[144:145], v[72:73] op_sel_hi:[1,0,1]
	v_pk_fma_f32 v[74:75], v[106:107], v[144:145], v[74:75] op_sel_hi:[1,0,1]
	v_pk_fma_f32 v[72:73], v[108:109], v[146:147], v[72:73] op_sel_hi:[1,0,1]
	v_pk_fma_f32 v[74:75], v[110:111], v[146:147], v[74:75] op_sel_hi:[1,0,1]
	v_cvt_pk_f32_fp8_e32 v[104:105], v11
	v_cvt_pk_f32_fp8_e32 v[108:109], v15
	v_cvt_pk_f32_fp8_sdwa v[106:107], v11 src0_sel:WORD_1
	v_cvt_pk_f32_fp8_sdwa v[110:111], v15 src0_sel:WORD_1
	v_pk_fma_f32 v[76:77], v[104:105], v[144:145], v[76:77] op_sel_hi:[1,0,1]
	v_pk_fma_f32 v[78:79], v[106:107], v[144:145], v[78:79] op_sel_hi:[1,0,1]
	s_waitcnt lgkmcnt(0)
	v_and_or_b32 v142, v142, s2, v235
	v_and_or_b32 v143, v143, s2, v235
	global_load_dwordx4 v[8:11], v142, s[84:85]
	global_load_dwordx4 v[12:15], v143, s[84:85]
	v_pk_fma_f32 v[76:77], v[108:109], v[146:147], v[76:77] op_sel_hi:[1,0,1]
	v_pk_fma_f32 v[78:79], v[110:111], v[146:147], v[78:79] op_sel_hi:[1,0,1]
	ds_bpermute_b32 v142, v253, v134
	ds_bpermute_b32 v143, v254, v134
	ds_bpermute_b32 v144, v255, v136
	ds_bpermute_b32 v146, v153, v136
	s_waitcnt vmcnt(18) lgkmcnt(4)
	v_cvt_pk_f32_fp8_e32 v[104:105], v16
	v_cvt_pk_f32_fp8_e32 v[108:109], v20
	v_cvt_pk_f32_fp8_sdwa v[106:107], v16 src0_sel:WORD_1
	v_cvt_pk_f32_fp8_sdwa v[110:111], v20 src0_sel:WORD_1
	v_pk_fma_f32 v[64:65], v[104:105], v[138:139], v[64:65] op_sel_hi:[1,0,1]
	v_pk_fma_f32 v[66:67], v[106:107], v[138:139], v[66:67] op_sel_hi:[1,0,1]
	v_pk_fma_f32 v[64:65], v[108:109], v[140:141], v[64:65] op_sel_hi:[1,0,1]
	v_pk_fma_f32 v[66:67], v[110:111], v[140:141], v[66:67] op_sel_hi:[1,0,1]
	v_cvt_pk_f32_fp8_e32 v[104:105], v17
	v_cvt_pk_f32_fp8_e32 v[108:109], v21
	v_cvt_pk_f32_fp8_sdwa v[106:107], v17 src0_sel:WORD_1
	v_cvt_pk_f32_fp8_sdwa v[110:111], v21 src0_sel:WORD_1
	v_pk_fma_f32 v[68:69], v[104:105], v[138:139], v[68:69] op_sel_hi:[1,0,1]
	v_pk_fma_f32 v[70:71], v[106:107], v[138:139], v[70:71] op_sel_hi:[1,0,1]
	v_pk_fma_f32 v[68:69], v[108:109], v[140:141], v[68:69] op_sel_hi:[1,0,1]
	v_pk_fma_f32 v[70:71], v[110:111], v[140:141], v[70:71] op_sel_hi:[1,0,1]
	v_cvt_pk_f32_fp8_e32 v[104:105], v18
	v_cvt_pk_f32_fp8_e32 v[108:109], v22
	v_cvt_pk_f32_fp8_sdwa v[106:107], v18 src0_sel:WORD_1
	v_cvt_pk_f32_fp8_sdwa v[110:111], v22 src0_sel:WORD_1
	v_pk_fma_f32 v[72:73], v[104:105], v[138:139], v[72:73] op_sel_hi:[1,0,1]
	v_pk_fma_f32 v[74:75], v[106:107], v[138:139], v[74:75] op_sel_hi:[1,0,1]
	v_pk_fma_f32 v[72:73], v[108:109], v[140:141], v[72:73] op_sel_hi:[1,0,1]
	v_pk_fma_f32 v[74:75], v[110:111], v[140:141], v[74:75] op_sel_hi:[1,0,1]
	v_cvt_pk_f32_fp8_e32 v[104:105], v19
	v_cvt_pk_f32_fp8_e32 v[108:109], v23
	v_cvt_pk_f32_fp8_sdwa v[106:107], v19 src0_sel:WORD_1
	v_cvt_pk_f32_fp8_sdwa v[110:111], v23 src0_sel:WORD_1
	v_pk_fma_f32 v[76:77], v[104:105], v[138:139], v[76:77] op_sel_hi:[1,0,1]
	v_pk_fma_f32 v[78:79], v[106:107], v[138:139], v[78:79] op_sel_hi:[1,0,1]
	s_waitcnt lgkmcnt(0)
	v_and_or_b32 v142, v142, s2, v235
	v_and_or_b32 v143, v143, s2, v235
	global_load_dwordx4 v[16:19], v142, s[84:85]
	global_load_dwordx4 v[20:23], v143, s[84:85]
	v_pk_fma_f32 v[76:77], v[108:109], v[140:141], v[76:77] op_sel_hi:[1,0,1]
	v_pk_fma_f32 v[78:79], v[110:111], v[140:141], v[78:79] op_sel_hi:[1,0,1]
	ds_bpermute_b32 v142, v255, v134
	ds_bpermute_b32 v143, v153, v134
	ds_bpermute_b32 v138, v249, v137
	ds_bpermute_b32 v140, v250, v137
	s_waitcnt vmcnt(18) lgkmcnt(4)
; #define PG_ISSUE(BUF, TAB, e0_) do { const int isrc_ = ((e0_) < 64) ? myi0 : myi1; \
;       _Pragma("unroll") for (int e = 0; e < 8; ++e) { const int idx_ = __builtin_amdgcn_readlane(isrc_, ((e0_) + e) & 63); \
;         BUF[e] = *(const u32x4*)((TAB) + (size_t)idx_ * 1024 + lane * 16); } } while (0)
; DEV void peer_gather(const Params& P, int l, int m0, const int* idxs, const float* gs) {
;     ...
;     for (int e0 = 0; e0 < 128; e0 += 16) {
;       PG_ISSUE(b1, V, e0 + 8);
;       if (e0 == 64 && i + 1 < 16) sort_lists(lane, ni0, ni1, ng0, ng1);
;       PG_V16(b0, e0);
;       if (e0 + 16 < 128) PG_ISSUE(b0, V, e0 + 16);
;       PG_V16(b1, e0 + 8);
	v_cvt_pk_f32_fp8_e32 v[104:105], v24
	v_cvt_pk_f32_fp8_e32 v[108:109], v28
	v_cvt_pk_f32_fp8_sdwa v[106:107], v24 src0_sel:WORD_1
	v_cvt_pk_f32_fp8_sdwa v[110:111], v28 src0_sel:WORD_1
	v_pk_fma_f32 v[64:65], v[104:105], v[144:145], v[64:65] op_sel_hi:[1,0,1]
	v_pk_fma_f32 v[66:67], v[106:107], v[144:145], v[66:67] op_sel_hi:[1,0,1]
	v_pk_fma_f32 v[64:65], v[108:109], v[146:147], v[64:65] op_sel_hi:[1,0,1]
	v_pk_fma_f32 v[66:67], v[110:111], v[146:147], v[66:67] op_sel_hi:[1,0,1]
	v_cvt_pk_f32_fp8_e32 v[104:105], v25
	v_cvt_pk_f32_fp8_e32 v[108:109], v29
	v_cvt_pk_f32_fp8_sdwa v[106:107], v25 src0_sel:WORD_1
	v_cvt_pk_f32_fp8_sdwa v[110:111], v29 src0_sel:WORD_1
	v_pk_fma_f32 v[68:69], v[104:105], v[144:145], v[68:69] op_sel_hi:[1,0,1]
	v_pk_fma_f32 v[70:71], v[106:107], v[144:145], v[70:71] op_sel_hi:[1,0,1]
	v_pk_fma_f32 v[68:69], v[108:109], v[146:147], v[68:69] op_sel_hi:[1,0,1]
	v_pk_fma_f32 v[70:71], v[110:111], v[146:147], v[70:71] op_sel_hi:[1,0,1]
	v_cvt_pk_f32_fp8_e32 v[104:105], v26
	v_cvt_pk_f32_fp8_e32 v[108:109], v30
	v_cvt_pk_f32_fp8_sdwa v[106:107], v26 src0_sel:WORD_1
	v_cvt_pk_f32_fp8_sdwa v[110:111], v30 src0_sel:WORD_1
	v_pk_fma_f32 v[72:73], v[104:105], v[144:145], v[72:73] op_sel_hi:[1,0,1]
	v_pk_fma_f32 v[74:75], v[106:107], v[144:145], v[74:75] op_sel_hi:[1,0,1]
	v_pk_fma_f32 v[72:73], v[108:109], v[146:147], v[72:73] op_sel_hi:[1,0,1]
	v_pk_fma_f32 v[74:75], v[110:111], v[146:147], v[74:75] op_sel_hi:[1,0,1]
	v_cvt_pk_f32_fp8_e32 v[104:105], v27
	v_cvt_pk_f32_fp8_e32 v[108:109], v31
	v_cvt_pk_f32_fp8_sdwa v[106:107], v27 src0_sel:WORD_1
	v_cvt_pk_f32_fp8_sdwa v[110:111], v31 src0_sel:WORD_1
	v_pk_fma_f32 v[76:77], v[104:105], v[144:145], v[76:77] op_sel_hi:[1,0,1]
	v_pk_fma_f32 v[78:79], v[106:107], v[144:145], v[78:79] op_sel_hi:[1,0,1]
	s_waitcnt lgkmcnt(0)
	v_and_or_b32 v142, v142, s2, v235
	v_and_or_b32 v143, v143, s2, v235
	global_load_dwordx4 v[24:27], v142, s[84:85]
	global_load_dwordx4 v[28:31], v143, s[84:85]
	v_pk_fma_f32 v[76:77], v[108:109], v[146:147], v[76:77] op_sel_hi:[1,0,1]
	v_pk_fma_f32 v[78:79], v[110:111], v[146:147], v[78:79] op_sel_hi:[1,0,1]
	ds_bpermute_b32 v142, v249, v135
	ds_bpermute_b32 v143, v250, v135
	ds_bpermute_b32 v144, v251, v137
	ds_bpermute_b32 v146, v252, v137
	s_waitcnt vmcnt(18) lgkmcnt(4)
	v_cvt_pk_f32_fp8_e32 v[104:105], v32
	v_cvt_pk_f32_fp8_e32 v[108:109], v36
	v_cvt_pk_f32_fp8_sdwa v[106:107], v32 src0_sel:WORD_1
	v_cvt_pk_f32_fp8_sdwa v[110:111], v36 src0_sel:WORD_1
	v_pk_fma_f32 v[64:65], v[104:105], v[138:139], v[64:65] op_sel_hi:[1,0,1]
	v_pk_fma_f32 v[66:67], v[106:107], v[138:139], v[66:67] op_sel_hi:[1,0,1]
	v_pk_fma_f32 v[64:65], v[108:109], v[140:141], v[64:65] op_sel_hi:[1,0,1]
	v_pk_fma_f32 v[66:67], v[110:111], v[140:141], v[66:67] op_sel_hi:[1,0,1]
	v_cvt_pk_f32_fp8_e32 v[104:105], v33
	v_cvt_pk_f32_fp8_e32 v[108:109], v37
	v_cvt_pk_f32_fp8_sdwa v[106:107], v33 src0_sel:WORD_1
	v_cvt_pk_f32_fp8_sdwa v[110:111], v37 src0_sel:WORD_1
	v_pk_fma_f32 v[68:69], v[104:105], v[138:139], v[68:69] op_sel_hi:[1,0,1]
	v_pk_fma_f32 v[70:71], v[106:107], v[138:139], v[70:71] op_sel_hi:[1,0,1]
	v_pk_fma_f32 v[68:69], v[108:109], v[140:141], v[68:69] op_sel_hi:[1,0,1]
	v_pk_fma_f32 v[70:71], v[110:111], v[140:141], v[70:71] op_sel_hi:[1,0,1]
	v_cvt_pk_f32_fp8_e32 v[104:105], v34
	v_cvt_pk_f32_fp8_e32 v[108:109], v38
	v_cvt_pk_f32_fp8_sdwa v[106:107], v34 src0_sel:WORD_1
	v_cvt_pk_f32_fp8_sdwa v[110:111], v38 src0_sel:WORD_1
	v_pk_fma_f32 v[72:73], v[104:105], v[138:139], v[72:73] op_sel_hi:[1,0,1]
	v_pk_fma_f32 v[74:75], v[106:107], v[138:139], v[74:75] op_sel_hi:[1,0,1]
	v_pk_fma_f32 v[72:73], v[108:109], v[140:141], v[72:73] op_sel_hi:[1,0,1]
	v_pk_fma_f32 v[74:75], v[110:111], v[140:141], v[74:75] op_sel_hi:[1,0,1]
	v_cvt_pk_f32_fp8_e32 v[104:105], v35
	v_cvt_pk_f32_fp8_e32 v[108:109], v39
	v_cvt_pk_f32_fp8_sdwa v[106:107], v35 src0_sel:WORD_1
	v_cvt_pk_f32_fp8_sdwa v[110:111], v39 src0_sel:WORD_1
	v_pk_fma_f32 v[76:77], v[104:105], v[138:139], v[76:77] op_sel_hi:[1,0,1]
	v_pk_fma_f32 v[78:79], v[106:107], v[138:139], v[78:79] op_sel_hi:[1,0,1]
	s_waitcnt lgkmcnt(0)
	v_and_or_b32 v142, v142, s2, v235
	v_and_or_b32 v143, v143, s2, v235
	global_load_dwordx4 v[32:35], v142, s[84:85]
	global_load_dwordx4 v[36:39], v143, s[84:85]
	v_pk_fma_f32 v[76:77], v[108:109], v[140:141], v[76:77] op_sel_hi:[1,0,1]
	v_pk_fma_f32 v[78:79], v[110:111], v[140:141], v[78:79] op_sel_hi:[1,0,1]
	ds_bpermute_b32 v142, v251, v135
	ds_bpermute_b32 v143, v252, v135
	ds_bpermute_b32 v138, v253, v137
	ds_bpermute_b32 v140, v254, v137
	s_waitcnt vmcnt(18) lgkmcnt(4)
	v_cvt_pk_f32_fp8_e32 v[104:105], v40
	v_cvt_pk_f32_fp8_e32 v[108:109], v44
	v_cvt_pk_f32_fp8_sdwa v[106:107], v40 src0_sel:WORD_1
	v_cvt_pk_f32_fp8_sdwa v[110:111], v44 src0_sel:WORD_1
	v_pk_fma_f32 v[64:65], v[104:105], v[144:145], v[64:65] op_sel_hi:[1,0,1]
	v_pk_fma_f32 v[66:67], v[106:107], v[144:145], v[66:67] op_sel_hi:[1,0,1]
	v_pk_fma_f32 v[64:65], v[108:109], v[146:147], v[64:65] op_sel_hi:[1,0,1]
	v_pk_fma_f32 v[66:67], v[110:111], v[146:147], v[66:67] op_sel_hi:[1,0,1]
	v_cvt_pk_f32_fp8_e32 v[104:105], v41
	v_cvt_pk_f32_fp8_e32 v[108:109], v45
	v_cvt_pk_f32_fp8_sdwa v[106:107], v41 src0_sel:WORD_1
	v_cvt_pk_f32_fp8_sdwa v[110:111], v45 src0_sel:WORD_1
	v_pk_fma_f32 v[68:69], v[104:105], v[144:145], v[68:69] op_sel_hi:[1,0,1]
	v_pk_fma_f32 v[70:71], v[106:107], v[144:145], v[70:71] op_sel_hi:[1,0,1]
	v_pk_fma_f32 v[68:69], v[108:109], v[146:147], v[68:69] op_sel_hi:[1,0,1]
	v_pk_fma_f32 v[70:71], v[110:111], v[146:147], v[70:71] op_sel_hi:[1,0,1]
	v_cvt_pk_f32_fp8_e32 v[104:105], v42
	v_cvt_pk_f32_fp8_e32 v[108:109], v46
	v_cvt_pk_f32_fp8_sdwa v[106:107], v42 src0_sel:WORD_1
	v_cvt_pk_f32_fp8_sdwa v[110:111], v46 src0_sel:WORD_1
	v_pk_fma_f32 v[72:73], v[104:105], v[144:145], v[72:73] op_sel_hi:[1,0,1]
	v_pk_fma_f32 v[74:75], v[106:107], v[144:145], v[74:75] op_sel_hi:[1,0,1]
	v_pk_fma_f32 v[72:73], v[108:109], v[146:147], v[72:73] op_sel_hi:[1,0,1]
	v_pk_fma_f32 v[74:75], v[110:111], v[146:147], v[74:75] op_sel_hi:[1,0,1]
	v_cvt_pk_f32_fp8_e32 v[104:105], v43
	v_cvt_pk_f32_fp8_e32 v[108:109], v47
	v_cvt_pk_f32_fp8_sdwa v[106:107], v43 src0_sel:WORD_1
	v_cvt_pk_f32_fp8_sdwa v[110:111], v47 src0_sel:WORD_1
	v_pk_fma_f32 v[76:77], v[104:105], v[144:145], v[76:77] op_sel_hi:[1,0,1]
	v_pk_fma_f32 v[78:79], v[106:107], v[144:145], v[78:79] op_sel_hi:[1,0,1]
	s_waitcnt lgkmcnt(0)
; DEV void peer_gather(const Params& P, int l, int m0, const int* idxs, const float* gs) {
;     ...
;     for (int q = 0; q < 4; ++q) {
;       hv[q][0] += acc[2 * q][0] * TAB_INV; hv[q][1] += acc[2 * q][1] * TAB_INV; hv[q][2] += acc[2 * q + 1][0] * TAB_INV; hv[q][3] += acc[2 * q + 1][1] * TAB_INV;
;       ss += hv[q][0] * hv[q][0] + hv[q][1] * hv[q][1] + hv[q][2] * hv[q][2] + hv[q][3] * hv[q][3];
;       *(f32x4*)(hrow + 4 * q) = hv[q];
	v_and_or_b32 v142, v142, s2, v235
	v_and_or_b32 v143, v143, s2, v235
	global_load_dwordx4 v[40:43], v142, s[84:85]
	global_load_dwordx4 v[44:47], v143, s[84:85]
	v_pk_fma_f32 v[76:77], v[108:109], v[146:147], v[76:77] op_sel_hi:[1,0,1]
	v_pk_fma_f32 v[78:79], v[110:111], v[146:147], v[78:79] op_sel_hi:[1,0,1]
	ds_bpermute_b32 v142, v253, v135
	ds_bpermute_b32 v143, v254, v135
	ds_bpermute_b32 v144, v255, v137
	ds_bpermute_b32 v146, v153, v137
	s_waitcnt vmcnt(18) lgkmcnt(4)
	v_cvt_pk_f32_fp8_e32 v[104:105], v48
	v_cvt_pk_f32_fp8_e32 v[108:109], v52
	v_cvt_pk_f32_fp8_sdwa v[106:107], v48 src0_sel:WORD_1
	v_cvt_pk_f32_fp8_sdwa v[110:111], v52 src0_sel:WORD_1
	v_pk_fma_f32 v[64:65], v[104:105], v[138:139], v[64:65] op_sel_hi:[1,0,1]
	v_pk_fma_f32 v[66:67], v[106:107], v[138:139], v[66:67] op_sel_hi:[1,0,1]
	v_pk_fma_f32 v[64:65], v[108:109], v[140:141], v[64:65] op_sel_hi:[1,0,1]
	v_pk_fma_f32 v[66:67], v[110:111], v[140:141], v[66:67] op_sel_hi:[1,0,1]
	v_cvt_pk_f32_fp8_e32 v[104:105], v49
	v_cvt_pk_f32_fp8_e32 v[108:109], v53
	v_cvt_pk_f32_fp8_sdwa v[106:107], v49 src0_sel:WORD_1
	v_cvt_pk_f32_fp8_sdwa v[110:111], v53 src0_sel:WORD_1
	v_pk_fma_f32 v[68:69], v[104:105], v[138:139], v[68:69] op_sel_hi:[1,0,1]
	v_pk_fma_f32 v[70:71], v[106:107], v[138:139], v[70:71] op_sel_hi:[1,0,1]
	v_pk_fma_f32 v[68:69], v[108:109], v[140:141], v[68:69] op_sel_hi:[1,0,1]
	v_pk_fma_f32 v[70:71], v[110:111], v[140:141], v[70:71] op_sel_hi:[1,0,1]
	v_cvt_pk_f32_fp8_e32 v[104:105], v50
	v_cvt_pk_f32_fp8_e32 v[108:109], v54
	v_cvt_pk_f32_fp8_sdwa v[106:107], v50 src0_sel:WORD_1
	v_cvt_pk_f32_fp8_sdwa v[110:111], v54 src0_sel:WORD_1
	v_pk_fma_f32 v[72:73], v[104:105], v[138:139], v[72:73] op_sel_hi:[1,0,1]
	v_pk_fma_f32 v[74:75], v[106:107], v[138:139], v[74:75] op_sel_hi:[1,0,1]
	v_pk_fma_f32 v[72:73], v[108:109], v[140:141], v[72:73] op_sel_hi:[1,0,1]
	v_pk_fma_f32 v[74:75], v[110:111], v[140:141], v[74:75] op_sel_hi:[1,0,1]
	v_cvt_pk_f32_fp8_e32 v[104:105], v51
	v_cvt_pk_f32_fp8_e32 v[108:109], v55
	v_cvt_pk_f32_fp8_sdwa v[106:107], v51 src0_sel:WORD_1
	v_cvt_pk_f32_fp8_sdwa v[110:111], v55 src0_sel:WORD_1
	v_pk_fma_f32 v[76:77], v[104:105], v[138:139], v[76:77] op_sel_hi:[1,0,1]
	v_pk_fma_f32 v[78:79], v[106:107], v[138:139], v[78:79] op_sel_hi:[1,0,1]
	s_waitcnt lgkmcnt(0)
	v_and_or_b32 v142, v142, s2, v235
	v_and_or_b32 v143, v143, s2, v235
	global_load_dwordx4 v[48:51], v142, s[84:85]
	global_load_dwordx4 v[52:55], v143, s[84:85]
	v_pk_fma_f32 v[76:77], v[108:109], v[140:141], v[76:77] op_sel_hi:[1,0,1]
	v_pk_fma_f32 v[78:79], v[110:111], v[140:141], v[78:79] op_sel_hi:[1,0,1]
	ds_bpermute_b32 v142, v255, v135
	ds_bpermute_b32 v143, v153, v135
	s_waitcnt vmcnt(18) lgkmcnt(2)
	v_cvt_pk_f32_fp8_e32 v[104:105], v56
	v_cvt_pk_f32_fp8_e32 v[108:109], v60
	v_cvt_pk_f32_fp8_sdwa v[106:107], v56 src0_sel:WORD_1
	v_cvt_pk_f32_fp8_sdwa v[110:111], v60 src0_sel:WORD_1
	v_pk_fma_f32 v[64:65], v[104:105], v[144:145], v[64:65] op_sel_hi:[1,0,1]
	v_pk_fma_f32 v[66:67], v[106:107], v[144:145], v[66:67] op_sel_hi:[1,0,1]
	v_pk_fma_f32 v[64:65], v[108:109], v[146:147], v[64:65] op_sel_hi:[1,0,1]
	v_pk_fma_f32 v[66:67], v[110:111], v[146:147], v[66:67] op_sel_hi:[1,0,1]
	v_cvt_pk_f32_fp8_e32 v[104:105], v57
	v_cvt_pk_f32_fp8_e32 v[108:109], v61
	v_cvt_pk_f32_fp8_sdwa v[106:107], v57 src0_sel:WORD_1
	v_cvt_pk_f32_fp8_sdwa v[110:111], v61 src0_sel:WORD_1
	v_pk_fma_f32 v[68:69], v[104:105], v[144:145], v[68:69] op_sel_hi:[1,0,1]
	v_pk_fma_f32 v[70:71], v[106:107], v[144:145], v[70:71] op_sel_hi:[1,0,1]
	v_pk_fma_f32 v[68:69], v[108:109], v[146:147], v[68:69] op_sel_hi:[1,0,1]
	v_pk_fma_f32 v[70:71], v[110:111], v[146:147], v[70:71] op_sel_hi:[1,0,1]
	v_cvt_pk_f32_fp8_e32 v[104:105], v58
	v_cvt_pk_f32_fp8_e32 v[108:109], v62
	v_cvt_pk_f32_fp8_sdwa v[106:107], v58 src0_sel:WORD_1
	v_cvt_pk_f32_fp8_sdwa v[110:111], v62 src0_sel:WORD_1
	v_pk_fma_f32 v[72:73], v[104:105], v[144:145], v[72:73] op_sel_hi:[1,0,1]
	v_pk_fma_f32 v[74:75], v[106:107], v[144:145], v[74:75] op_sel_hi:[1,0,1]
	v_pk_fma_f32 v[72:73], v[108:109], v[146:147], v[72:73] op_sel_hi:[1,0,1]
	v_pk_fma_f32 v[74:75], v[110:111], v[146:147], v[74:75] op_sel_hi:[1,0,1]
	v_cvt_pk_f32_fp8_e32 v[104:105], v59
	v_cvt_pk_f32_fp8_e32 v[108:109], v63
	v_cvt_pk_f32_fp8_sdwa v[106:107], v59 src0_sel:WORD_1
	v_cvt_pk_f32_fp8_sdwa v[110:111], v63 src0_sel:WORD_1
	v_pk_fma_f32 v[76:77], v[104:105], v[144:145], v[76:77] op_sel_hi:[1,0,1]
	v_pk_fma_f32 v[78:79], v[106:107], v[144:145], v[78:79] op_sel_hi:[1,0,1]
	s_waitcnt lgkmcnt(0)
	v_and_or_b32 v142, v142, s2, v235
	v_and_or_b32 v143, v143, s2, v235
	global_load_dwordx4 v[56:59], v142, s[84:85]
	global_load_dwordx4 v[60:63], v143, s[84:85]
	v_pk_fma_f32 v[76:77], v[108:109], v[146:147], v[76:77] op_sel_hi:[1,0,1]
	v_pk_fma_f32 v[78:79], v[110:111], v[146:147], v[78:79] op_sel_hi:[1,0,1]
	s_add_u32 s92, s100, 2
	s_and_b32 s92, s92, 15
	v_lshl_add_u32 v116, s92, 9, v246
	ds_read_b32 v134, v116
	ds_read_b32 v135, v116 offset:256
	s_add_u32 s92, s100, 1
	s_and_b32 s92, s92, 15
	v_lshl_add_u32 v117, s92, 9, v247
	ds_read_b32 v136, v117
	ds_read_b32 v137, v117 offset:256
	s_nop 1
	v_permlane32_swap_b32_e32 v64, v65
	v_permlane32_swap_b32_e32 v66, v67
	v_permlane32_swap_b32_e32 v68, v69
	v_permlane32_swap_b32_e32 v70, v71
	v_permlane32_swap_b32_e32 v72, v73
	v_permlane32_swap_b32_e32 v74, v75
	v_permlane32_swap_b32_e32 v76, v77
	v_permlane32_swap_b32_e32 v78, v79
	v_add_f32_e32 v64, v64, v65
	v_add_f32_e32 v66, v66, v67
	v_add_f32_e32 v68, v68, v69
	v_add_f32_e32 v70, v70, v71
	v_add_f32_e32 v72, v72, v73
	v_add_f32_e32 v74, v74, v75
	v_add_f32_e32 v76, v76, v77
	v_add_f32_e32 v78, v78, v79
	s_nop 1
	v_permlane16_swap_b32_e32 v64, v66
	v_permlane16_swap_b32_e32 v68, v70
	v_permlane16_swap_b32_e32 v72, v74
	v_permlane16_swap_b32_e32 v76, v78
	v_add_f32_e32 v64, v64, v66
	v_add_f32_e32 v68, v68, v70
	v_add_f32_e32 v72, v72, v74
	v_add_f32_e32 v76, v76, v78
	s_mov_b32 s88, 0xff00ff00
	s_mov_b32 s89, 0xff00ff00
	s_nop 0
	v_cndmask_b32_e64 v65, v64, v68, s[88:89]
	v_cndmask_b32_e64 v66, v68, v64, s[88:89]
	v_cndmask_b32_e64 v73, v72, v76, s[88:89]
	v_cndmask_b32_e64 v74, v76, v72, s[88:89]
	s_nop 1
	v_add_f32_dpp v64, v66, v65 row_ror:8 row_mask:0xf bank_mask:0xf
	v_add_f32_dpp v72, v74, v73 row_ror:8 row_mask:0xf bank_mask:0xf
	s_waitcnt vmcnt(16)
	v_fmac_f32_e32 v80, 0x3c800000, v64
	v_fmac_f32_e32 v81, 0x3c800000, v72
	global_store_dword v119, v80, s[82:83]
	global_store_dword v119, v81, s[82:83] offset:32
	s_add_u32 s100, s100, 1
	s_cmp_lt_u32 s100, 128
	s_cbranch_scc1 .Lpg0_vloop
	s_waitcnt vmcnt(0) lgkmcnt(0)
	v_readfirstlane_b32 s88, v130
	v_readfirstlane_b32 s89, v131
	s_nop 4
	v_lshlrev_b32_e32 v117, 6, v233
	global_load_dwordx4 v[16:19], v117, s[88:89] offset:0
	global_load_dwordx4 v[20:23], v117, s[88:89] offset:16
	global_load_dwordx4 v[24:27], v117, s[88:89] offset:32
	global_load_dwordx4 v[28:31], v117, s[88:89] offset:48
	s_mov_b32 s2, 0

; DEV void sort_lists(int lane, int& myi0, int& myi1, float& myg0, float& myg1) {
; #pragma unroll
;     for (int k = 2; k <= 128; k <<= 1) {
; #pragma unroll
;       for (int j = k >> 1; j >= 1; j >>= 1) {
;         if (j == 64) {
;           const bool sw_ = myi1 < myi0;
;           const int ti = sw_ ? myi1 : myi0, tj = sw_ ? myi0 : myi1; const float tg = sw_ ? myg1 : myg0, th = sw_ ? myg0 : myg1;
;           myi0 = ti; myi1 = tj; myg0 = tg; myg1 = th;
;         } else {
;           const bool lower = (lane & j) == 0;
;           {
;             const bool up = (k == 128) ? true : ((k == 64) ? true : ((lane & k) == 0));
;             const int oi = __shfl_xor(myi0, j); const float og = __shfl_xor(myg0, j);
;             const bool take = (lower == up) ? (oi < myi0) : (oi > myi0);
;             myi0 = take ? oi : myi0; myg0 = take ? og : myg0;
;           }
;           {
;             const bool up = (k == 128) ? true : ((k == 64) ? false : ((lane & k) == 0));
;             const int oi = __shfl_xor(myi1, j); const float og = __shfl_xor(myg1, j);
;             const bool take = (lower == up) ? (oi < myi1) : (oi > myi1);
;             myi1 = take ? oi : myi1; myg1 = take ? og : myg1;
;           }
;         }
;       }
;     }
; }
; DEV void peer_gather(const Params& P, int l, int m0, const int* idxs, const float* gs) {
;     ...
;   int ni0 = idxs[(wid * 16) * 128 + lane], ni1 = idxs[(wid * 16) * 128 + 64 + lane];
;   float ng0 = gs[(wid * 16) * 128 + lane], ng1 = gs[(wid * 16) * 128 + 64 + lane];
.Lpg1_p0:
	v_readlane_b32 s82, v231, 13
	v_readlane_b32 s83, v231, 14
	s_nop 4
	s_lshl_b32 s98, s2, 2
	s_add_u32 s98, s98, s33
	s_add_u32 s98, s98, 0
	s_lshl_b32 s98, s98, 9
	v_add_u32_e32 v116, s98, v234
	global_load_dword v241, v116, s[82:83]
	global_load_dword v242, v116, s[82:83] offset:256
	s_lshl_b32 s98, s2, 2
	s_add_u32 s98, s98, s33
	s_add_u32 s98, s98, 1
	s_lshl_b32 s98, s98, 9
	v_add_u32_e32 v117, s98, v234
	global_load_dword v243, v117, s[82:83]
	global_load_dword v244, v117, s[82:83] offset:256
	s_lshl_b32 s98, s2, 2
	s_add_u32 s98, s98, s33
	s_add_u32 s98, s98, 2
	s_lshl_b32 s98, s98, 9
	v_add_u32_e32 v118, s98, v234
	global_load_dword v245, v118, s[82:83]
	global_load_dword v246, v118, s[82:83] offset:256
	s_lshl_b32 s98, s2, 2
	s_add_u32 s98, s98, s33
	s_add_u32 s98, s98, 3
	s_lshl_b32 s98, s98, 9
	v_add_u32_e32 v119, s98, v234
	global_load_dword v247, v119, s[82:83]
	global_load_dword v248, v119, s[82:83] offset:256
	s_waitcnt vmcnt(0)
	v_or_b32_e32 v116, 64, v233
	v_lshl_or_b32 v241, v241, 7, v233
	v_lshl_or_b32 v242, v242, 7, v116
	v_lshl_or_b32 v243, v243, 7, v233
	v_lshl_or_b32 v244, v244, 7, v116
	v_lshl_or_b32 v245, v245, 7, v233
	v_lshl_or_b32 v246, v246, 7, v116
	v_lshl_or_b32 v247, v247, 7, v233
	v_lshl_or_b32 v248, v248, 7, v116
	v_xor_b32_e32 v116, 4, v234
	ds_bpermute_b32 v0, v116, v241
	ds_bpermute_b32 v1, v116, v243
	ds_bpermute_b32 v2, v116, v245
	ds_bpermute_b32 v3, v116, v247
	ds_bpermute_b32 v4, v116, v242
	ds_bpermute_b32 v5, v116, v244
	ds_bpermute_b32 v6, v116, v246
	ds_bpermute_b32 v7, v116, v248
	s_waitcnt lgkmcnt(0)
	s_mov_b32 s88, 0x99999999
	s_mov_b32 s89, 0x99999999
	v_min_u32_e32 v104, v241, v0
	v_max_u32_e32 v105, v241, v0
	v_cndmask_b32_e64 v241, v105, v104, s[88:89]
	v_min_u32_e32 v106, v243, v1
	v_max_u32_e32 v107, v243, v1
	v_cndmask_b32_e64 v243, v107, v106, s[88:89]
	v_min_u32_e32 v104, v245, v2
	v_max_u32_e32 v105, v245, v2
	v_cndmask_b32_e64 v245, v105, v104, s[88:89]
	v_min_u32_e32 v106, v247, v3
	v_max_u32_e32 v107, v247, v3
	v_cndmask_b32_e64 v247, v107, v106, s[88:89]
	v_min_u32_e32 v104, v242, v4
	v_max_u32_e32 v105, v242, v4
	v_cndmask_b32_e64 v242, v105, v104, s[88:89]
	v_min_u32_e32 v106, v244, v5
	v_max_u32_e32 v107, v244, v5
	v_cndmask_b32_e64 v244, v107, v106, s[88:89]
	v_min_u32_e32 v104, v246, v6
	v_max_u32_e32 v105, v246, v6
	v_cndmask_b32_e64 v246, v105, v104, s[88:89]
	v_min_u32_e32 v106, v248, v7
	v_max_u32_e32 v107, v248, v7
	v_cndmask_b32_e64 v248, v107, v106, s[88:89]
	v_xor_b32_e32 v116, 8, v234
	ds_bpermute_b32 v0, v116, v241
	ds_bpermute_b32 v1, v116, v243
	ds_bpermute_b32 v2, v116, v245
	ds_bpermute_b32 v3, v116, v247
	ds_bpermute_b32 v4, v116, v242
	ds_bpermute_b32 v5, v116, v244
	ds_bpermute_b32 v6, v116, v246
	ds_bpermute_b32 v7, v116, v248
	s_waitcnt lgkmcnt(0)
	s_mov_b32 s88, 0xc3c3c3c3
	s_mov_b32 s89, 0xc3c3c3c3
	v_min_u32_e32 v104, v241, v0
	v_max_u32_e32 v105, v241, v0
	v_cndmask_b32_e64 v241, v105, v104, s[88:89]
	v_min_u32_e32 v106, v243, v1
	v_max_u32_e32 v107, v243, v1
	v_cndmask_b32_e64 v243, v107, v106, s[88:89]
	v_min_u32_e32 v104, v245, v2
	v_max_u32_e32 v105, v245, v2
	v_cndmask_b32_e64 v245, v105, v104, s[88:89]
	v_min_u32_e32 v106, v247, v3
	v_max_u32_e32 v107, v247, v3
	v_cndmask_b32_e64 v247, v107, v106, s[88:89]
	v_min_u32_e32 v104, v242, v4
	v_max_u32_e32 v105, v242, v4
	v_cndmask_b32_e64 v242, v105, v104, s[88:89]
	v_min_u32_e32 v106, v244, v5
	v_max_u32_e32 v107, v244, v5
	v_cndmask_b32_e64 v244, v107, v106, s[88:89]
	v_min_u32_e32 v104, v246, v6
	v_max_u32_e32 v105, v246, v6
	v_cndmask_b32_e64 v246, v105, v104, s[88:89]
	v_min_u32_e32 v106, v248, v7
	v_max_u32_e32 v107, v248, v7
	v_cndmask_b32_e64 v248, v107, v106, s[88:89]
	v_xor_b32_e32 v116, 4, v234
	ds_bpermute_b32 v0, v116, v241
	ds_bpermute_b32 v1, v116, v243
	ds_bpermute_b32 v2, v116, v245
	ds_bpermute_b32 v3, v116, v247
	ds_bpermute_b32 v4, v116, v242
	ds_bpermute_b32 v5, v116, v244
	ds_bpermute_b32 v6, v116, v246
	ds_bpermute_b32 v7, v116, v248
	s_waitcnt lgkmcnt(0)
	s_mov_b32 s88, 0xa5a5a5a5
	s_mov_b32 s89, 0xa5a5a5a5
	v_min_u32_e32 v104, v241, v0
	v_max_u32_e32 v105, v241, v0
	v_cndmask_b32_e64 v241, v105, v104, s[88:89]
	v_min_u32_e32 v106, v243, v1
	v_max_u32_e32 v107, v243, v1
	v_cndmask_b32_e64 v243, v107, v106, s[88:89]
	v_min_u32_e32 v104, v245, v2
	v_max_u32_e32 v105, v245, v2
	v_cndmask_b32_e64 v245, v105, v104, s[88:89]
	v_min_u32_e32 v106, v247, v3
	v_max_u32_e32 v107, v247, v3
	v_cndmask_b32_e64 v247, v107, v106, s[88:89]
	v_min_u32_e32 v104, v242, v4
	v_max_u32_e32 v105, v242, v4
	v_cndmask_b32_e64 v242, v105, v104, s[88:89]
	v_min_u32_e32 v106, v244, v5
	v_max_u32_e32 v107, v244, v5
	v_cndmask_b32_e64 v244, v107, v106, s[88:89]
	v_min_u32_e32 v104, v246, v6
	v_max_u32_e32 v105, v246, v6
	v_cndmask_b32_e64 v246, v105, v104, s[88:89]
	v_min_u32_e32 v106, v248, v7
	v_max_u32_e32 v107, v248, v7
	v_cndmask_b32_e64 v248, v107, v106, s[88:89]
	v_xor_b32_e32 v116, 16, v234
	ds_bpermute_b32 v0, v116, v241
	ds_bpermute_b32 v1, v116, v243
	ds_bpermute_b32 v2, v116, v245
	ds_bpermute_b32 v3, v116, v247
	ds_bpermute_b32 v4, v116, v242
	ds_bpermute_b32 v5, v116, v244
	ds_bpermute_b32 v6, v116, v246
	ds_bpermute_b32 v7, v116, v248
	s_waitcnt lgkmcnt(0)
; DEV void sort_lists(int lane, int& myi0, int& myi1, float& myg0, float& myg1) {
; #pragma unroll
;     for (int k = 2; k <= 128; k <<= 1) {
; #pragma unroll
;       for (int j = k >> 1; j >= 1; j >>= 1) {
;         if (j == 64) {
;           const bool sw_ = myi1 < myi0;
;           const int ti = sw_ ? myi1 : myi0, tj = sw_ ? myi0 : myi1; const float tg = sw_ ? myg1 : myg0, th = sw_ ? myg0 : myg1;
;           myi0 = ti; myi1 = tj; myg0 = tg; myg1 = th;
;         } else {
;           const bool lower = (lane & j) == 0;
;           {
;             const bool up = (k == 128) ? true : ((k == 64) ? true : ((lane & k) == 0));
;             const int oi = __shfl_xor(myi0, j); const float og = __shfl_xor(myg0, j);
;             const bool take = (lower == up) ? (oi < myi0) : (oi > myi0);
;             myi0 = take ? oi : myi0; myg0 = take ? og : myg0;
;           }
;           {
;             const bool up = (k == 128) ? true : ((k == 64) ? false : ((lane & k) == 0));
;             const int oi = __shfl_xor(myi1, j); const float og = __shfl_xor(myg1, j);
;             const bool take = (lower == up) ? (oi < myi1) : (oi > myi1);
;             myi1 = take ? oi : myi1; myg1 = take ? og : myg1;
;           }
;         }
;       }
;     }
; }
	s_mov_b32 s88, 0xf00ff00f
	s_mov_b32 s89, 0xf00ff00f
	v_min_u32_e32 v104, v241, v0
	v_max_u32_e32 v105, v241, v0
	v_cndmask_b32_e64 v241, v105, v104, s[88:89]
	v_min_u32_e32 v106, v243, v1
	v_max_u32_e32 v107, v243, v1
	v_cndmask_b32_e64 v243, v107, v106, s[88:89]
	v_min_u32_e32 v104, v245, v2
	v_max_u32_e32 v105, v245, v2
	v_cndmask_b32_e64 v245, v105, v104, s[88:89]
	v_min_u32_e32 v106, v247, v3
	v_max_u32_e32 v107, v247, v3
	v_cndmask_b32_e64 v247, v107, v106, s[88:89]
	v_min_u32_e32 v104, v242, v4
	v_max_u32_e32 v105, v242, v4
	v_cndmask_b32_e64 v242, v105, v104, s[88:89]
	v_min_u32_e32 v106, v244, v5
	v_max_u32_e32 v107, v244, v5
	v_cndmask_b32_e64 v244, v107, v106, s[88:89]
	v_min_u32_e32 v104, v246, v6
	v_max_u32_e32 v105, v246, v6
	v_cndmask_b32_e64 v246, v105, v104, s[88:89]
	v_min_u32_e32 v106, v248, v7
	v_max_u32_e32 v107, v248, v7
	v_cndmask_b32_e64 v248, v107, v106, s[88:89]
	v_xor_b32_e32 v116, 8, v234
	ds_bpermute_b32 v0, v116, v241
	ds_bpermute_b32 v1, v116, v243
	ds_bpermute_b32 v2, v116, v245
	ds_bpermute_b32 v3, v116, v247
	ds_bpermute_b32 v4, v116, v242
	ds_bpermute_b32 v5, v116, v244
	ds_bpermute_b32 v6, v116, v246
	ds_bpermute_b32 v7, v116, v248
	s_waitcnt lgkmcnt(0)
	s_mov_b32 s88, 0xcc33cc33
	s_mov_b32 s89, 0xcc33cc33
	v_min_u32_e32 v104, v241, v0
	v_max_u32_e32 v105, v241, v0
	v_cndmask_b32_e64 v241, v105, v104, s[88:89]
	v_min_u32_e32 v106, v243, v1
	v_max_u32_e32 v107, v243, v1
	v_cndmask_b32_e64 v243, v107, v106, s[88:89]
	v_min_u32_e32 v104, v245, v2
	v_max_u32_e32 v105, v245, v2
	v_cndmask_b32_e64 v245, v105, v104, s[88:89]
	v_min_u32_e32 v106, v247, v3
	v_max_u32_e32 v107, v247, v3
	v_cndmask_b32_e64 v247, v107, v106, s[88:89]
	v_min_u32_e32 v104, v242, v4
	v_max_u32_e32 v105, v242, v4
	v_cndmask_b32_e64 v242, v105, v104, s[88:89]
	v_min_u32_e32 v106, v244, v5
	v_max_u32_e32 v107, v244, v5
	v_cndmask_b32_e64 v244, v107, v106, s[88:89]
	v_min_u32_e32 v104, v246, v6
	v_max_u32_e32 v105, v246, v6
	v_cndmask_b32_e64 v246, v105, v104, s[88:89]
	v_min_u32_e32 v106, v248, v7
	v_max_u32_e32 v107, v248, v7
	v_cndmask_b32_e64 v248, v107, v106, s[88:89]
	v_xor_b32_e32 v116, 4, v234
	ds_bpermute_b32 v0, v116, v241
	ds_bpermute_b32 v1, v116, v243
	ds_bpermute_b32 v2, v116, v245
	ds_bpermute_b32 v3, v116, v247
	ds_bpermute_b32 v4, v116, v242
	ds_bpermute_b32 v5, v116, v244
	ds_bpermute_b32 v6, v116, v246
	ds_bpermute_b32 v7, v116, v248
	s_waitcnt lgkmcnt(0)
	s_mov_b32 s88, 0xaa55aa55
	s_mov_b32 s89, 0xaa55aa55
	v_min_u32_e32 v104, v241, v0
	v_max_u32_e32 v105, v241, v0
	v_cndmask_b32_e64 v241, v105, v104, s[88:89]
	v_min_u32_e32 v106, v243, v1
	v_max_u32_e32 v107, v243, v1
	v_cndmask_b32_e64 v243, v107, v106, s[88:89]
	v_min_u32_e32 v104, v245, v2
	v_max_u32_e32 v105, v245, v2
	v_cndmask_b32_e64 v245, v105, v104, s[88:89]
	v_min_u32_e32 v106, v247, v3
	v_max_u32_e32 v107, v247, v3
	v_cndmask_b32_e64 v247, v107, v106, s[88:89]
	v_min_u32_e32 v104, v242, v4
	v_max_u32_e32 v105, v242, v4
	v_cndmask_b32_e64 v242, v105, v104, s[88:89]
	v_min_u32_e32 v106, v244, v5
	v_max_u32_e32 v107, v244, v5
	v_cndmask_b32_e64 v244, v107, v106, s[88:89]
	v_min_u32_e32 v104, v246, v6
	v_max_u32_e32 v105, v246, v6
	v_cndmask_b32_e64 v246, v105, v104, s[88:89]
	v_min_u32_e32 v106, v248, v7
	v_max_u32_e32 v107, v248, v7
	v_cndmask_b32_e64 v248, v107, v106, s[88:89]
	v_xor_b32_e32 v116, 32, v234
	ds_bpermute_b32 v0, v116, v241
	ds_bpermute_b32 v1, v116, v243
	ds_bpermute_b32 v2, v116, v245
	ds_bpermute_b32 v3, v116, v247
	ds_bpermute_b32 v4, v116, v242
	ds_bpermute_b32 v5, v116, v244
	ds_bpermute_b32 v6, v116, v246
	ds_bpermute_b32 v7, v116, v248
	s_waitcnt lgkmcnt(0)
	s_mov_b32 s88, 0xff0000ff
	s_mov_b32 s89, 0xff0000ff
	v_min_u32_e32 v104, v241, v0
	v_max_u32_e32 v105, v241, v0
	v_cndmask_b32_e64 v241, v105, v104, s[88:89]
	v_min_u32_e32 v106, v243, v1
	v_max_u32_e32 v107, v243, v1
	v_cndmask_b32_e64 v243, v107, v106, s[88:89]
	v_min_u32_e32 v104, v245, v2
	v_max_u32_e32 v105, v245, v2
	v_cndmask_b32_e64 v245, v105, v104, s[88:89]
	v_min_u32_e32 v106, v247, v3
	v_max_u32_e32 v107, v247, v3
	v_cndmask_b32_e64 v247, v107, v106, s[88:89]
	v_min_u32_e32 v104, v242, v4
	v_max_u32_e32 v105, v242, v4
	v_cndmask_b32_e64 v242, v105, v104, s[88:89]
	v_min_u32_e32 v106, v244, v5
	v_max_u32_e32 v107, v244, v5
	v_cndmask_b32_e64 v244, v107, v106, s[88:89]
	v_min_u32_e32 v104, v246, v6
	v_max_u32_e32 v105, v246, v6
	v_cndmask_b32_e64 v246, v105, v104, s[88:89]
	v_min_u32_e32 v106, v248, v7
	v_max_u32_e32 v107, v248, v7
	v_cndmask_b32_e64 v248, v107, v106, s[88:89]
	v_xor_b32_e32 v116, 16, v234
	ds_bpermute_b32 v0, v116, v241
	ds_bpermute_b32 v1, v116, v243
	ds_bpermute_b32 v2, v116, v245
	ds_bpermute_b32 v3, v116, v247
	ds_bpermute_b32 v4, v116, v242
	ds_bpermute_b32 v5, v116, v244
	ds_bpermute_b32 v6, v116, v246
	ds_bpermute_b32 v7, v116, v248
	s_waitcnt lgkmcnt(0)
	s_mov_b32 s88, 0xf0f00f0f
	s_mov_b32 s89, 0xf0f00f0f
	v_min_u32_e32 v104, v241, v0
	v_max_u32_e32 v105, v241, v0
	v_cndmask_b32_e64 v241, v105, v104, s[88:89]
	v_min_u32_e32 v106, v243, v1
	v_max_u32_e32 v107, v243, v1
	v_cndmask_b32_e64 v243, v107, v106, s[88:89]
	v_min_u32_e32 v104, v245, v2
	v_max_u32_e32 v105, v245, v2
	v_cndmask_b32_e64 v245, v105, v104, s[88:89]
	v_min_u32_e32 v106, v247, v3
	v_max_u32_e32 v107, v247, v3
	v_cndmask_b32_e64 v247, v107, v106, s[88:89]
	v_min_u32_e32 v104, v242, v4
	v_max_u32_e32 v105, v242, v4
	v_cndmask_b32_e64 v242, v105, v104, s[88:89]
	v_min_u32_e32 v106, v244, v5
	v_max_u32_e32 v107, v244, v5
	v_cndmask_b32_e64 v244, v107, v106, s[88:89]
	v_min_u32_e32 v104, v246, v6
	v_max_u32_e32 v105, v246, v6
	v_cndmask_b32_e64 v246, v105, v104, s[88:89]
	v_min_u32_e32 v106, v248, v7
	v_max_u32_e32 v107, v248, v7
	v_cndmask_b32_e64 v248, v107, v106, s[88:89]
	v_xor_b32_e32 v116, 8, v234
	ds_bpermute_b32 v0, v116, v241
	ds_bpermute_b32 v1, v116, v243
	ds_bpermute_b32 v2, v116, v245
	ds_bpermute_b32 v3, v116, v247
	ds_bpermute_b32 v4, v116, v242
	ds_bpermute_b32 v5, v116, v244
	ds_bpermute_b32 v6, v116, v246
	ds_bpermute_b32 v7, v116, v248
	s_waitcnt lgkmcnt(0)
; DEV void sort_lists(int lane, int& myi0, int& myi1, float& myg0, float& myg1) {
; #pragma unroll
;     for (int k = 2; k <= 128; k <<= 1) {
; #pragma unroll
;       for (int j = k >> 1; j >= 1; j >>= 1) {
;         if (j == 64) {
;           const bool sw_ = myi1 < myi0;
;           const int ti = sw_ ? myi1 : myi0, tj = sw_ ? myi0 : myi1; const float tg = sw_ ? myg1 : myg0, th = sw_ ? myg0 : myg1;
;           myi0 = ti; myi1 = tj; myg0 = tg; myg1 = th;
;         } else {
;           const bool lower = (lane & j) == 0;
;           {
;             const bool up = (k == 128) ? true : ((k == 64) ? true : ((lane & k) == 0));
;             const int oi = __shfl_xor(myi0, j); const float og = __shfl_xor(myg0, j);
;             const bool take = (lower == up) ? (oi < myi0) : (oi > myi0);
;             myi0 = take ? oi : myi0; myg0 = take ? og : myg0;
;           }
;           {
;             const bool up = (k == 128) ? true : ((k == 64) ? false : ((lane & k) == 0));
;             const int oi = __shfl_xor(myi1, j); const float og = __shfl_xor(myg1, j);
;             const bool take = (lower == up) ? (oi < myi1) : (oi > myi1);
;             myi1 = take ? oi : myi1; myg1 = take ? og : myg1;
;           }
;         }
;       }
;     }
; }
	s_mov_b32 s88, 0xcccc3333
	s_mov_b32 s89, 0xcccc3333
	v_min_u32_e32 v104, v241, v0
	v_max_u32_e32 v105, v241, v0
	v_cndmask_b32_e64 v241, v105, v104, s[88:89]
	v_min_u32_e32 v106, v243, v1
	v_max_u32_e32 v107, v243, v1
	v_cndmask_b32_e64 v243, v107, v106, s[88:89]
	v_min_u32_e32 v104, v245, v2
	v_max_u32_e32 v105, v245, v2
	v_cndmask_b32_e64 v245, v105, v104, s[88:89]
	v_min_u32_e32 v106, v247, v3
	v_max_u32_e32 v107, v247, v3
	v_cndmask_b32_e64 v247, v107, v106, s[88:89]
	v_min_u32_e32 v104, v242, v4
	v_max_u32_e32 v105, v242, v4
	v_cndmask_b32_e64 v242, v105, v104, s[88:89]
	v_min_u32_e32 v106, v244, v5
	v_max_u32_e32 v107, v244, v5
	v_cndmask_b32_e64 v244, v107, v106, s[88:89]
	v_min_u32_e32 v104, v246, v6
	v_max_u32_e32 v105, v246, v6
	v_cndmask_b32_e64 v246, v105, v104, s[88:89]
	v_min_u32_e32 v106, v248, v7
	v_max_u32_e32 v107, v248, v7
	v_cndmask_b32_e64 v248, v107, v106, s[88:89]
	v_xor_b32_e32 v116, 4, v234
	ds_bpermute_b32 v0, v116, v241
	ds_bpermute_b32 v1, v116, v243
	ds_bpermute_b32 v2, v116, v245
	ds_bpermute_b32 v3, v116, v247
	ds_bpermute_b32 v4, v116, v242
	ds_bpermute_b32 v5, v116, v244
	ds_bpermute_b32 v6, v116, v246
	ds_bpermute_b32 v7, v116, v248
	s_waitcnt lgkmcnt(0)
	s_mov_b32 s88, 0xaaaa5555
	s_mov_b32 s89, 0xaaaa5555
	v_min_u32_e32 v104, v241, v0
	v_max_u32_e32 v105, v241, v0
	v_cndmask_b32_e64 v241, v105, v104, s[88:89]
	v_min_u32_e32 v106, v243, v1
	v_max_u32_e32 v107, v243, v1
	v_cndmask_b32_e64 v243, v107, v106, s[88:89]
	v_min_u32_e32 v104, v245, v2
	v_max_u32_e32 v105, v245, v2
	v_cndmask_b32_e64 v245, v105, v104, s[88:89]
	v_min_u32_e32 v106, v247, v3
	v_max_u32_e32 v107, v247, v3
	v_cndmask_b32_e64 v247, v107, v106, s[88:89]
	v_min_u32_e32 v104, v242, v4
	v_max_u32_e32 v105, v242, v4
	v_cndmask_b32_e64 v242, v105, v104, s[88:89]
	v_min_u32_e32 v106, v244, v5
	v_max_u32_e32 v107, v244, v5
	v_cndmask_b32_e64 v244, v107, v106, s[88:89]
	v_min_u32_e32 v104, v246, v6
	v_max_u32_e32 v105, v246, v6
	v_cndmask_b32_e64 v246, v105, v104, s[88:89]
	v_min_u32_e32 v106, v248, v7
	v_max_u32_e32 v107, v248, v7
	v_cndmask_b32_e64 v248, v107, v106, s[88:89]
	v_xor_b32_e32 v116, 64, v234
	ds_bpermute_b32 v0, v116, v241
	ds_bpermute_b32 v1, v116, v243
	ds_bpermute_b32 v2, v116, v245
	ds_bpermute_b32 v3, v116, v247
	ds_bpermute_b32 v4, v116, v242
	ds_bpermute_b32 v5, v116, v244
	ds_bpermute_b32 v6, v116, v246
	ds_bpermute_b32 v7, v116, v248
	s_waitcnt lgkmcnt(0)
	s_mov_b32 s88, 0xffff
	s_mov_b32 s89, 0xffff0000
	v_min_u32_e32 v104, v241, v0
	v_max_u32_e32 v105, v241, v0
	v_cndmask_b32_e64 v241, v105, v104, s[88:89]
	v_min_u32_e32 v106, v243, v1
	v_max_u32_e32 v107, v243, v1
	v_cndmask_b32_e64 v243, v107, v106, s[88:89]
	v_min_u32_e32 v104, v245, v2
	v_max_u32_e32 v105, v245, v2
	v_cndmask_b32_e64 v245, v105, v104, s[88:89]
	v_min_u32_e32 v106, v247, v3
	v_max_u32_e32 v107, v247, v3
	v_cndmask_b32_e64 v247, v107, v106, s[88:89]
	v_min_u32_e32 v104, v242, v4
	v_max_u32_e32 v105, v242, v4
	v_cndmask_b32_e64 v242, v105, v104, s[88:89]
	v_min_u32_e32 v106, v244, v5
	v_max_u32_e32 v107, v244, v5
	v_cndmask_b32_e64 v244, v107, v106, s[88:89]
	v_min_u32_e32 v104, v246, v6
	v_max_u32_e32 v105, v246, v6
	v_cndmask_b32_e64 v246, v105, v104, s[88:89]
	v_min_u32_e32 v106, v248, v7
	v_max_u32_e32 v107, v248, v7
	v_cndmask_b32_e64 v248, v107, v106, s[88:89]
	v_xor_b32_e32 v116, 32, v234
	ds_bpermute_b32 v0, v116, v241
	ds_bpermute_b32 v1, v116, v243
	ds_bpermute_b32 v2, v116, v245
	ds_bpermute_b32 v3, v116, v247
	ds_bpermute_b32 v4, v116, v242
	ds_bpermute_b32 v5, v116, v244
	ds_bpermute_b32 v6, v116, v246
	ds_bpermute_b32 v7, v116, v248
	s_waitcnt lgkmcnt(0)
	s_mov_b32 s88, 0xff00ff
	s_mov_b32 s89, 0xff00ff00
	v_min_u32_e32 v104, v241, v0
	v_max_u32_e32 v105, v241, v0
	v_cndmask_b32_e64 v241, v105, v104, s[88:89]
	v_min_u32_e32 v106, v243, v1
	v_max_u32_e32 v107, v243, v1
	v_cndmask_b32_e64 v243, v107, v106, s[88:89]
	v_min_u32_e32 v104, v245, v2
	v_max_u32_e32 v105, v245, v2
	v_cndmask_b32_e64 v245, v105, v104, s[88:89]
	v_min_u32_e32 v106, v247, v3
	v_max_u32_e32 v107, v247, v3
	v_cndmask_b32_e64 v247, v107, v106, s[88:89]
	v_min_u32_e32 v104, v242, v4
	v_max_u32_e32 v105, v242, v4
	v_cndmask_b32_e64 v242, v105, v104, s[88:89]
	v_min_u32_e32 v106, v244, v5
	v_max_u32_e32 v107, v244, v5
	v_cndmask_b32_e64 v244, v107, v106, s[88:89]
	v_min_u32_e32 v104, v246, v6
	v_max_u32_e32 v105, v246, v6
	v_cndmask_b32_e64 v246, v105, v104, s[88:89]
	v_min_u32_e32 v106, v248, v7
	v_max_u32_e32 v107, v248, v7
	v_cndmask_b32_e64 v248, v107, v106, s[88:89]
	v_xor_b32_e32 v116, 16, v234
	ds_bpermute_b32 v0, v116, v241
	ds_bpermute_b32 v1, v116, v243
	ds_bpermute_b32 v2, v116, v245
	ds_bpermute_b32 v3, v116, v247
	ds_bpermute_b32 v4, v116, v242
	ds_bpermute_b32 v5, v116, v244
	ds_bpermute_b32 v6, v116, v246
	ds_bpermute_b32 v7, v116, v248
	s_waitcnt lgkmcnt(0)
	s_mov_b32 s88, 0xf0f0f0f
	s_mov_b32 s89, 0xf0f0f0f0
	v_min_u32_e32 v104, v241, v0
	v_max_u32_e32 v105, v241, v0
	v_cndmask_b32_e64 v241, v105, v104, s[88:89]
	v_min_u32_e32 v106, v243, v1
	v_max_u32_e32 v107, v243, v1
	v_cndmask_b32_e64 v243, v107, v106, s[88:89]
	v_min_u32_e32 v104, v245, v2
	v_max_u32_e32 v105, v245, v2
	v_cndmask_b32_e64 v245, v105, v104, s[88:89]
	v_min_u32_e32 v106, v247, v3
	v_max_u32_e32 v107, v247, v3
	v_cndmask_b32_e64 v247, v107, v106, s[88:89]
	v_min_u32_e32 v104, v242, v4
	v_max_u32_e32 v105, v242, v4
	v_cndmask_b32_e64 v242, v105, v104, s[88:89]
	v_min_u32_e32 v106, v244, v5
	v_max_u32_e32 v107, v244, v5
	v_cndmask_b32_e64 v244, v107, v106, s[88:89]
	v_min_u32_e32 v104, v246, v6
	v_max_u32_e32 v105, v246, v6
	v_cndmask_b32_e64 v246, v105, v104, s[88:89]
	v_min_u32_e32 v106, v248, v7
	v_max_u32_e32 v107, v248, v7
	v_cndmask_b32_e64 v248, v107, v106, s[88:89]
	v_xor_b32_e32 v116, 8, v234
	ds_bpermute_b32 v0, v116, v241
	ds_bpermute_b32 v1, v116, v243
	ds_bpermute_b32 v2, v116, v245
	ds_bpermute_b32 v3, v116, v247
	ds_bpermute_b32 v4, v116, v242
	ds_bpermute_b32 v5, v116, v244
	ds_bpermute_b32 v6, v116, v246
	ds_bpermute_b32 v7, v116, v248
	s_waitcnt lgkmcnt(0)
; DEV void sort_lists(int lane, int& myi0, int& myi1, float& myg0, float& myg1) {
; #pragma unroll
;     for (int k = 2; k <= 128; k <<= 1) {
; #pragma unroll
;       for (int j = k >> 1; j >= 1; j >>= 1) {
;         if (j == 64) {
;           const bool sw_ = myi1 < myi0;
;           const int ti = sw_ ? myi1 : myi0, tj = sw_ ? myi0 : myi1; const float tg = sw_ ? myg1 : myg0, th = sw_ ? myg0 : myg1;
;           myi0 = ti; myi1 = tj; myg0 = tg; myg1 = th;
;         } else {
;           const bool lower = (lane & j) == 0;
;           {
;             const bool up = (k == 128) ? true : ((k == 64) ? true : ((lane & k) == 0));
;             const int oi = __shfl_xor(myi0, j); const float og = __shfl_xor(myg0, j);
;             const bool take = (lower == up) ? (oi < myi0) : (oi > myi0);
;             myi0 = take ? oi : myi0; myg0 = take ? og : myg0;
;           }
;           {
;             const bool up = (k == 128) ? true : ((k == 64) ? false : ((lane & k) == 0));
;             const int oi = __shfl_xor(myi1, j); const float og = __shfl_xor(myg1, j);
;             const bool take = (lower == up) ? (oi < myi1) : (oi > myi1);
;             myi1 = take ? oi : myi1; myg1 = take ? og : myg1;
;           }
;         }
;       }
;     }
; }
	s_mov_b32 s88, 0x33333333
	s_mov_b32 s89, 0xcccccccc
	v_min_u32_e32 v104, v241, v0
	v_max_u32_e32 v105, v241, v0
	v_cndmask_b32_e64 v241, v105, v104, s[88:89]
	v_min_u32_e32 v106, v243, v1
	v_max_u32_e32 v107, v243, v1
	v_cndmask_b32_e64 v243, v107, v106, s[88:89]
	v_min_u32_e32 v104, v245, v2
	v_max_u32_e32 v105, v245, v2
	v_cndmask_b32_e64 v245, v105, v104, s[88:89]
	v_min_u32_e32 v106, v247, v3
	v_max_u32_e32 v107, v247, v3
	v_cndmask_b32_e64 v247, v107, v106, s[88:89]
	v_min_u32_e32 v104, v242, v4
	v_max_u32_e32 v105, v242, v4
	v_cndmask_b32_e64 v242, v105, v104, s[88:89]
	v_min_u32_e32 v106, v244, v5
	v_max_u32_e32 v107, v244, v5
	v_cndmask_b32_e64 v244, v107, v106, s[88:89]
	v_min_u32_e32 v104, v246, v6
	v_max_u32_e32 v105, v246, v6
	v_cndmask_b32_e64 v246, v105, v104, s[88:89]
	v_min_u32_e32 v106, v248, v7
	v_max_u32_e32 v107, v248, v7
	v_cndmask_b32_e64 v248, v107, v106, s[88:89]
	v_xor_b32_e32 v116, 4, v234
	ds_bpermute_b32 v0, v116, v241
	ds_bpermute_b32 v1, v116, v243
	ds_bpermute_b32 v2, v116, v245
	ds_bpermute_b32 v3, v116, v247
	ds_bpermute_b32 v4, v116, v242
	ds_bpermute_b32 v5, v116, v244
	ds_bpermute_b32 v6, v116, v246
	ds_bpermute_b32 v7, v116, v248
	s_waitcnt lgkmcnt(0)
	s_mov_b32 s88, 0x55555555
	s_mov_b32 s89, 0xaaaaaaaa
	v_min_u32_e32 v104, v241, v0
	v_max_u32_e32 v105, v241, v0
	v_cndmask_b32_e64 v241, v105, v104, s[88:89]
	v_min_u32_e32 v106, v243, v1
	v_max_u32_e32 v107, v243, v1
	v_cndmask_b32_e64 v243, v107, v106, s[88:89]
	v_min_u32_e32 v104, v245, v2
	v_max_u32_e32 v105, v245, v2
	v_cndmask_b32_e64 v245, v105, v104, s[88:89]
	v_min_u32_e32 v106, v247, v3
	v_max_u32_e32 v107, v247, v3
	v_cndmask_b32_e64 v247, v107, v106, s[88:89]
	v_min_u32_e32 v104, v242, v4
	v_max_u32_e32 v105, v242, v4
	v_cndmask_b32_e64 v242, v105, v104, s[88:89]
	v_min_u32_e32 v106, v244, v5
	v_max_u32_e32 v107, v244, v5
	v_cndmask_b32_e64 v244, v107, v106, s[88:89]
	v_min_u32_e32 v104, v246, v6
	v_max_u32_e32 v105, v246, v6
	v_cndmask_b32_e64 v246, v105, v104, s[88:89]
	v_min_u32_e32 v106, v248, v7
	v_max_u32_e32 v107, v248, v7
	v_cndmask_b32_e64 v248, v107, v106, s[88:89]
	v_xor_b32_e32 v116, 128, v234
	ds_bpermute_b32 v0, v116, v241
	ds_bpermute_b32 v1, v116, v243
	ds_bpermute_b32 v2, v116, v245
	ds_bpermute_b32 v3, v116, v247
	ds_bpermute_b32 v4, v116, v242
	ds_bpermute_b32 v5, v116, v244
	ds_bpermute_b32 v6, v116, v246
	ds_bpermute_b32 v7, v116, v248
	s_waitcnt lgkmcnt(0)
	s_mov_b32 s88, 0xffffffff
	s_mov_b32 s89, 0x0
	v_min_u32_e32 v104, v241, v0
	v_max_u32_e32 v105, v241, v0
	v_cndmask_b32_e64 v241, v105, v104, s[88:89]
	v_min_u32_e32 v106, v243, v1
	v_max_u32_e32 v107, v243, v1
	v_cndmask_b32_e64 v243, v107, v106, s[88:89]
	v_min_u32_e32 v104, v245, v2
	v_max_u32_e32 v105, v245, v2
	v_cndmask_b32_e64 v245, v105, v104, s[88:89]
	v_min_u32_e32 v106, v247, v3
	v_max_u32_e32 v107, v247, v3
	v_cndmask_b32_e64 v247, v107, v106, s[88:89]
	s_mov_b32 s88, 0x0
	s_mov_b32 s89, 0xffffffff
	v_min_u32_e32 v104, v242, v4
	v_max_u32_e32 v105, v242, v4
	v_cndmask_b32_e64 v242, v105, v104, s[88:89]
	v_min_u32_e32 v106, v244, v5
	v_max_u32_e32 v107, v244, v5
	v_cndmask_b32_e64 v244, v107, v106, s[88:89]
	v_min_u32_e32 v104, v246, v6
	v_max_u32_e32 v105, v246, v6
	v_cndmask_b32_e64 v246, v105, v104, s[88:89]
	v_min_u32_e32 v106, v248, v7
	v_max_u32_e32 v107, v248, v7
	v_cndmask_b32_e64 v248, v107, v106, s[88:89]
	v_xor_b32_e32 v116, 64, v234
	ds_bpermute_b32 v0, v116, v241
	ds_bpermute_b32 v1, v116, v243
	ds_bpermute_b32 v2, v116, v245
	ds_bpermute_b32 v3, v116, v247
	ds_bpermute_b32 v4, v116, v242
	ds_bpermute_b32 v5, v116, v244
	ds_bpermute_b32 v6, v116, v246
	ds_bpermute_b32 v7, v116, v248
	s_waitcnt lgkmcnt(0)
	s_mov_b32 s88, 0xffff
	s_mov_b32 s89, 0xffff
	v_min_u32_e32 v104, v241, v0
	v_max_u32_e32 v105, v241, v0
	v_cndmask_b32_e64 v241, v105, v104, s[88:89]
	v_min_u32_e32 v106, v243, v1
	v_max_u32_e32 v107, v243, v1
	v_cndmask_b32_e64 v243, v107, v106, s[88:89]
	v_min_u32_e32 v104, v245, v2
	v_max_u32_e32 v105, v245, v2
	v_cndmask_b32_e64 v245, v105, v104, s[88:89]
	v_min_u32_e32 v106, v247, v3
	v_max_u32_e32 v107, v247, v3
	v_cndmask_b32_e64 v247, v107, v106, s[88:89]
	s_mov_b32 s88, 0xffff0000
	s_mov_b32 s89, 0xffff0000
	v_min_u32_e32 v104, v242, v4
	v_max_u32_e32 v105, v242, v4
	v_cndmask_b32_e64 v242, v105, v104, s[88:89]
	v_min_u32_e32 v106, v244, v5
	v_max_u32_e32 v107, v244, v5
	v_cndmask_b32_e64 v244, v107, v106, s[88:89]
	v_min_u32_e32 v104, v246, v6
	v_max_u32_e32 v105, v246, v6
	v_cndmask_b32_e64 v246, v105, v104, s[88:89]
	v_min_u32_e32 v106, v248, v7
	v_max_u32_e32 v107, v248, v7
	v_cndmask_b32_e64 v248, v107, v106, s[88:89]
	v_xor_b32_e32 v116, 32, v234
	ds_bpermute_b32 v0, v116, v241
	ds_bpermute_b32 v1, v116, v243
	ds_bpermute_b32 v2, v116, v245
	ds_bpermute_b32 v3, v116, v247
	ds_bpermute_b32 v4, v116, v242
	ds_bpermute_b32 v5, v116, v244
	ds_bpermute_b32 v6, v116, v246
	ds_bpermute_b32 v7, v116, v248
	s_waitcnt lgkmcnt(0)
	s_mov_b32 s88, 0xff00ff
	s_mov_b32 s89, 0xff00ff
	v_min_u32_e32 v104, v241, v0
	v_max_u32_e32 v105, v241, v0
	v_cndmask_b32_e64 v241, v105, v104, s[88:89]
	v_min_u32_e32 v106, v243, v1
	v_max_u32_e32 v107, v243, v1
	v_cndmask_b32_e64 v243, v107, v106, s[88:89]
	v_min_u32_e32 v104, v245, v2
	v_max_u32_e32 v105, v245, v2
	v_cndmask_b32_e64 v245, v105, v104, s[88:89]
	v_min_u32_e32 v106, v247, v3
	v_max_u32_e32 v107, v247, v3
	v_cndmask_b32_e64 v247, v107, v106, s[88:89]
	s_mov_b32 s88, 0xff00ff00
	s_mov_b32 s89, 0xff00ff00
	v_min_u32_e32 v104, v242, v4
	v_max_u32_e32 v105, v242, v4
	v_cndmask_b32_e64 v242, v105, v104, s[88:89]
	v_min_u32_e32 v106, v244, v5
	v_max_u32_e32 v107, v244, v5
	v_cndmask_b32_e64 v244, v107, v106, s[88:89]
	v_min_u32_e32 v104, v246, v6
	v_max_u32_e32 v105, v246, v6
	v_cndmask_b32_e64 v246, v105, v104, s[88:89]
	v_min_u32_e32 v106, v248, v7
	v_max_u32_e32 v107, v248, v7
	v_cndmask_b32_e64 v248, v107, v106, s[88:89]
	v_xor_b32_e32 v116, 16, v234
	ds_bpermute_b32 v0, v116, v241
	ds_bpermute_b32 v1, v116, v243
	ds_bpermute_b32 v2, v116, v245
	ds_bpermute_b32 v3, v116, v247
	ds_bpermute_b32 v4, v116, v242
	ds_bpermute_b32 v5, v116, v244
	ds_bpermute_b32 v6, v116, v246
	ds_bpermute_b32 v7, v116, v248
	s_waitcnt lgkmcnt(0)
; DEV void sort_lists(int lane, int& myi0, int& myi1, float& myg0, float& myg1) {
; #pragma unroll
;     for (int k = 2; k <= 128; k <<= 1) {
; #pragma unroll
;       for (int j = k >> 1; j >= 1; j >>= 1) {
;         if (j == 64) {
;           const bool sw_ = myi1 < myi0;
;           const int ti = sw_ ? myi1 : myi0, tj = sw_ ? myi0 : myi1; const float tg = sw_ ? myg1 : myg0, th = sw_ ? myg0 : myg1;
;           myi0 = ti; myi1 = tj; myg0 = tg; myg1 = th;
;         } else {
;           const bool lower = (lane & j) == 0;
;           {
;             const bool up = (k == 128) ? true : ((k == 64) ? true : ((lane & k) == 0));
;             const int oi = __shfl_xor(myi0, j); const float og = __shfl_xor(myg0, j);
;             const bool take = (lower == up) ? (oi < myi0) : (oi > myi0);
;             myi0 = take ? oi : myi0; myg0 = take ? og : myg0;
;           }
;           {
;             const bool up = (k == 128) ? true : ((k == 64) ? false : ((lane & k) == 0));
;             const int oi = __shfl_xor(myi1, j); const float og = __shfl_xor(myg1, j);
;             const bool take = (lower == up) ? (oi < myi1) : (oi > myi1);
;             myi1 = take ? oi : myi1; myg1 = take ? og : myg1;
;           }
;         }
;       }
;     }
; }
	s_mov_b32 s88, 0xf0f0f0f
	s_mov_b32 s89, 0xf0f0f0f
	v_min_u32_e32 v104, v241, v0
	v_max_u32_e32 v105, v241, v0
	v_cndmask_b32_e64 v241, v105, v104, s[88:89]
	v_min_u32_e32 v106, v243, v1
	v_max_u32_e32 v107, v243, v1
	v_cndmask_b32_e64 v243, v107, v106, s[88:89]
	v_min_u32_e32 v104, v245, v2
	v_max_u32_e32 v105, v245, v2
	v_cndmask_b32_e64 v245, v105, v104, s[88:89]
	v_min_u32_e32 v106, v247, v3
	v_max_u32_e32 v107, v247, v3
	v_cndmask_b32_e64 v247, v107, v106, s[88:89]
	s_mov_b32 s88, 0xf0f0f0f0
	s_mov_b32 s89, 0xf0f0f0f0
	v_min_u32_e32 v104, v242, v4
	v_max_u32_e32 v105, v242, v4
	v_cndmask_b32_e64 v242, v105, v104, s[88:89]
	v_min_u32_e32 v106, v244, v5
	v_max_u32_e32 v107, v244, v5
	v_cndmask_b32_e64 v244, v107, v106, s[88:89]
	v_min_u32_e32 v104, v246, v6
	v_max_u32_e32 v105, v246, v6
	v_cndmask_b32_e64 v246, v105, v104, s[88:89]
	v_min_u32_e32 v106, v248, v7
	v_max_u32_e32 v107, v248, v7
	v_cndmask_b32_e64 v248, v107, v106, s[88:89]
	v_xor_b32_e32 v116, 8, v234
	ds_bpermute_b32 v0, v116, v241
	ds_bpermute_b32 v1, v116, v243
	ds_bpermute_b32 v2, v116, v245
	ds_bpermute_b32 v3, v116, v247
	ds_bpermute_b32 v4, v116, v242
	ds_bpermute_b32 v5, v116, v244
	ds_bpermute_b32 v6, v116, v246
	ds_bpermute_b32 v7, v116, v248
	s_waitcnt lgkmcnt(0)
	s_mov_b32 s88, 0x33333333
	s_mov_b32 s89, 0x33333333
	v_min_u32_e32 v104, v241, v0
	v_max_u32_e32 v105, v241, v0
	v_cndmask_b32_e64 v241, v105, v104, s[88:89]
	v_min_u32_e32 v106, v243, v1
	v_max_u32_e32 v107, v243, v1
	v_cndmask_b32_e64 v243, v107, v106, s[88:89]
	v_min_u32_e32 v104, v245, v2
	v_max_u32_e32 v105, v245, v2
	v_cndmask_b32_e64 v245, v105, v104, s[88:89]
	v_min_u32_e32 v106, v247, v3
	v_max_u32_e32 v107, v247, v3
	v_cndmask_b32_e64 v247, v107, v106, s[88:89]
	s_mov_b32 s88, 0xcccccccc
	s_mov_b32 s89, 0xcccccccc
	v_min_u32_e32 v104, v242, v4
	v_max_u32_e32 v105, v242, v4
	v_cndmask_b32_e64 v242, v105, v104, s[88:89]
	v_min_u32_e32 v106, v244, v5
	v_max_u32_e32 v107, v244, v5
	v_cndmask_b32_e64 v244, v107, v106, s[88:89]
	v_min_u32_e32 v104, v246, v6
	v_max_u32_e32 v105, v246, v6
	v_cndmask_b32_e64 v246, v105, v104, s[88:89]
	v_min_u32_e32 v106, v248, v7
	v_max_u32_e32 v107, v248, v7
	v_cndmask_b32_e64 v248, v107, v106, s[88:89]
	v_xor_b32_e32 v116, 4, v234
	ds_bpermute_b32 v0, v116, v241
	ds_bpermute_b32 v1, v116, v243
	ds_bpermute_b32 v2, v116, v245
	ds_bpermute_b32 v3, v116, v247
	ds_bpermute_b32 v4, v116, v242
	ds_bpermute_b32 v5, v116, v244
	ds_bpermute_b32 v6, v116, v246
	ds_bpermute_b32 v7, v116, v248
	s_waitcnt lgkmcnt(0)
	s_mov_b32 s88, 0x55555555
	s_mov_b32 s89, 0x55555555
	v_min_u32_e32 v104, v241, v0
	v_max_u32_e32 v105, v241, v0
	v_cndmask_b32_e64 v241, v105, v104, s[88:89]
	v_min_u32_e32 v106, v243, v1
	v_max_u32_e32 v107, v243, v1
	v_cndmask_b32_e64 v243, v107, v106, s[88:89]
	v_min_u32_e32 v104, v245, v2
	v_max_u32_e32 v105, v245, v2
	v_cndmask_b32_e64 v245, v105, v104, s[88:89]
	v_min_u32_e32 v106, v247, v3
	v_max_u32_e32 v107, v247, v3
	v_cndmask_b32_e64 v247, v107, v106, s[88:89]
	s_mov_b32 s88, 0xaaaaaaaa
	s_mov_b32 s89, 0xaaaaaaaa
	v_min_u32_e32 v104, v242, v4
	v_max_u32_e32 v105, v242, v4
	v_cndmask_b32_e64 v242, v105, v104, s[88:89]
	v_min_u32_e32 v106, v244, v5
	v_max_u32_e32 v107, v244, v5
	v_cndmask_b32_e64 v244, v107, v106, s[88:89]
	v_min_u32_e32 v104, v246, v6
	v_max_u32_e32 v105, v246, v6
	v_cndmask_b32_e64 v246, v105, v104, s[88:89]
	v_min_u32_e32 v106, v248, v7
	v_max_u32_e32 v107, v248, v7
	v_cndmask_b32_e64 v248, v107, v106, s[88:89]
	v_min_u32_e32 v104, v241, v242
	v_max_u32_e32 v242, v241, v242
	v_mov_b32_e32 v241, v104
	v_min_u32_e32 v106, v243, v244
	v_max_u32_e32 v244, v243, v244
	v_mov_b32_e32 v243, v106
	v_min_u32_e32 v104, v245, v246
	v_max_u32_e32 v246, v245, v246
	v_mov_b32_e32 v245, v104
	v_min_u32_e32 v106, v247, v248
	v_max_u32_e32 v248, v247, v248
	v_mov_b32_e32 v247, v106
	v_xor_b32_e32 v116, 128, v234
	ds_bpermute_b32 v0, v116, v241
	ds_bpermute_b32 v1, v116, v243
	ds_bpermute_b32 v2, v116, v245
	ds_bpermute_b32 v3, v116, v247
	ds_bpermute_b32 v4, v116, v242
	ds_bpermute_b32 v5, v116, v244
	ds_bpermute_b32 v6, v116, v246
	ds_bpermute_b32 v7, v116, v248
	s_waitcnt lgkmcnt(0)
	s_mov_b32 s88, 0xffffffff
	s_mov_b32 s89, 0x0
	v_min_u32_e32 v104, v241, v0
	v_max_u32_e32 v105, v241, v0
	v_cndmask_b32_e64 v241, v105, v104, s[88:89]
	v_min_u32_e32 v106, v243, v1
	v_max_u32_e32 v107, v243, v1
	v_cndmask_b32_e64 v243, v107, v106, s[88:89]
	v_min_u32_e32 v104, v245, v2
	v_max_u32_e32 v105, v245, v2
	v_cndmask_b32_e64 v245, v105, v104, s[88:89]
	v_min_u32_e32 v106, v247, v3
	v_max_u32_e32 v107, v247, v3
	v_cndmask_b32_e64 v247, v107, v106, s[88:89]
	v_min_u32_e32 v104, v242, v4
	v_max_u32_e32 v105, v242, v4
	v_cndmask_b32_e64 v242, v105, v104, s[88:89]
	v_min_u32_e32 v106, v244, v5
	v_max_u32_e32 v107, v244, v5
	v_cndmask_b32_e64 v244, v107, v106, s[88:89]
	v_min_u32_e32 v104, v246, v6
	v_max_u32_e32 v105, v246, v6
	v_cndmask_b32_e64 v246, v105, v104, s[88:89]
	v_min_u32_e32 v106, v248, v7
	v_max_u32_e32 v107, v248, v7
	v_cndmask_b32_e64 v248, v107, v106, s[88:89]
	v_xor_b32_e32 v116, 64, v234
	ds_bpermute_b32 v0, v116, v241
	ds_bpermute_b32 v1, v116, v243
	ds_bpermute_b32 v2, v116, v245
	ds_bpermute_b32 v3, v116, v247
	ds_bpermute_b32 v4, v116, v242
	ds_bpermute_b32 v5, v116, v244
	ds_bpermute_b32 v6, v116, v246
	ds_bpermute_b32 v7, v116, v248
	s_waitcnt lgkmcnt(0)
; DEV void sort_lists(int lane, int& myi0, int& myi1, float& myg0, float& myg1) {
; #pragma unroll
;     for (int k = 2; k <= 128; k <<= 1) {
; #pragma unroll
;       for (int j = k >> 1; j >= 1; j >>= 1) {
;         if (j == 64) {
;           const bool sw_ = myi1 < myi0;
;           const int ti = sw_ ? myi1 : myi0, tj = sw_ ? myi0 : myi1; const float tg = sw_ ? myg1 : myg0, th = sw_ ? myg0 : myg1;
;           myi0 = ti; myi1 = tj; myg0 = tg; myg1 = th;
;         } else {
;           const bool lower = (lane & j) == 0;
;           {
;             const bool up = (k == 128) ? true : ((k == 64) ? true : ((lane & k) == 0));
;             const int oi = __shfl_xor(myi0, j); const float og = __shfl_xor(myg0, j);
;             const bool take = (lower == up) ? (oi < myi0) : (oi > myi0);
;             myi0 = take ? oi : myi0; myg0 = take ? og : myg0;
;           }
;           {
;             const bool up = (k == 128) ? true : ((k == 64) ? false : ((lane & k) == 0));
;             const int oi = __shfl_xor(myi1, j); const float og = __shfl_xor(myg1, j);
;             const bool take = (lower == up) ? (oi < myi1) : (oi > myi1);
;             myi1 = take ? oi : myi1; myg1 = take ? og : myg1;
;           }
;         }
;       }
;     }
; }
	s_mov_b32 s88, 0xffff
	s_mov_b32 s89, 0xffff
	v_min_u32_e32 v104, v241, v0
	v_max_u32_e32 v105, v241, v0
	v_cndmask_b32_e64 v241, v105, v104, s[88:89]
	v_min_u32_e32 v106, v243, v1
	v_max_u32_e32 v107, v243, v1
	v_cndmask_b32_e64 v243, v107, v106, s[88:89]
	v_min_u32_e32 v104, v245, v2
	v_max_u32_e32 v105, v245, v2
	v_cndmask_b32_e64 v245, v105, v104, s[88:89]
	v_min_u32_e32 v106, v247, v3
	v_max_u32_e32 v107, v247, v3
	v_cndmask_b32_e64 v247, v107, v106, s[88:89]
	v_min_u32_e32 v104, v242, v4
	v_max_u32_e32 v105, v242, v4
	v_cndmask_b32_e64 v242, v105, v104, s[88:89]
	v_min_u32_e32 v106, v244, v5
	v_max_u32_e32 v107, v244, v5
	v_cndmask_b32_e64 v244, v107, v106, s[88:89]
	v_min_u32_e32 v104, v246, v6
	v_max_u32_e32 v105, v246, v6
	v_cndmask_b32_e64 v246, v105, v104, s[88:89]
	v_min_u32_e32 v106, v248, v7
	v_max_u32_e32 v107, v248, v7
	v_cndmask_b32_e64 v248, v107, v106, s[88:89]
	v_xor_b32_e32 v116, 32, v234
	ds_bpermute_b32 v0, v116, v241
	ds_bpermute_b32 v1, v116, v243
	ds_bpermute_b32 v2, v116, v245
	ds_bpermute_b32 v3, v116, v247
	ds_bpermute_b32 v4, v116, v242
	ds_bpermute_b32 v5, v116, v244
	ds_bpermute_b32 v6, v116, v246
	ds_bpermute_b32 v7, v116, v248
	s_waitcnt lgkmcnt(0)
	s_mov_b32 s88, 0xff00ff
	s_mov_b32 s89, 0xff00ff
	v_min_u32_e32 v104, v241, v0
	v_max_u32_e32 v105, v241, v0
	v_cndmask_b32_e64 v241, v105, v104, s[88:89]
	v_min_u32_e32 v106, v243, v1
	v_max_u32_e32 v107, v243, v1
	v_cndmask_b32_e64 v243, v107, v106, s[88:89]
	v_min_u32_e32 v104, v245, v2
	v_max_u32_e32 v105, v245, v2
	v_cndmask_b32_e64 v245, v105, v104, s[88:89]
	v_min_u32_e32 v106, v247, v3
	v_max_u32_e32 v107, v247, v3
	v_cndmask_b32_e64 v247, v107, v106, s[88:89]
	v_min_u32_e32 v104, v242, v4
	v_max_u32_e32 v105, v242, v4
	v_cndmask_b32_e64 v242, v105, v104, s[88:89]
	v_min_u32_e32 v106, v244, v5
	v_max_u32_e32 v107, v244, v5
	v_cndmask_b32_e64 v244, v107, v106, s[88:89]
	v_min_u32_e32 v104, v246, v6
	v_max_u32_e32 v105, v246, v6
	v_cndmask_b32_e64 v246, v105, v104, s[88:89]
	v_min_u32_e32 v106, v248, v7
	v_max_u32_e32 v107, v248, v7
	v_cndmask_b32_e64 v248, v107, v106, s[88:89]
	v_xor_b32_e32 v116, 16, v234
	ds_bpermute_b32 v0, v116, v241
	ds_bpermute_b32 v1, v116, v243
	ds_bpermute_b32 v2, v116, v245
	ds_bpermute_b32 v3, v116, v247
	ds_bpermute_b32 v4, v116, v242
	ds_bpermute_b32 v5, v116, v244
	ds_bpermute_b32 v6, v116, v246
	ds_bpermute_b32 v7, v116, v248
	s_waitcnt lgkmcnt(0)
	s_mov_b32 s88, 0xf0f0f0f
	s_mov_b32 s89, 0xf0f0f0f
	v_min_u32_e32 v104, v241, v0
	v_max_u32_e32 v105, v241, v0
	v_cndmask_b32_e64 v241, v105, v104, s[88:89]
	v_min_u32_e32 v106, v243, v1
	v_max_u32_e32 v107, v243, v1
	v_cndmask_b32_e64 v243, v107, v106, s[88:89]
	v_min_u32_e32 v104, v245, v2
	v_max_u32_e32 v105, v245, v2
	v_cndmask_b32_e64 v245, v105, v104, s[88:89]
	v_min_u32_e32 v106, v247, v3
	v_max_u32_e32 v107, v247, v3
	v_cndmask_b32_e64 v247, v107, v106, s[88:89]
	v_min_u32_e32 v104, v242, v4
	v_max_u32_e32 v105, v242, v4
	v_cndmask_b32_e64 v242, v105, v104, s[88:89]
	v_min_u32_e32 v106, v244, v5
	v_max_u32_e32 v107, v244, v5
	v_cndmask_b32_e64 v244, v107, v106, s[88:89]
	v_min_u32_e32 v104, v246, v6
	v_max_u32_e32 v105, v246, v6
	v_cndmask_b32_e64 v246, v105, v104, s[88:89]
	v_min_u32_e32 v106, v248, v7
	v_max_u32_e32 v107, v248, v7
	v_cndmask_b32_e64 v248, v107, v106, s[88:89]
	v_xor_b32_e32 v116, 8, v234
	ds_bpermute_b32 v0, v116, v241
	ds_bpermute_b32 v1, v116, v243
	ds_bpermute_b32 v2, v116, v245
	ds_bpermute_b32 v3, v116, v247
	ds_bpermute_b32 v4, v116, v242
	ds_bpermute_b32 v5, v116, v244
	ds_bpermute_b32 v6, v116, v246
	ds_bpermute_b32 v7, v116, v248
	s_waitcnt lgkmcnt(0)
	s_mov_b32 s88, 0x33333333
	s_mov_b32 s89, 0x33333333
	v_min_u32_e32 v104, v241, v0
	v_max_u32_e32 v105, v241, v0
	v_cndmask_b32_e64 v241, v105, v104, s[88:89]
	v_min_u32_e32 v106, v243, v1
	v_max_u32_e32 v107, v243, v1
	v_cndmask_b32_e64 v243, v107, v106, s[88:89]
	v_min_u32_e32 v104, v245, v2
	v_max_u32_e32 v105, v245, v2
	v_cndmask_b32_e64 v245, v105, v104, s[88:89]
	v_min_u32_e32 v106, v247, v3
	v_max_u32_e32 v107, v247, v3
	v_cndmask_b32_e64 v247, v107, v106, s[88:89]
	v_min_u32_e32 v104, v242, v4
	v_max_u32_e32 v105, v242, v4
	v_cndmask_b32_e64 v242, v105, v104, s[88:89]
	v_min_u32_e32 v106, v244, v5
	v_max_u32_e32 v107, v244, v5
	v_cndmask_b32_e64 v244, v107, v106, s[88:89]
	v_min_u32_e32 v104, v246, v6
	v_max_u32_e32 v105, v246, v6
	v_cndmask_b32_e64 v246, v105, v104, s[88:89]
	v_min_u32_e32 v106, v248, v7
	v_max_u32_e32 v107, v248, v7
	v_cndmask_b32_e64 v248, v107, v106, s[88:89]
	v_xor_b32_e32 v116, 4, v234
	ds_bpermute_b32 v0, v116, v241
	ds_bpermute_b32 v1, v116, v243
	ds_bpermute_b32 v2, v116, v245
	ds_bpermute_b32 v3, v116, v247
	ds_bpermute_b32 v4, v116, v242
	ds_bpermute_b32 v5, v116, v244
	ds_bpermute_b32 v6, v116, v246
	ds_bpermute_b32 v7, v116, v248
	s_waitcnt lgkmcnt(0)
	s_mov_b32 s88, 0x55555555
	s_mov_b32 s89, 0x55555555
	v_min_u32_e32 v104, v241, v0
	v_max_u32_e32 v105, v241, v0
	v_cndmask_b32_e64 v241, v105, v104, s[88:89]
	v_min_u32_e32 v106, v243, v1
	v_max_u32_e32 v107, v243, v1
	v_cndmask_b32_e64 v243, v107, v106, s[88:89]
	v_min_u32_e32 v104, v245, v2
	v_max_u32_e32 v105, v245, v2
	v_cndmask_b32_e64 v245, v105, v104, s[88:89]
	v_min_u32_e32 v106, v247, v3
	v_max_u32_e32 v107, v247, v3
	v_cndmask_b32_e64 v247, v107, v106, s[88:89]
	v_min_u32_e32 v104, v242, v4
	v_max_u32_e32 v105, v242, v4
	v_cndmask_b32_e64 v242, v105, v104, s[88:89]
	v_min_u32_e32 v106, v244, v5
	v_max_u32_e32 v107, v244, v5
	v_cndmask_b32_e64 v244, v107, v106, s[88:89]
	v_min_u32_e32 v104, v246, v6
	v_max_u32_e32 v105, v246, v6
	v_cndmask_b32_e64 v246, v105, v104, s[88:89]
	v_min_u32_e32 v106, v248, v7
	v_max_u32_e32 v107, v248, v7
	v_cndmask_b32_e64 v248, v107, v106, s[88:89]
	v_mov_b32_e32 v117, 0
	s_lshl_b32 s98, s2, 11
	s_add_u32 s98, s98, s101
	v_add_u32_e32 v116, s98, v234
	ds_write_b32 v116, v241 offset:0
	ds_write_b32 v116, v242 offset:256
	ds_write_b32 v116, v243 offset:512
	ds_write_b32 v116, v244 offset:768
	ds_write_b32 v116, v245 offset:1024
	ds_write_b32 v116, v246 offset:1280
	ds_write_b32 v116, v247 offset:1536
	ds_write_b32 v116, v248 offset:1792
	v_add_u32_e32 v118, 0x10000, v116
	ds_write_b32 v118, v117 offset:0
	ds_write_b32 v118, v117 offset:256
	ds_write_b32 v118, v117 offset:512
	ds_write_b32 v118, v117 offset:768
	ds_write_b32 v118, v117 offset:1024
	ds_write_b32 v118, v117 offset:1280
	ds_write_b32 v118, v117 offset:1536
	ds_write_b32 v118, v117 offset:1792
	s_add_u32 s2, s2, 1
	s_cmp_lt_u32 s2, 4
	s_cbranch_scc1 .Lpg1_p0
; #define PG_ISSUE(BUF, TAB, e0_) do { const int isrc_ = ((e0_) < 64) ? myi0 : myi1; \
;       _Pragma("unroll") for (int e = 0; e < 8; ++e) { const int idx_ = __builtin_amdgcn_readlane(isrc_, ((e0_) + e) & 63); \
;         BUF[e] = *(const u32x4*)((TAB) + (size_t)idx_ * 1024 + lane * 16); } } while (0)
; DEV void peer_gather(const Params& P, int l, int m0, const int* idxs, const float* gs) {
;     ...
;     PG_ISSUE(b0, U, 0);
; #pragma nounroll
;     for (int e0 = 0; e0 < 128; e0 += 16) {
;       PG_ISSUE(b1, U, e0 + 8);
;       PG_U8(b0, 0, e0);
;       if (e0 + 16 < 128) PG_ISSUE(b0, U, e0 + 16); else PG_ISSUE(b0, V, 0);
	s_waitcnt lgkmcnt(0)
	v_lshrrev_b32_e32 v248, 3, v233
	v_readfirstlane_b32 s82, v122
	v_readfirstlane_b32 s83, v123
	s_nop 4
	v_readfirstlane_b32 s80, v126
	v_readfirstlane_b32 s81, v127
	s_nop 4
	s_mov_b32 s2, 0xffffff80
	s_mov_b32 s86, 0xcccccccc
	s_mov_b32 s87, 0xcccccccc
	s_mov_b32 s88, 0xaaaaaaaa
	s_mov_b32 s89, 0xaaaaaaaa
	s_mov_b32 s90, 0xf0f0f0f0
	s_mov_b32 s91, 0xf0f0f0f0
	s_lshl_b32 vcc_lo, s3, 11
	s_add_u32 s82, s82, vcc_lo
	s_addc_u32 s83, s83, 0
	v_add_u32_e32 v246, s101, v234
	v_add_u32_e32 v247, 0x10000, v246
	s_mov_b32 s100, 0
	s_mov_b32 s98, 0
	s_mov_b32 s99, 0
	s_lshl3_add_u32 vcc_lo, s98, s99
	v_lshl_add_u32 v119, vcc_lo, 8, v236
	global_load_dwordx4 v[80:83], v119, s[82:83]
	global_load_dwordx4 v[84:87], v119, s[82:83] offset:16
	v_lshl_add_u32 v116, s98, 9, v246
	ds_read_b32 v134, v116
	ds_read_b32 v135, v116 offset:256
	s_lshl_b32 vcc_lo, s99, 21
	s_add_u32 s84, s80, vcc_lo
	s_addc_u32 s85, s81, 0
	s_waitcnt lgkmcnt(0)
	ds_bpermute_b32 v142, v249, v134
	ds_bpermute_b32 v143, v250, v134
	s_waitcnt lgkmcnt(0)
	v_and_or_b32 v142, v142, s2, v235
	v_and_or_b32 v143, v143, s2, v235
	global_load_dwordx4 v[0:3], v142, s[84:85]
	global_load_dwordx4 v[4:7], v143, s[84:85]
	ds_bpermute_b32 v142, v251, v134
	ds_bpermute_b32 v143, v252, v134
	s_waitcnt lgkmcnt(0)
	v_and_or_b32 v142, v142, s2, v235
	v_and_or_b32 v143, v143, s2, v235
	global_load_dwordx4 v[8:11], v142, s[84:85]
	global_load_dwordx4 v[12:15], v143, s[84:85]
	ds_bpermute_b32 v142, v253, v134
	ds_bpermute_b32 v143, v254, v134
	s_waitcnt lgkmcnt(0)
	v_and_or_b32 v142, v142, s2, v235
	v_and_or_b32 v143, v143, s2, v235
	global_load_dwordx4 v[16:19], v142, s[84:85]
	global_load_dwordx4 v[20:23], v143, s[84:85]
	ds_bpermute_b32 v142, v255, v134
	ds_bpermute_b32 v143, v153, v134
	s_waitcnt lgkmcnt(0)
	v_and_or_b32 v142, v142, s2, v235
	v_and_or_b32 v143, v143, s2, v235
	global_load_dwordx4 v[24:27], v142, s[84:85]
	global_load_dwordx4 v[28:31], v143, s[84:85]
	ds_bpermute_b32 v142, v249, v135
	ds_bpermute_b32 v143, v250, v135
	s_waitcnt lgkmcnt(0)
	v_and_or_b32 v142, v142, s2, v235
	v_and_or_b32 v143, v143, s2, v235
	global_load_dwordx4 v[32:35], v142, s[84:85]
	global_load_dwordx4 v[36:39], v143, s[84:85]
	ds_bpermute_b32 v142, v251, v135
	ds_bpermute_b32 v143, v252, v135
	s_waitcnt lgkmcnt(0)
	v_and_or_b32 v142, v142, s2, v235
	v_and_or_b32 v143, v143, s2, v235
	global_load_dwordx4 v[40:43], v142, s[84:85]
	global_load_dwordx4 v[44:47], v143, s[84:85]
	ds_bpermute_b32 v142, v253, v135
	ds_bpermute_b32 v143, v254, v135
	s_waitcnt lgkmcnt(0)
	v_and_or_b32 v142, v142, s2, v235
	v_and_or_b32 v143, v143, s2, v235
	global_load_dwordx4 v[48:51], v142, s[84:85]
	global_load_dwordx4 v[52:55], v143, s[84:85]
	ds_bpermute_b32 v142, v255, v135
	ds_bpermute_b32 v143, v153, v135
	s_waitcnt lgkmcnt(0)
	v_and_or_b32 v142, v142, s2, v235
	v_and_or_b32 v143, v143, s2, v235
	global_load_dwordx4 v[56:59], v142, s[84:85]
	global_load_dwordx4 v[60:63], v143, s[84:85]
	s_mov_b32 s92, 1
	v_lshl_add_u32 v116, s92, 9, v246
	ds_read_b32 v134, v116
	ds_read_b32 v135, v116 offset:256

.Lpg1_act:
	v_readlane_b32 s82, v232, 1
	v_readlane_b32 s83, v232, 2
	s_nop 4
	s_lshl_b32 s98, s2, 11
	s_add_u32 s98, s98, s101
	v_add_u32_e32 v116, s98, v234
	v_add_u32_e32 v117, 0x10000, v116
	ds_read_b32 v0, v116 offset:0
	ds_read_b32 v8, v117 offset:0
	ds_read_b32 v1, v116 offset:256
	ds_read_b32 v9, v117 offset:256
	ds_read_b32 v2, v116 offset:512
	ds_read_b32 v10, v117 offset:512
	ds_read_b32 v3, v116 offset:768
	ds_read_b32 v11, v117 offset:768
	ds_read_b32 v4, v116 offset:1024
	ds_read_b32 v12, v117 offset:1024
	ds_read_b32 v5, v116 offset:1280
	ds_read_b32 v13, v117 offset:1280
	ds_read_b32 v6, v116 offset:1536
	ds_read_b32 v14, v117 offset:1536
	ds_read_b32 v7, v116 offset:1792
	ds_read_b32 v15, v117 offset:1792
	s_waitcnt lgkmcnt(0)
	s_lshl_b32 s99, s2, 2
	s_add_u32 s99, s99, s33
	s_add_u32 s99, s99, 0
	s_lshl_b32 s99, s99, 9
	v_and_b32_e32 v0, 0x7f, v0
	v_lshl_add_u32 v0, v0, 2, s99
	global_load_dword v16, v0, s[82:83]
	v_and_b32_e32 v1, 0x7f, v1
	v_lshl_add_u32 v1, v1, 2, s99
	global_load_dword v17, v1, s[82:83]
	s_lshl_b32 s99, s2, 2
	s_add_u32 s99, s99, s33
	s_add_u32 s99, s99, 1
	s_lshl_b32 s99, s99, 9
	v_and_b32_e32 v2, 0x7f, v2
	v_lshl_add_u32 v2, v2, 2, s99
	global_load_dword v18, v2, s[82:83]
	v_and_b32_e32 v3, 0x7f, v3
	v_lshl_add_u32 v3, v3, 2, s99
	global_load_dword v19, v3, s[82:83]
	s_lshl_b32 s99, s2, 2
	s_add_u32 s99, s99, s33
	s_add_u32 s99, s99, 2
	s_lshl_b32 s99, s99, 9
	v_and_b32_e32 v4, 0x7f, v4
	v_lshl_add_u32 v4, v4, 2, s99
	global_load_dword v20, v4, s[82:83]
	v_and_b32_e32 v5, 0x7f, v5
	v_lshl_add_u32 v5, v5, 2, s99
	global_load_dword v21, v5, s[82:83]
	s_lshl_b32 s99, s2, 2
	s_add_u32 s99, s99, s33
	s_add_u32 s99, s99, 3
	s_lshl_b32 s99, s99, 9
	v_and_b32_e32 v6, 0x7f, v6
	v_lshl_add_u32 v6, v6, 2, s99
	global_load_dword v22, v6, s[82:83]
	v_and_b32_e32 v7, 0x7f, v7
	v_lshl_add_u32 v7, v7, 2, s99
	global_load_dword v23, v7, s[82:83]
	v_mul_f32_e32 v8, 0x3c800000, v8
	v_mul_f32_e32 v9, 0x3c800000, v9
	v_mul_f32_e32 v10, 0x3c800000, v10
	v_mul_f32_e32 v11, 0x3c800000, v11
	v_mul_f32_e32 v12, 0x3c800000, v12
	v_mul_f32_e32 v13, 0x3c800000, v13
	v_mul_f32_e32 v14, 0x3c800000, v14
	v_mul_f32_e32 v15, 0x3c800000, v15
	v_mul_f32_e32 v24, 0x3d372713, v8
	v_mul_f32_e32 v25, 0x3d372713, v9
	v_mul_f32_e32 v26, 0x3d372713, v10
	v_mul_f32_e32 v27, 0x3d372713, v11
	v_mul_f32_e32 v28, 0x3d372713, v12
	v_mul_f32_e32 v29, 0x3d372713, v13
	v_mul_f32_e32 v30, 0x3d372713, v14
	v_mul_f32_e32 v31, 0x3d372713, v15
	v_mul_f32_e32 v24, v8, v24
	v_mul_f32_e32 v25, v9, v25
	v_mul_f32_e32 v26, v10, v26
	v_mul_f32_e32 v27, v11, v27
	v_mul_f32_e32 v28, v12, v28
	v_mul_f32_e32 v29, v13, v29
	v_mul_f32_e32 v30, v14, v30
	v_mul_f32_e32 v31, v15, v31
	v_fma_f32 v24, v8, v24, v8
	v_fma_f32 v25, v9, v25, v9
	v_fma_f32 v26, v10, v26, v10
	v_fma_f32 v27, v11, v27, v11
	v_fma_f32 v28, v12, v28, v12
	v_fma_f32 v29, v13, v29, v13
	v_fma_f32 v30, v14, v30, v14
	v_fma_f32 v31, v15, v31, v15
	v_mul_f32_e32 v24, 0xbfcc422a, v24
	v_mul_f32_e32 v25, 0xbfcc422a, v25
	v_mul_f32_e32 v26, 0xbfcc422a, v26
	v_mul_f32_e32 v27, 0xbfcc422a, v27
	v_mul_f32_e32 v28, 0xbfcc422a, v28
	v_mul_f32_e32 v29, 0xbfcc422a, v29
	v_mul_f32_e32 v30, 0xbfcc422a, v30
	v_mul_f32_e32 v31, 0xbfcc422a, v31
	v_mul_f32_e32 v24, 0x3fb8aa3b, v24
	v_mul_f32_e32 v25, 0x3fb8aa3b, v25
	v_mul_f32_e32 v26, 0x3fb8aa3b, v26
	v_mul_f32_e32 v27, 0x3fb8aa3b, v27
	v_mul_f32_e32 v28, 0x3fb8aa3b, v28
	v_mul_f32_e32 v29, 0x3fb8aa3b, v29
	v_mul_f32_e32 v30, 0x3fb8aa3b, v30
	v_mul_f32_e32 v31, 0x3fb8aa3b, v31
	v_exp_f32_e32 v24, v24
	v_exp_f32_e32 v25, v25
	v_exp_f32_e32 v26, v26
	v_exp_f32_e32 v27, v27
	v_exp_f32_e32 v28, v28
	v_exp_f32_e32 v29, v29
	v_exp_f32_e32 v30, v30
	v_exp_f32_e32 v31, v31
	s_nop 0
	v_add_f32_e32 v24, 1.0, v24
	v_add_f32_e32 v25, 1.0, v25
	v_add_f32_e32 v26, 1.0, v26
	v_add_f32_e32 v27, 1.0, v27
	v_add_f32_e32 v28, 1.0, v28
	v_add_f32_e32 v29, 1.0, v29
	v_add_f32_e32 v30, 1.0, v30
	v_add_f32_e32 v31, 1.0, v31
	v_rcp_f32_e32 v24, v24
	v_rcp_f32_e32 v25, v25
	v_rcp_f32_e32 v26, v26
	v_rcp_f32_e32 v27, v27
	v_rcp_f32_e32 v28, v28
	v_rcp_f32_e32 v29, v29
	v_rcp_f32_e32 v30, v30
	v_rcp_f32_e32 v31, v31
	s_nop 0
	v_mul_f32_e32 v24, v8, v24
	v_mul_f32_e32 v25, v9, v25
	v_mul_f32_e32 v26, v10, v26
	v_mul_f32_e32 v27, v11, v27
	v_mul_f32_e32 v28, v12, v28
	v_mul_f32_e32 v29, v13, v29
	v_mul_f32_e32 v30, v14, v30
	v_mul_f32_e32 v31, v15, v31
	s_waitcnt vmcnt(0)
	v_mul_f32_e32 v24, v24, v16
	ds_write_b32 v117, v24 offset:0
	v_mul_f32_e32 v25, v25, v17
	ds_write_b32 v117, v25 offset:256
	v_mul_f32_e32 v26, v26, v18
	ds_write_b32 v117, v26 offset:512
	v_mul_f32_e32 v27, v27, v19
	ds_write_b32 v117, v27 offset:768
	v_mul_f32_e32 v28, v28, v20
	ds_write_b32 v117, v28 offset:1024
	v_mul_f32_e32 v29, v29, v21
	ds_write_b32 v117, v29 offset:1280
	v_mul_f32_e32 v30, v30, v22
	ds_write_b32 v117, v30 offset:1536
	v_mul_f32_e32 v31, v31, v23
	ds_write_b32 v117, v31 offset:1792
	s_add_u32 s2, s2, 1
	s_cmp_lt_u32 s2, 4
	s_cbranch_scc1 .Lpg1_act
; #define PG_ISSUE(BUF, TAB, e0_) do { const int isrc_ = ((e0_) < 64) ? myi0 : myi1; \
;       _Pragma("unroll") for (int e = 0; e < 8; ++e) { const int idx_ = __builtin_amdgcn_readlane(isrc_, ((e0_) + e) & 63); \
;         BUF[e] = *(const u32x4*)((TAB) + (size_t)idx_ * 1024 + lane * 16); } } while (0)
; DEV void peer_gather(const Params& P, int l, int m0, const int* idxs, const float* gs) {
;     ...
; #pragma nounroll
;     for (int e0 = 0; e0 < 128; e0 += 16) {
;       PG_ISSUE(b1, V, e0 + 8);
;       if (e0 == 64 && i + 1 < 16) sort_lists(lane, ni0, ni1, ng0, ng1);
;       PG_V16(b0, e0);
;       if (e0 + 16 < 128) PG_ISSUE(b0, V, e0 + 16);
	s_waitcnt lgkmcnt(0)
	v_add_u32_e32 v249, 0, v237
	v_add_u32_e32 v250, 32, v237
	v_add_u32_e32 v251, 64, v237
	v_add_u32_e32 v252, 96, v237
	v_add_u32_e32 v253, 128, v237
	v_add_u32_e32 v254, 160, v237
	v_add_u32_e32 v255, 192, v237
	v_add_u32_e32 v153, 224, v237
	v_readfirstlane_b32 s80, v128
	v_readfirstlane_b32 s81, v129
	s_nop 4
	v_add_u32_e32 v246, s101, v234
	v_add_u32_e32 v247, 0x10000, v246
	v_readfirstlane_b32 s82, v132
	v_readfirstlane_b32 s83, v133
	s_nop 4
	s_mov_b32 s2, 0xffffff80
	s_mov_b32 s100, 0
	s_mov_b32 s98, 0
	s_mov_b32 s99, 0
	v_lshl_add_u32 v116, s98, 9, v246
	ds_read_b32 v134, v116
	ds_read_b32 v135, v116 offset:256
	s_lshl_b32 vcc_lo, s99, 21
	s_add_u32 s84, s80, vcc_lo
	s_addc_u32 s85, s81, 0
	s_waitcnt lgkmcnt(0)
	ds_bpermute_b32 v142, v249, v134
	ds_bpermute_b32 v143, v250, v134
	s_waitcnt lgkmcnt(0)
	v_and_or_b32 v142, v142, s2, v235
	v_and_or_b32 v143, v143, s2, v235
	global_load_dwordx4 v[0:3], v142, s[84:85]
	global_load_dwordx4 v[4:7], v143, s[84:85]
	ds_bpermute_b32 v142, v251, v134
	ds_bpermute_b32 v143, v252, v134
	s_waitcnt lgkmcnt(0)
	v_and_or_b32 v142, v142, s2, v235
	v_and_or_b32 v143, v143, s2, v235
	global_load_dwordx4 v[8:11], v142, s[84:85]
	global_load_dwordx4 v[12:15], v143, s[84:85]
	ds_bpermute_b32 v142, v253, v134
	ds_bpermute_b32 v143, v254, v134
	s_waitcnt lgkmcnt(0)
	v_and_or_b32 v142, v142, s2, v235
	v_and_or_b32 v143, v143, s2, v235
	global_load_dwordx4 v[16:19], v142, s[84:85]
	global_load_dwordx4 v[20:23], v143, s[84:85]
	ds_bpermute_b32 v142, v255, v134
	ds_bpermute_b32 v143, v153, v134
	s_waitcnt lgkmcnt(0)
	v_and_or_b32 v142, v142, s2, v235
	v_and_or_b32 v143, v143, s2, v235
	global_load_dwordx4 v[24:27], v142, s[84:85]
	global_load_dwordx4 v[28:31], v143, s[84:85]
	ds_bpermute_b32 v142, v249, v135
	ds_bpermute_b32 v143, v250, v135
	s_waitcnt lgkmcnt(0)
	v_and_or_b32 v142, v142, s2, v235
	v_and_or_b32 v143, v143, s2, v235
	global_load_dwordx4 v[32:35], v142, s[84:85]
	global_load_dwordx4 v[36:39], v143, s[84:85]
	ds_bpermute_b32 v142, v251, v135
	ds_bpermute_b32 v143, v252, v135
	s_waitcnt lgkmcnt(0)
	v_and_or_b32 v142, v142, s2, v235
	v_and_or_b32 v143, v143, s2, v235
	global_load_dwordx4 v[40:43], v142, s[84:85]
	global_load_dwordx4 v[44:47], v143, s[84:85]
	ds_bpermute_b32 v142, v253, v135
	ds_bpermute_b32 v143, v254, v135
	s_waitcnt lgkmcnt(0)
	v_and_or_b32 v142, v142, s2, v235
	v_and_or_b32 v143, v143, s2, v235
	global_load_dwordx4 v[48:51], v142, s[84:85]
	global_load_dwordx4 v[52:55], v143, s[84:85]
	ds_bpermute_b32 v142, v255, v135
	ds_bpermute_b32 v143, v153, v135
	s_waitcnt lgkmcnt(0)
	v_and_or_b32 v142, v142, s2, v235
	v_and_or_b32 v143, v143, s2, v235
	global_load_dwordx4 v[56:59], v142, s[84:85]
	global_load_dwordx4 v[60:63], v143, s[84:85]
	s_mov_b32 s92, 1
	v_lshl_add_u32 v116, s92, 9, v246
	ds_read_b32 v134, v116
	ds_read_b32 v135, v116 offset:256
	v_lshl_add_u32 v117, s98, 9, v247
	ds_read_b32 v136, v117
	ds_read_b32 v137, v117 offset:256
	s_waitcnt vmcnt(0)
